# latency edits on top: cross-attn QK block with all 16 Q fragments preloaded and 4-deep LDS read pipeline; sg group loop with weights/U preloaded before the barrier; w_out epilogue residual loads issue
# speedup vs baseline: 1.0094x; 1.0040x over previous
; #define LDSP(T, p) ((__attribute__((address_space(3))) T*)(p))
; DI unsigned pk2(float lo, float hi) { bf2_t v = __builtin_convertvector((f32x2){lo, hi}, bf2_t); return __builtin_bit_cast(unsigned, v); }
; DI float bf_lo(unsigned u) { return __uint_as_float(u << 16); }
; DI void sg_phase(const Params& p, lds_t* shm) {
;     ...
;     for (int g = 0; g < 8; ++g) {
;       __syncthreads();
; #pragma unroll
;       for (int i = 0; i < 4; ++i) {
;         const int idx = tid + 512 * i, row = idx >> 4, ch = idx & 15; const int c0 = g * 128 + ch * 8;
;         const u32x4 v = raw[i];
;         const float mu = stats[2 * row], rs = stats[2 * row + 1];
;         const f32x4 g0 = *(const f32x4*)(p.ln_g + c0), g1 = *(const f32x4*)(p.ln_g + c0 + 4), b0 = *(const f32x4*)(p.ln_b + c0), b1 = *(const f32x4*)(p.ln_b + c0 + 4);
;         u32x4 o;
;         o.x = pk2((bf_lo(v.x) - mu) * rs * g0[0] + b0[0], (bf_hi(v.x) - mu) * rs * g0[1] + b0[1]);
;         o.y = pk2((bf_lo(v.y) - mu) * rs * g0[2] + b0[2], (bf_hi(v.y) - mu) * rs * g0[3] + b0[3]);
;         o.z = pk2((bf_lo(v.z) - mu) * rs * g1[0] + b1[0], (bf_hi(v.z) - mu) * rs * g1[1] + b1[1]);
;         o.w = pk2((bf_lo(v.w) - mu) * rs * g1[2] + b1[2], (bf_hi(v.w) - mu) * rs * g1[3] + b1[3]);
;         *LDSP(u32x4, shm + off_a(row, ch)) = o;
;       }
;       if (g + 1 < 8) {
; #pragma unroll
;         for (int i = 0; i < 4; ++i) { const int idx = tid + 512 * i, row = idx >> 4, ch = idx & 15; raw[i] = *(const u32x4*)(Vs + (size_t)(w * 128 + row) * DM + (g + 1) * 128 + ch * 8); }
;       }
;       __syncthreads();
;       const int ib = wid & 3, chalf = wid >> 2, nks = (ib < 2) ? 4 : 8;
;       f32x16 acc[2];
; #pragma unroll
;       for (int cc = 0; cc < 2; ++cc)
; #pragma unroll
;         for (int i = 0; i < 16; ++i) acc[cc][i] = 0.f;
;       const bf16_t* wrow = wm + ((size_t)(g * 128 + ib * 32 + l31)) * 128 + 8 * h;
;       for (int ks = 0; ks < nks; ++ks) {
;         const bf16x8 bfr = *(const bf16x8*)(wrow + 16 * ks);
;     ...
;       const int tok = w * 128 + ib * 32 + l31; const float bias = p.sg_b[g * 128 + ib * 32 + l31];
; #pragma unroll
;       for (int cc = 0; cc < 2; ++cc)
; #pragma unroll
;         for (int g4 = 0; g4 < 4; ++g4) {
;           bf16_t* up = U + (size_t)tok * DM + g * 128 + 32 * (2 * chalf + cc) + 8 * g4 + 4 * h;
;           const u32x2 uu = *(const u32x2*)up; f32x4 o;
.LBB0_396:
	s_lshl_b32 s1, s0, 7
	v_or_b32_e32 v48, s1, v77
	v_lshlrev_b64 v[0:1], 2, v[48:49]
	v_lshl_add_u64 v[8:9], s[40:41], 0, v[0:1]
	s_waitcnt lgkmcnt(2)
	v_lshl_add_u64 v[12:13], s[42:43], 0, v[0:1]
	s_waitcnt lgkmcnt(0)
	s_barrier
	global_load_dwordx4 v[0:3], v[12:13], off
	global_load_dwordx4 v[4:7], v[8:9], off
	s_nop 0
	global_load_dwordx4 v[8:11], v[8:9], off offset:16
	s_nop 0
	global_load_dwordx4 v[12:15], v[12:13], off offset:16
	ds_read_b64 v[16:17], v91 offset:32768
	s_waitcnt vmcnt(7)
	v_lshlrev_b32_e32 v18, 16, v32
	v_and_b32_e32 v19, 0xffff0000, v32
	v_lshlrev_b32_e32 v20, 16, v33
	v_and_b32_e32 v21, 0xffff0000, v33
	v_lshlrev_b32_e32 v22, 16, v34
	v_and_b32_e32 v23, 0xffff0000, v34
	v_lshlrev_b32_e32 v24, 16, v35
	v_and_b32_e32 v25, 0xffff0000, v35
	s_waitcnt lgkmcnt(0)
	v_pk_add_f32 v[18:19], v[18:19], v[16:17] op_sel_hi:[1,0] neg_lo:[0,1] neg_hi:[0,1]
	v_pk_add_f32 v[20:21], v[20:21], v[16:17] op_sel_hi:[1,0] neg_lo:[0,1] neg_hi:[0,1]
	v_pk_add_f32 v[22:23], v[22:23], v[16:17] op_sel_hi:[1,0] neg_lo:[0,1] neg_hi:[0,1]
	v_pk_add_f32 v[24:25], v[24:25], v[16:17] op_sel_hi:[1,0] neg_lo:[0,1] neg_hi:[0,1]
	v_pk_mul_f32 v[18:19], v[16:17], v[18:19] op_sel:[1,0]
	v_pk_mul_f32 v[20:21], v[16:17], v[20:21] op_sel:[1,0]
	v_pk_mul_f32 v[22:23], v[16:17], v[22:23] op_sel:[1,0]
	v_pk_mul_f32 v[16:17], v[16:17], v[24:25] op_sel:[1,0]
	s_waitcnt vmcnt(6)
	v_lshlrev_b32_e32 v26, 16, v36
	v_and_b32_e32 v27, 0xffff0000, v36
	v_lshlrev_b32_e32 v28, 16, v37
	v_and_b32_e32 v29, 0xffff0000, v37
	v_lshlrev_b32_e32 v30, 16, v38
	v_and_b32_e32 v31, 0xffff0000, v38
	v_lshlrev_b32_e32 v68, 16, v39
	v_and_b32_e32 v69, 0xffff0000, v39
	s_waitcnt vmcnt(5)
	v_lshlrev_b32_e32 v100, 16, v40
	v_and_b32_e32 v101, 0xffff0000, v40
	v_lshlrev_b32_e32 v102, 16, v41
	v_and_b32_e32 v103, 0xffff0000, v41
	v_lshlrev_b32_e32 v104, 16, v42
	v_and_b32_e32 v105, 0xffff0000, v42
	s_mov_b32 s4, s0
	s_add_i32 s0, s0, 1
	s_cmp_eq_u32 s4, 7
	s_waitcnt vmcnt(2)
	v_pk_fma_f32 v[18:19], v[18:19], v[4:5], v[0:1]
	v_pk_fma_f32 v[20:21], v[20:21], v[6:7], v[2:3]
	s_waitcnt vmcnt(0)
	v_pk_fma_f32 v[22:23], v[22:23], v[8:9], v[12:13]
	v_pk_fma_f32 v[24:25], v[16:17], v[10:11], v[14:15]
	v_cvt_pk_bf16_f32 v16, v18, v19
	v_cvt_pk_bf16_f32 v17, v20, v21
	v_cvt_pk_bf16_f32 v18, v22, v23
	v_cvt_pk_bf16_f32 v19, v24, v25
	ds_write_b128 v92, v[16:19]
	ds_read_b64 v[16:17], v93 offset:32768
	v_lshlrev_b32_e32 v20, 16, v43
	v_and_b32_e32 v21, 0xffff0000, v43
	v_lshlrev_b32_e32 v22, 16, v44
	v_and_b32_e32 v23, 0xffff0000, v44
	s_waitcnt lgkmcnt(0)
	v_pk_add_f32 v[18:19], v[26:27], v[16:17] op_sel_hi:[1,0] neg_lo:[0,1] neg_hi:[0,1]
	v_pk_add_f32 v[24:25], v[28:29], v[16:17] op_sel_hi:[1,0] neg_lo:[0,1] neg_hi:[0,1]
	v_pk_add_f32 v[26:27], v[30:31], v[16:17] op_sel_hi:[1,0] neg_lo:[0,1] neg_hi:[0,1]
	v_pk_add_f32 v[28:29], v[68:69], v[16:17] op_sel_hi:[1,0] neg_lo:[0,1] neg_hi:[0,1]
	v_pk_mul_f32 v[18:19], v[16:17], v[18:19] op_sel:[1,0]
	v_pk_mul_f32 v[24:25], v[16:17], v[24:25] op_sel:[1,0]
	v_pk_mul_f32 v[26:27], v[16:17], v[26:27] op_sel:[1,0]
	v_pk_mul_f32 v[16:17], v[16:17], v[28:29] op_sel:[1,0]
	v_pk_fma_f32 v[18:19], v[4:5], v[18:19], v[0:1]
	v_pk_fma_f32 v[24:25], v[6:7], v[24:25], v[2:3]
	v_pk_fma_f32 v[26:27], v[8:9], v[26:27], v[12:13]
	v_pk_fma_f32 v[28:29], v[10:11], v[16:17], v[14:15]
	v_cvt_pk_bf16_f32 v16, v18, v19
	v_cvt_pk_bf16_f32 v17, v24, v25
	v_cvt_pk_bf16_f32 v18, v26, v27
	v_cvt_pk_bf16_f32 v19, v28, v29
	ds_write_b128 v94, v[16:19]
	ds_read_b64 v[16:17], v95 offset:32768
	v_lshlrev_b32_e32 v24, 16, v45
	v_and_b32_e32 v25, 0xffff0000, v45
	v_lshlrev_b32_e32 v26, 16, v46
	v_and_b32_e32 v27, 0xffff0000, v46
	s_waitcnt lgkmcnt(0)
	v_pk_add_f32 v[18:19], v[100:101], v[16:17] op_sel_hi:[1,0] neg_lo:[0,1] neg_hi:[0,1]
	v_pk_add_f32 v[28:29], v[102:103], v[16:17] op_sel_hi:[1,0] neg_lo:[0,1] neg_hi:[0,1]
	v_pk_add_f32 v[30:31], v[104:105], v[16:17] op_sel_hi:[1,0] neg_lo:[0,1] neg_hi:[0,1]
	v_pk_add_f32 v[20:21], v[20:21], v[16:17] op_sel_hi:[1,0] neg_lo:[0,1] neg_hi:[0,1]
	v_pk_mul_f32 v[18:19], v[16:17], v[18:19] op_sel:[1,0]
	v_pk_mul_f32 v[28:29], v[16:17], v[28:29] op_sel:[1,0]
	v_pk_mul_f32 v[30:31], v[16:17], v[30:31] op_sel:[1,0]
	v_pk_mul_f32 v[16:17], v[16:17], v[20:21] op_sel:[1,0]
	v_pk_fma_f32 v[18:19], v[4:5], v[18:19], v[0:1]
	v_pk_fma_f32 v[20:21], v[6:7], v[28:29], v[2:3]
	v_pk_fma_f32 v[28:29], v[8:9], v[30:31], v[12:13]
	v_pk_fma_f32 v[30:31], v[10:11], v[16:17], v[14:15]
	v_cvt_pk_bf16_f32 v16, v18, v19
	v_cvt_pk_bf16_f32 v17, v20, v21
	v_cvt_pk_bf16_f32 v18, v28, v29
	v_cvt_pk_bf16_f32 v19, v30, v31
	ds_write_b128 v96, v[16:19]
	ds_read_b64 v[16:17], v97 offset:32768
	v_lshlrev_b32_e32 v18, 16, v47
	v_and_b32_e32 v19, 0xffff0000, v47
	s_waitcnt lgkmcnt(0)
	v_pk_add_f32 v[20:21], v[22:23], v[16:17] op_sel_hi:[1,0] neg_lo:[0,1] neg_hi:[0,1]
	v_pk_add_f32 v[22:23], v[24:25], v[16:17] op_sel_hi:[1,0] neg_lo:[0,1] neg_hi:[0,1]
	v_pk_add_f32 v[24:25], v[26:27], v[16:17] op_sel_hi:[1,0] neg_lo:[0,1] neg_hi:[0,1]
	v_pk_add_f32 v[18:19], v[18:19], v[16:17] op_sel_hi:[1,0] neg_lo:[0,1] neg_hi:[0,1]
	v_pk_mul_f32 v[20:21], v[16:17], v[20:21] op_sel:[1,0]
	v_pk_mul_f32 v[22:23], v[16:17], v[22:23] op_sel:[1,0]
	v_pk_mul_f32 v[24:25], v[16:17], v[24:25] op_sel:[1,0]
	v_pk_mul_f32 v[16:17], v[16:17], v[18:19] op_sel:[1,0]
	v_pk_fma_f32 v[0:1], v[4:5], v[20:21], v[0:1]
	v_pk_fma_f32 v[2:3], v[6:7], v[22:23], v[2:3]
	v_pk_fma_f32 v[4:5], v[8:9], v[24:25], v[12:13]
	v_pk_fma_f32 v[6:7], v[10:11], v[16:17], v[14:15]
	v_cvt_pk_bf16_f32 v0, v0, v1
	v_cvt_pk_bf16_f32 v1, v2, v3
	v_cvt_pk_bf16_f32 v2, v4, v5
	v_cvt_pk_bf16_f32 v3, v6, v7
	ds_write_b128 v98, v[0:3]
	v_or_b32_e32 v192, s1, v79
	v_mov_b32_e32 v193, 0
	v_lshl_add_u64 v[194:195], v[192:193], 2, s[46:47]
	v_lshlrev_b64 v[192:193], 8, v[192:193]
	v_lshl_add_u64 v[192:193], v[54:55], 0, v[192:193]
	global_load_dwordx4 v[160:163], v[192:193], off
	global_load_dwordx4 v[164:167], v[192:193], off offset:32
	global_load_dwordx4 v[168:171], v[192:193], off offset:64
	global_load_dwordx4 v[172:175], v[192:193], off offset:96
	global_load_dwordx4 v[176:179], v[192:193], off offset:128
	global_load_dwordx4 v[180:183], v[192:193], off offset:160
	global_load_dwordx4 v[184:187], v[192:193], off offset:192
	global_load_dwordx4 v[188:191], v[192:193], off offset:224
	global_load_dword v194, v[194:195], off
	s_lshl_b32 s8, s1, 1
	v_lshl_add_u64 v[130:131], v[66:67], 0, s[8:9]
	global_load_dwordx2 v[196:197], v[130:131], off
	global_load_dwordx2 v[198:199], v[130:131], off offset:16
	global_load_dwordx2 v[200:201], v[130:131], off offset:32
	global_load_dwordx2 v[202:203], v[130:131], off offset:48
	global_load_dwordx2 v[204:205], v[130:131], off offset:64
	global_load_dwordx2 v[206:207], v[130:131], off offset:80
	global_load_dwordx2 v[208:209], v[130:131], off offset:96
	global_load_dwordx2 v[210:211], v[130:131], off offset:112
	s_cmp_eq_u32 s4, 7
	s_cbranch_scc1 .Lsg_dummy
; #define MFMA32(a, b, c) __builtin_amdgcn_mfma_f32_32x32x16_bf16((a), (b), (c), 0, 0, 0)
; DI void sg_phase(const Params& p, lds_t* shm) {
;     ...
;       if (g + 1 < 8) {
; #pragma unroll
;         for (int i = 0; i < 4; ++i) { const int idx = tid + 512 * i, row = idx >> 4, ch = idx & 15; raw[i] = *(const u32x4*)(Vs + (size_t)(w * 128 + row) * DM + (g + 1) * 128 + ch * 8); }
;       }
;       __syncthreads();
;       const int ib = wid & 3, chalf = wid >> 2, nks = (ib < 2) ? 4 : 8;
;       f32x16 acc[2];
; #pragma unroll
;       for (int cc = 0; cc < 2; ++cc)
; #pragma unroll
;         for (int i = 0; i < 16; ++i) acc[cc][i] = 0.f;
;       const bf16_t* wrow = wm + ((size_t)(g * 128 + ib * 32 + l31)) * 128 + 8 * h;
;       for (int ks = 0; ks < nks; ++ks) {
;         const bf16x8 bfr = *(const bf16x8*)(wrow + 16 * ks);
; #pragma unroll
;         for (int cc = 0; cc < 2; ++cc) {
;           const unsigned chb = 4 * (2 * chalf + cc) + 2 * blk + (pp >> 1);
;           const bf16x8 af = tr_pair(shm + off_a(16 * ks + 8 * h + q4, chb) + 8 * (pp & 1), shm + off_a(16 * ks + 8 * h + 4 + q4, chb) + 8 * (pp & 1));
;           acc[cc] = MFMA32(af, bfr, acc[cc]);
;         }
;       }
	s_lshl_b32 s8, s0, 8
	v_lshl_add_u64 v[0:1], v[52:53], 0, s[8:9]
	v_lshl_add_u64 v[2:3], v[0:1], 0, v[58:59]
	v_lshl_add_u64 v[4:5], v[0:1], 0, v[60:61]
	v_lshl_add_u64 v[6:7], v[0:1], 0, v[62:63]
	v_lshl_add_u64 v[0:1], v[0:1], 0, v[64:65]
	global_load_dwordx4 v[32:35], v[2:3], off
	global_load_dwordx4 v[36:39], v[4:5], off
	global_load_dwordx4 v[40:43], v[6:7], off
	global_load_dwordx4 v[44:47], v[0:1], off
	s_branch .LBB0_398
.Lsg_dummy:
	global_load_dword v132, v[192:193], off
	global_load_dword v132, v[192:193], off
	global_load_dword v132, v[192:193], off
	global_load_dword v132, v[192:193], off
.LBB0_398:
	v_readfirstlane_b32 s4, v78
	v_or_b32_e32 v48, s1, v79
	v_lshlrev_b64 v[0:1], 8, v[48:49]
	v_mov_b32_e32 v16, 0
	v_lshl_add_u64 v[68:69], v[54:55], 0, v[0:1]
	s_mov_b32 s8, 0
	s_mov_b64 s[6:7], 0
	v_mov_b32_e32 v100, v90
	v_mov_b32_e32 v101, v78
	v_mov_b32_e32 v17, v16
	v_mov_b32_e32 v18, v16
	v_mov_b32_e32 v19, v16
	v_mov_b32_e32 v20, v16
	v_mov_b32_e32 v21, v16
	v_mov_b32_e32 v22, v16
	v_mov_b32_e32 v23, v16
	v_mov_b32_e32 v24, v16
	v_mov_b32_e32 v25, v16
	v_mov_b32_e32 v26, v16
	v_mov_b32_e32 v27, v16
	v_mov_b32_e32 v28, v16
	v_mov_b32_e32 v29, v16
	v_mov_b32_e32 v30, v16
	v_mov_b32_e32 v31, v16
	v_mov_b32_e32 v0, v16
	v_mov_b32_e32 v1, v16
	v_mov_b32_e32 v2, v16
	v_mov_b32_e32 v3, v16
	v_mov_b32_e32 v4, v16
	v_mov_b32_e32 v5, v16
	v_mov_b32_e32 v6, v16
	v_mov_b32_e32 v7, v16
	v_mov_b32_e32 v8, v16
	v_mov_b32_e32 v9, v16
	v_mov_b32_e32 v10, v16
	v_mov_b32_e32 v11, v16
	v_mov_b32_e32 v12, v16
	v_mov_b32_e32 v13, v16
	v_mov_b32_e32 v14, v16
	v_mov_b32_e32 v15, v16
	s_waitcnt lgkmcnt(0)
	s_barrier
	v_mov_b32_e32 v122, v89
	v_and_b32_e32 v123, 0xfffff800, v100
	v_lshrrev_b32_e32 v122, 2, v122
	v_add_u32_e32 v125, v88, v123
	v_bitop3_b32 v124, v122, v81, 1 bitop3:0x36
	ds_read_b64_tr_b16 v[106:107], v125
	v_lshlrev_b32_e32 v124, 4, v124
	v_and_b32_e32 v124, 48, v124
	v_add3_u32 v123, v82, v123, v124
	v_add3_u32 v126, v123, v83, v80
	ds_read_b64_tr_b16 v[108:109], v126 offset:256
	ds_read_b64_tr_b16 v[110:111], v125 offset:512
	ds_read_b64_tr_b16 v[112:113], v126 offset:768
	v_add_u32_e32 v100, 0x1000, v100
	v_add_u32_e32 v122, 16, v89
	v_and_b32_e32 v123, 0xfffff800, v100
	v_lshrrev_b32_e32 v122, 2, v122
	v_add_u32_e32 v125, v88, v123
	v_bitop3_b32 v124, v122, v81, 1 bitop3:0x36
	ds_read_b64_tr_b16 v[114:115], v125
	v_lshlrev_b32_e32 v124, 4, v124
	v_and_b32_e32 v124, 48, v124
	v_add3_u32 v123, v82, v123, v124
	v_add3_u32 v126, v123, v83, v80
	ds_read_b64_tr_b16 v[116:117], v126 offset:256
	ds_read_b64_tr_b16 v[118:119], v125 offset:512
	ds_read_b64_tr_b16 v[120:121], v126 offset:768
	v_add_u32_e32 v100, 0x1000, v100
	s_waitcnt vmcnt(20) lgkmcnt(4)
	v_mfma_f32_32x32x16_bf16 v[16:31], v[106:109], v[160:163], v[16:31]
	v_mfma_f32_32x32x16_bf16 v[0:15], v[110:113], v[160:163], v[0:15]
	v_add_u32_e32 v122, 32, v89
	v_and_b32_e32 v123, 0xfffff800, v100
	v_lshrrev_b32_e32 v122, 2, v122
	v_add_u32_e32 v125, v88, v123
	v_bitop3_b32 v124, v122, v81, 1 bitop3:0x36
	ds_read_b64_tr_b16 v[106:107], v125
	v_lshlrev_b32_e32 v124, 4, v124
	v_and_b32_e32 v124, 48, v124
	v_add3_u32 v123, v82, v123, v124
	v_add3_u32 v126, v123, v83, v80
	ds_read_b64_tr_b16 v[108:109], v126 offset:256
	ds_read_b64_tr_b16 v[110:111], v125 offset:512
	ds_read_b64_tr_b16 v[112:113], v126 offset:768
	v_add_u32_e32 v100, 0x1000, v100
	s_waitcnt vmcnt(19) lgkmcnt(4)
	v_mfma_f32_32x32x16_bf16 v[16:31], v[114:117], v[164:167], v[16:31]
	v_mfma_f32_32x32x16_bf16 v[0:15], v[118:121], v[164:167], v[0:15]
	v_add_u32_e32 v122, 48, v89
	v_and_b32_e32 v123, 0xfffff800, v100
	v_lshrrev_b32_e32 v122, 2, v122
	v_add_u32_e32 v125, v88, v123
	v_bitop3_b32 v124, v122, v81, 1 bitop3:0x36
	ds_read_b64_tr_b16 v[114:115], v125
	v_lshlrev_b32_e32 v124, 4, v124
	v_and_b32_e32 v124, 48, v124
	v_add3_u32 v123, v82, v123, v124
	v_add3_u32 v126, v123, v83, v80
	ds_read_b64_tr_b16 v[116:117], v126 offset:256
	ds_read_b64_tr_b16 v[118:119], v125 offset:512
	ds_read_b64_tr_b16 v[120:121], v126 offset:768
	v_add_u32_e32 v100, 0x1000, v100
	s_waitcnt vmcnt(18) lgkmcnt(4)
	v_mfma_f32_32x32x16_bf16 v[16:31], v[106:109], v[168:171], v[16:31]
	v_mfma_f32_32x32x16_bf16 v[0:15], v[110:113], v[168:171], v[0:15]
	s_cmp_eq_u32 s4, 4
	s_cbranch_scc1 .Lsg_tail3
; #define MFMA32(a, b, c) __builtin_amdgcn_mfma_f32_32x32x16_bf16((a), (b), (c), 0, 0, 0)
; DI void sg_phase(const Params& p, lds_t* shm) {
;     ...
;       for (int ks = 0; ks < nks; ++ks) {
;         const bf16x8 bfr = *(const bf16x8*)(wrow + 16 * ks);
; #pragma unroll
;         for (int cc = 0; cc < 2; ++cc) {
;           const unsigned chb = 4 * (2 * chalf + cc) + 2 * blk + (pp >> 1);
;           const bf16x8 af = tr_pair(shm + off_a(16 * ks + 8 * h + q4, chb) + 8 * (pp & 1), shm + off_a(16 * ks + 8 * h + 4 + q4, chb) + 8 * (pp & 1));
;           acc[cc] = MFMA32(af, bfr, acc[cc]);
;         }
;       }
	v_add_u32_e32 v122, 64, v89
	v_and_b32_e32 v123, 0xfffff800, v100
	v_lshrrev_b32_e32 v122, 2, v122
	v_add_u32_e32 v125, v88, v123
	v_bitop3_b32 v124, v122, v81, 1 bitop3:0x36
	ds_read_b64_tr_b16 v[106:107], v125
	v_lshlrev_b32_e32 v124, 4, v124
	v_and_b32_e32 v124, 48, v124
	v_add3_u32 v123, v82, v123, v124
	v_add3_u32 v126, v123, v83, v80
	ds_read_b64_tr_b16 v[108:109], v126 offset:256
	ds_read_b64_tr_b16 v[110:111], v125 offset:512
	ds_read_b64_tr_b16 v[112:113], v126 offset:768
	v_add_u32_e32 v100, 0x1000, v100
	s_waitcnt vmcnt(17) lgkmcnt(4)
	v_mfma_f32_32x32x16_bf16 v[16:31], v[114:117], v[172:175], v[16:31]
	v_mfma_f32_32x32x16_bf16 v[0:15], v[118:121], v[172:175], v[0:15]
	v_add_u32_e32 v122, 80, v89
	v_and_b32_e32 v123, 0xfffff800, v100
	v_lshrrev_b32_e32 v122, 2, v122
	v_add_u32_e32 v125, v88, v123
	v_bitop3_b32 v124, v122, v81, 1 bitop3:0x36
	ds_read_b64_tr_b16 v[114:115], v125
	v_lshlrev_b32_e32 v124, 4, v124
	v_and_b32_e32 v124, 48, v124
	v_add3_u32 v123, v82, v123, v124
	v_add3_u32 v126, v123, v83, v80
	ds_read_b64_tr_b16 v[116:117], v126 offset:256
	ds_read_b64_tr_b16 v[118:119], v125 offset:512
	ds_read_b64_tr_b16 v[120:121], v126 offset:768
	v_add_u32_e32 v100, 0x1000, v100
	s_waitcnt vmcnt(16) lgkmcnt(4)
	v_mfma_f32_32x32x16_bf16 v[16:31], v[106:109], v[176:179], v[16:31]
	v_mfma_f32_32x32x16_bf16 v[0:15], v[110:113], v[176:179], v[0:15]
	v_add_u32_e32 v122, 96, v89
	v_and_b32_e32 v123, 0xfffff800, v100
	v_lshrrev_b32_e32 v122, 2, v122
	v_add_u32_e32 v125, v88, v123
	v_bitop3_b32 v124, v122, v81, 1 bitop3:0x36
	ds_read_b64_tr_b16 v[106:107], v125
	v_lshlrev_b32_e32 v124, 4, v124
	v_and_b32_e32 v124, 48, v124
	v_add3_u32 v123, v82, v123, v124
	v_add3_u32 v126, v123, v83, v80
	ds_read_b64_tr_b16 v[108:109], v126 offset:256
	ds_read_b64_tr_b16 v[110:111], v125 offset:512
	ds_read_b64_tr_b16 v[112:113], v126 offset:768
	v_add_u32_e32 v100, 0x1000, v100
	s_waitcnt vmcnt(15) lgkmcnt(4)
	v_mfma_f32_32x32x16_bf16 v[16:31], v[114:117], v[180:183], v[16:31]
	v_mfma_f32_32x32x16_bf16 v[0:15], v[118:121], v[180:183], v[0:15]
	v_add_u32_e32 v122, 112, v89
	v_and_b32_e32 v123, 0xfffff800, v100
	v_lshrrev_b32_e32 v122, 2, v122
	v_add_u32_e32 v125, v88, v123
	v_bitop3_b32 v124, v122, v81, 1 bitop3:0x36
	ds_read_b64_tr_b16 v[114:115], v125
	v_lshlrev_b32_e32 v124, 4, v124
	v_and_b32_e32 v124, 48, v124
	v_add3_u32 v123, v82, v123, v124
	v_add3_u32 v126, v123, v83, v80
	ds_read_b64_tr_b16 v[116:117], v126 offset:256
	ds_read_b64_tr_b16 v[118:119], v125 offset:512
	ds_read_b64_tr_b16 v[120:121], v126 offset:768
	v_add_u32_e32 v100, 0x1000, v100
	s_waitcnt vmcnt(14) lgkmcnt(4)
	v_mfma_f32_32x32x16_bf16 v[16:31], v[106:109], v[184:187], v[16:31]
	v_mfma_f32_32x32x16_bf16 v[0:15], v[110:113], v[184:187], v[0:15]
	s_waitcnt vmcnt(13) lgkmcnt(0)
	v_mfma_f32_32x32x16_bf16 v[16:31], v[114:117], v[188:191], v[16:31]
	v_mfma_f32_32x32x16_bf16 v[0:15], v[118:121], v[188:191], v[0:15]
	s_branch .Lsg_done
.Lsg_tail3:
	s_waitcnt vmcnt(17) lgkmcnt(0)
	v_mfma_f32_32x32x16_bf16 v[16:31], v[114:117], v[172:175], v[16:31]
	v_mfma_f32_32x32x16_bf16 v[0:15], v[118:121], v[172:175], v[0:15]
; DI float bf_lo(unsigned u) { return __uint_as_float(u << 16); }
; DI float bf_hi(unsigned u) { return __uint_as_float(u & 0xffff0000u); }
; DI void st_bf4(bf16_t* p, f32x4 v) { u32x2 w; w.x = pk2(v[0], v[1]); w.y = pk2(v[2], v[3]); *(u32x2*)p = w; }
; DI void sg_phase(const Params& p, lds_t* shm) {
;     ...
;       const int tok = w * 128 + ib * 32 + l31; const float bias = p.sg_b[g * 128 + ib * 32 + l31];
; #pragma unroll
;       for (int cc = 0; cc < 2; ++cc)
; #pragma unroll
;         for (int g4 = 0; g4 < 4; ++g4) {
;           bf16_t* up = U + (size_t)tok * DM + g * 128 + 32 * (2 * chalf + cc) + 8 * g4 + 4 * h;
;           const u32x2 uu = *(const u32x2*)up; f32x4 o;
;           o[0] = bf_lo(uu.x) * (acc[cc][4 * g4 + 0] + bias); o[1] = bf_hi(uu.x) * (acc[cc][4 * g4 + 1] + bias);
;           o[2] = bf_lo(uu.y) * (acc[cc][4 * g4 + 2] + bias); o[3] = bf_hi(uu.y) * (acc[cc][4 * g4 + 3] + bias);
;           st_bf4(up, o);
;         }
.Lsg_done:
	s_or_b64 exec, exec, s[6:7]
	s_lshl_b32 s8, s1, 1
	v_lshl_add_u64 v[68:69], v[66:67], 0, s[8:9]
	s_cmp_eq_u32 s0, 8
	s_waitcnt vmcnt(11)
	v_lshlrev_b32_e32 v116, 16, v196
	v_and_b32_e32 v117, 0xffff0000, v196
	v_lshlrev_b32_e32 v100, 16, v197
	v_and_b32_e32 v101, 0xffff0000, v197
	v_pk_add_f32 v[16:17], v[16:17], v[194:195] op_sel_hi:[1, 0]
	v_pk_add_f32 v[18:19], v[18:19], v[194:195] op_sel_hi:[1, 0]
	v_pk_add_f32 v[0:1], v[0:1], v[194:195] op_sel_hi:[1, 0]
	v_pk_add_f32 v[2:3], v[2:3], v[194:195] op_sel_hi:[1, 0]
	s_waitcnt vmcnt(7)
	v_lshlrev_b32_e32 v124, 16, v204
	v_and_b32_e32 v125, 0xffff0000, v204
	v_lshlrev_b32_e32 v108, 16, v205
	v_and_b32_e32 v109, 0xffff0000, v205
	v_pk_add_f32 v[20:21], v[20:21], v[194:195] op_sel_hi:[1, 0]
	v_pk_add_f32 v[22:23], v[22:23], v[194:195] op_sel_hi:[1, 0]
	v_pk_add_f32 v[24:25], v[24:25], v[194:195] op_sel_hi:[1, 0]
	v_pk_add_f32 v[26:27], v[26:27], v[194:195] op_sel_hi:[1, 0]
	v_pk_add_f32 v[28:29], v[28:29], v[194:195] op_sel_hi:[1, 0]
	v_pk_add_f32 v[30:31], v[30:31], v[194:195] op_sel_hi:[1, 0]
	v_pk_add_f32 v[4:5], v[4:5], v[194:195] op_sel_hi:[1, 0]
	v_pk_add_f32 v[6:7], v[6:7], v[194:195] op_sel_hi:[1, 0]
	v_pk_add_f32 v[8:9], v[8:9], v[194:195] op_sel_hi:[1, 0]
	v_pk_add_f32 v[10:11], v[10:11], v[194:195] op_sel_hi:[1, 0]
	v_lshlrev_b32_e32 v118, 16, v198
	v_and_b32_e32 v119, 0xffff0000, v198
	v_lshlrev_b32_e32 v102, 16, v199
	v_and_b32_e32 v103, 0xffff0000, v199
	v_lshlrev_b32_e32 v120, 16, v200
	v_and_b32_e32 v121, 0xffff0000, v200
	v_lshlrev_b32_e32 v104, 16, v201
	v_and_b32_e32 v105, 0xffff0000, v201
	v_lshlrev_b32_e32 v122, 16, v202
	v_and_b32_e32 v123, 0xffff0000, v202
	v_lshlrev_b32_e32 v106, 16, v203
	v_and_b32_e32 v107, 0xffff0000, v203
	s_waitcnt vmcnt(6)
	v_lshlrev_b32_e32 v126, 16, v206
	v_and_b32_e32 v127, 0xffff0000, v206
	v_lshlrev_b32_e32 v110, 16, v207
	v_and_b32_e32 v111, 0xffff0000, v207
	s_waitcnt vmcnt(5)
	v_lshlrev_b32_e32 v128, 16, v208
	v_and_b32_e32 v129, 0xffff0000, v208
	v_lshlrev_b32_e32 v112, 16, v209
	v_and_b32_e32 v113, 0xffff0000, v209
	v_pk_mul_f32 v[16:17], v[16:17], v[116:117]
	v_pk_mul_f32 v[18:19], v[18:19], v[100:101]
	v_pk_mul_f32 v[0:1], v[0:1], v[124:125]
	v_pk_mul_f32 v[2:3], v[2:3], v[108:109]
	v_pk_mul_f32 v[20:21], v[20:21], v[118:119]
	v_pk_mul_f32 v[22:23], v[22:23], v[102:103]
	v_pk_mul_f32 v[24:25], v[24:25], v[120:121]
	v_pk_mul_f32 v[26:27], v[26:27], v[104:105]
	v_pk_mul_f32 v[28:29], v[28:29], v[122:123]
	v_pk_mul_f32 v[30:31], v[30:31], v[106:107]
	v_pk_mul_f32 v[4:5], v[4:5], v[126:127]
	v_pk_mul_f32 v[6:7], v[6:7], v[110:111]
	v_pk_mul_f32 v[8:9], v[8:9], v[128:129]
	v_pk_mul_f32 v[10:11], v[10:11], v[112:113]
	v_cvt_pk_bf16_f32 v16, v16, v17
	v_cvt_pk_bf16_f32 v17, v18, v19
	v_cvt_pk_bf16_f32 v0, v0, v1
	v_cvt_pk_bf16_f32 v1, v2, v3
	v_cvt_pk_bf16_f32 v18, v20, v21
	v_cvt_pk_bf16_f32 v19, v22, v23
	v_cvt_pk_bf16_f32 v20, v24, v25
	v_cvt_pk_bf16_f32 v21, v26, v27
	v_cvt_pk_bf16_f32 v22, v28, v29
	v_cvt_pk_bf16_f32 v23, v30, v31
	v_cvt_pk_bf16_f32 v2, v4, v5
	v_cvt_pk_bf16_f32 v3, v6, v7
	global_store_dwordx2 v[68:69], v[16:17], off
	global_store_dwordx2 v[68:69], v[18:19], off offset:16
	global_store_dwordx2 v[68:69], v[20:21], off offset:32
	global_store_dwordx2 v[68:69], v[22:23], off offset:48
	global_store_dwordx2 v[68:69], v[0:1], off offset:64
	global_store_dwordx2 v[68:69], v[2:3], off offset:80
	v_cvt_pk_bf16_f32 v0, v8, v9
	v_cvt_pk_bf16_f32 v1, v10, v11
	global_store_dwordx2 v[68:69], v[0:1], off offset:96
	s_waitcnt vmcnt(11)
	v_lshlrev_b32_e32 v0, 16, v210
	v_and_b32_e32 v1, 0xffff0000, v210
	v_pk_add_f32 v[2:3], v[12:13], v[194:195] op_sel_hi:[1, 0]
	v_pk_add_f32 v[4:5], v[14:15], v[194:195] op_sel_hi:[1, 0]
	v_pk_mul_f32 v[0:1], v[2:3], v[0:1]
	v_lshlrev_b32_e32 v2, 16, v211
	v_and_b32_e32 v3, 0xffff0000, v211
	v_pk_mul_f32 v[2:3], v[4:5], v[2:3]
	v_cvt_pk_bf16_f32 v0, v0, v1
	v_cvt_pk_bf16_f32 v1, v2, v3
	global_store_dwordx2 v[68:69], v[0:1], off offset:112
	s_cbranch_scc0 .LBB0_396
	s_add_i32 s3, s3, s90
	s_cmpk_gt_i32 s3, 0xff
	s_cbranch_scc0 .LBB0_387

; template <class T> DI T gld_nt(const void* base, unsigned off) { return __builtin_nontemporal_load((const T*)((const char*)base + off)); }
; DI u32x4 pk8(const f32x4& a, const f32x4& b) { u32x4 w; w.x = pk2(a[0], a[1]); w.y = pk2(a[2], a[3]); w.z = pk2(b[0], b[1]); w.w = pk2(b[2], b[3]); return w; }
; DI void unpk8(const u32x4& w, f32x4& a, f32x4& b) { a[0] = bf_lo(w.x); a[1] = bf_hi(w.x); a[2] = bf_lo(w.y); a[3] = bf_hi(w.y); b[0] = bf_lo(w.z); b[1] = bf_hi(w.z); b[2] = bf_lo(w.w); b[3] = bf_hi(w.w); }
;   DI void operator()(g8::Acc& acc, int pm, int pn, int wr, int wc, int fr, int fq) const {
;     using namespace g8;
; #pragma unroll
;     for (int ai = 0; ai < 2; ++ai)
; #pragma unroll
;       for (int m = 0; m < 4; ++m) {
;         const int row = pm * BM + ai * HALF + wr * 64 + m * 16 + fr; float s = 0.f; u32x4 wv[2];
; #pragma unroll
;         for (int bj = 0; bj < 2; ++bj) {
;           const int col8 = pn * BM + wc * 64 + bj * 32 + fq * 8; const unsigned eo = (unsigned)row * DM + (unsigned)col8;
;           f32x4 r0, r1;
;           if (resf) { r0 = gld_nt<f32x4>(resf, eo * 4u); r1 = gld_nt<f32x4>(resf, eo * 4u + 16u); }
;           else unpk8(gld_nt<u32x4>(resb, eo * 2u), r0, r1);
;           const f32x4 o0 = r0 + acc[ai][bj][m][0], o1 = r1 + acc[ai][bj][m][1];
;           if (outf) { gst<f32x4>(outf, eo * 4u, o0); gst<f32x4>(outf, eo * 4u + 16u, o1); }
;           wv[bj] = pk8(o0, o1);
;           s += o0[0] * o0[0] + o0[1] * o0[1] + o0[2] * o0[2] + o0[3] * o0[3] + o1[0] * o1[0] + o1[1] * o1[1] + o1[2] * o1[2] + o1[3] * o1[3];
;         }
;         if (outb) st_rows16(outb, DM * 2u, (unsigned)(row - fr), (unsigned)(pn * BM + wc * 64), fr, fq, wv[0], wv[1]);
;         s += __shfl_xor(s, 16); s += __shfl_xor(s, 32);
;         if (fq == 0) atomicAdd(ssq + row, s);
;         __builtin_amdgcn_sched_barrier(0);
;       }
;   }
.LBB0_554:
	s_lshl_b32 s21, s58, 8
	s_add_i32 s21, s21, s11
	v_lshl_or_b32 v141, s54, 8, v144
	v_or_b32_e32 v140, s21, v142
	v_lshlrev_b32_e32 v154, 2, v141
	v_lshl_add_u32 v248, v140, 12, v154
	global_load_dwordx4 v[176:179], v248, s[16:17] nt
	global_load_dwordx4 v[180:183], v248, s[16:17] offset:16 nt
	global_load_dwordx4 v[184:187], v248, s[16:17] offset:128 nt
	global_load_dwordx4 v[188:191], v248, s[16:17] offset:144 nt
	v_add_u32_e32 v249, 0x10000, v248
	global_load_dwordx4 v[192:195], v249, s[16:17] nt
	global_load_dwordx4 v[196:199], v249, s[16:17] offset:16 nt
	global_load_dwordx4 v[200:203], v249, s[16:17] offset:128 nt
	global_load_dwordx4 v[204:207], v249, s[16:17] offset:144 nt
	v_add_u32_e32 v249, 0x20000, v248
	global_load_dwordx4 v[216:219], v249, s[16:17] nt
	global_load_dwordx4 v[220:223], v249, s[16:17] offset:16 nt
	global_load_dwordx4 v[224:227], v249, s[16:17] offset:128 nt
	global_load_dwordx4 v[228:231], v249, s[16:17] offset:144 nt
	v_add_u32_e32 v249, 0x30000, v248
	global_load_dwordx4 v[232:235], v249, s[16:17] nt
	global_load_dwordx4 v[236:239], v249, s[16:17] offset:16 nt
	global_load_dwordx4 v[240:243], v249, s[16:17] offset:128 nt
	global_load_dwordx4 v[244:247], v249, s[16:17] offset:144 nt
	v_or_b32_e32 v152, v141, v146
	v_or_b32_e32 v141, v141, v147
	v_lshlrev_b32_e32 v153, 1, v152
	v_lshl_add_u32 v152, v141, 1, v151
	v_mov_b32_e32 v155, 0
	v_mov_b32_e32 v172, 0
	v_mov_b32_e32 v173, 0
	v_mov_b32_e32 v174, 0
	s_waitcnt vmcnt(12)
	v_pk_add_f32 v[124:125], v[124:125], v[176:177]
	s_nop 0
	v_cvt_pk_bf16_f32 v141, v124, v125
	v_mul_f32_e32 v125, v125, v125
	v_pk_add_f32 v[116:117], v[116:117], v[184:185]
	v_fmac_f32_e32 v125, v124, v124
	v_mul_f32_e32 v124, v117, v117
	v_pk_add_f32 v[126:127], v[126:127], v[178:179]
	v_pk_add_f32 v[156:157], v[118:119], v[186:187]
	v_fmac_f32_e32 v124, v116, v116
	v_fmac_f32_e32 v125, v126, v126
	v_fmac_f32_e32 v124, v156, v156
	v_pk_add_f32 v[120:121], v[120:121], v[180:181]
	v_pk_add_f32 v[112:113], v[112:113], v[188:189]
	v_fmac_f32_e32 v125, v127, v127
	v_fmac_f32_e32 v124, v157, v157
	v_fmac_f32_e32 v125, v120, v120
	v_fmac_f32_e32 v124, v112, v112
	v_pk_add_f32 v[122:123], v[122:123], v[182:183]
	v_pk_add_f32 v[158:159], v[114:115], v[190:191]
	v_fmac_f32_e32 v125, v121, v121
	v_fmac_f32_e32 v124, v113, v113
	v_fmac_f32_e32 v125, v122, v122
	v_fmac_f32_e32 v124, v158, v158
	v_fmac_f32_e32 v125, v123, v123
	v_fmac_f32_e32 v124, v159, v159
	v_cvt_pk_bf16_f32 v115, v112, v113
	v_add_f32_e32 v112, v125, v124
	ds_bpermute_b32 v113, v214, v112
	v_cvt_pk_bf16_f32 v162, v122, v123
	v_cvt_pk_bf16_f32 v114, v158, v159
	v_cvt_pk_bf16_f32 v118, v156, v157
	v_cvt_pk_bf16_f32 v117, v116, v117
	s_waitcnt lgkmcnt(0)
	v_add_f32_e32 v112, v112, v113
	ds_bpermute_b32 v113, v213, v112
	v_or_b32_e32 v122, s21, v145
	v_cvt_pk_bf16_f32 v160, v126, v127
	v_cvt_pk_bf16_f32 v161, v120, v121
	v_mov_b32_dpp v155, v117 row_ror:8 row_mask:0xf bank_mask:0xf
	v_mov_b32_dpp v172, v118 row_ror:8 row_mask:0xf bank_mask:0xf
	v_mov_b32_dpp v173, v115 row_ror:8 row_mask:0xf bank_mask:0xf
	v_mov_b32_dpp v174, v114 row_ror:8 row_mask:0xf bank_mask:0xf
	v_lshlrev_b32_e32 v122, 11, v122
	v_cndmask_b32_e64 v114, v141, v155, s[6:7]
	v_cndmask_b32_e64 v115, v160, v172, s[6:7]
	v_cndmask_b32_e64 v116, v161, v173, s[6:7]
	v_cndmask_b32_e64 v117, v162, v174, s[6:7]
	v_add_u32_e32 v123, v153, v122
	v_cndmask_b32_e64 v118, v155, v141, s[6:7]
	v_cndmask_b32_e64 v119, v172, v160, s[6:7]
	v_cndmask_b32_e64 v120, v173, v161, s[6:7]
	v_cndmask_b32_e64 v121, v174, v162, s[6:7]
	global_store_dwordx4 v123, v[114:117], s[24:25]
	s_nop 1
	v_add_u32_e32 v114, v152, v122
	global_store_dwordx4 v114, v[118:121], s[24:25]
	s_and_saveexec_b64 s[0:1], s[4:5]
	s_cbranch_execz .LBB0_556
	v_ashrrev_i32_e32 v141, 31, v140
	s_waitcnt lgkmcnt(0)
	v_add_f32_e32 v114, v112, v113
	v_lshl_add_u64 v[112:113], v[140:141], 2, s[78:79]
	global_atomic_add_f32 v[112:113], v114, off
.LBB0_556:
	s_or_b64 exec, exec, s[0:1]
	s_or_b32 s0, s21, 16
	v_or_b32_e32 v112, s0, v142
	s_waitcnt lgkmcnt(0)
	v_add_u32_e32 v249, 0x80000, v248
	global_load_dwordx4 v[176:179], v249, s[16:17] nt
	global_load_dwordx4 v[180:183], v249, s[16:17] offset:16 nt
	global_load_dwordx4 v[184:187], v249, s[16:17] offset:128 nt
	global_load_dwordx4 v[188:191], v249, s[16:17] offset:144 nt
	v_mov_b32_e32 v126, 0
	v_mov_b32_e32 v113, 0
	v_mov_b32_e32 v127, 0
	v_mov_b32_e32 v140, 0
	s_waitcnt vmcnt(14)
	v_pk_add_f32 v[108:109], v[108:109], v[192:193]
	v_pk_add_f32 v[104:105], v[104:105], v[196:197]
	v_cvt_pk_bf16_f32 v118, v108, v109
	v_mul_f32_e32 v109, v109, v109
	v_pk_add_f32 v[100:101], v[100:101], v[200:201]
	v_fmac_f32_e32 v109, v108, v108
	v_mul_f32_e32 v108, v101, v101
	v_pk_add_f32 v[110:111], v[110:111], v[194:195]
	v_pk_add_f32 v[114:115], v[102:103], v[202:203]
	v_fmac_f32_e32 v108, v100, v100
	v_fmac_f32_e32 v109, v110, v110
	v_fmac_f32_e32 v108, v114, v114
	v_pk_add_f32 v[96:97], v[96:97], v[204:205]
	v_fmac_f32_e32 v109, v111, v111
	v_fmac_f32_e32 v108, v115, v115
	v_fmac_f32_e32 v109, v104, v104
	v_fmac_f32_e32 v108, v96, v96
	v_pk_add_f32 v[106:107], v[106:107], v[198:199]
	v_pk_add_f32 v[116:117], v[98:99], v[206:207]
	v_fmac_f32_e32 v109, v105, v105
	v_fmac_f32_e32 v108, v97, v97
	v_fmac_f32_e32 v109, v106, v106
	v_fmac_f32_e32 v108, v116, v116
	v_fmac_f32_e32 v109, v107, v107
	v_fmac_f32_e32 v108, v117, v117
	v_cvt_pk_bf16_f32 v99, v96, v97
	v_add_f32_e32 v96, v109, v108
	ds_bpermute_b32 v97, v214, v96
	v_cvt_pk_bf16_f32 v121, v106, v107
	v_cvt_pk_bf16_f32 v98, v116, v117
	v_cvt_pk_bf16_f32 v102, v114, v115
	v_cvt_pk_bf16_f32 v101, v100, v101
	s_waitcnt lgkmcnt(0)
	v_add_f32_e32 v96, v96, v97
	ds_bpermute_b32 v97, v213, v96
	v_or_b32_e32 v106, s0, v145
	v_cvt_pk_bf16_f32 v119, v110, v111
	v_cvt_pk_bf16_f32 v120, v104, v105
	v_mov_b32_dpp v113, v101 row_ror:8 row_mask:0xf bank_mask:0xf
	v_mov_b32_dpp v126, v102 row_ror:8 row_mask:0xf bank_mask:0xf
	v_mov_b32_dpp v127, v99 row_ror:8 row_mask:0xf bank_mask:0xf
	v_mov_b32_dpp v140, v98 row_ror:8 row_mask:0xf bank_mask:0xf
	v_lshlrev_b32_e32 v106, 11, v106
	v_cndmask_b32_e64 v98, v118, v113, s[6:7]
	v_cndmask_b32_e64 v99, v119, v126, s[6:7]
	v_cndmask_b32_e64 v100, v120, v127, s[6:7]
	v_cndmask_b32_e64 v101, v121, v140, s[6:7]
	v_add_u32_e32 v107, v153, v106
	v_cndmask_b32_e64 v102, v113, v118, s[6:7]
	v_cndmask_b32_e64 v103, v126, v119, s[6:7]
	v_cndmask_b32_e64 v104, v127, v120, s[6:7]
	v_cndmask_b32_e64 v105, v140, v121, s[6:7]
	global_store_dwordx4 v107, v[98:101], s[24:25]
	s_nop 1
	v_add_u32_e32 v98, v152, v106
	global_store_dwordx4 v98, v[102:105], s[24:25]
	s_and_saveexec_b64 s[0:1], s[4:5]
	s_cbranch_execz .LBB0_558
	v_ashrrev_i32_e32 v113, 31, v112
	s_waitcnt lgkmcnt(0)
	v_add_f32_e32 v98, v96, v97
	v_lshl_add_u64 v[96:97], v[112:113], 2, s[78:79]
	global_atomic_add_f32 v[96:97], v98, off
; template <class T> DI T gld_nt(const void* base, unsigned off) { return __builtin_nontemporal_load((const T*)((const char*)base + off)); }
; DI u32x4 pk8(const f32x4& a, const f32x4& b) { u32x4 w; w.x = pk2(a[0], a[1]); w.y = pk2(a[2], a[3]); w.z = pk2(b[0], b[1]); w.w = pk2(b[2], b[3]); return w; }
; DI void unpk8(const u32x4& w, f32x4& a, f32x4& b) { a[0] = bf_lo(w.x); a[1] = bf_hi(w.x); a[2] = bf_lo(w.y); a[3] = bf_hi(w.y); b[0] = bf_lo(w.z); b[1] = bf_hi(w.z); b[2] = bf_lo(w.w); b[3] = bf_hi(w.w); }
;   DI void operator()(g8::Acc& acc, int pm, int pn, int wr, int wc, int fr, int fq) const {
;     using namespace g8;
; #pragma unroll
;     for (int ai = 0; ai < 2; ++ai)
; #pragma unroll
;       for (int m = 0; m < 4; ++m) {
;         const int row = pm * BM + ai * HALF + wr * 64 + m * 16 + fr; float s = 0.f; u32x4 wv[2];
; #pragma unroll
;         for (int bj = 0; bj < 2; ++bj) {
;           const int col8 = pn * BM + wc * 64 + bj * 32 + fq * 8; const unsigned eo = (unsigned)row * DM + (unsigned)col8;
;           f32x4 r0, r1;
;           if (resf) { r0 = gld_nt<f32x4>(resf, eo * 4u); r1 = gld_nt<f32x4>(resf, eo * 4u + 16u); }
;           else unpk8(gld_nt<u32x4>(resb, eo * 2u), r0, r1);
;           const f32x4 o0 = r0 + acc[ai][bj][m][0], o1 = r1 + acc[ai][bj][m][1];
;           if (outf) { gst<f32x4>(outf, eo * 4u, o0); gst<f32x4>(outf, eo * 4u + 16u, o1); }
;           wv[bj] = pk8(o0, o1);
;           s += o0[0] * o0[0] + o0[1] * o0[1] + o0[2] * o0[2] + o0[3] * o0[3] + o1[0] * o1[0] + o1[1] * o1[1] + o1[2] * o1[2] + o1[3] * o1[3];
;         }
;         if (outb) st_rows16(outb, DM * 2u, (unsigned)(row - fr), (unsigned)(pn * BM + wc * 64), fr, fq, wv[0], wv[1]);
;         s += __shfl_xor(s, 16); s += __shfl_xor(s, 32);
;         if (fq == 0) atomicAdd(ssq + row, s);
;         __builtin_amdgcn_sched_barrier(0);
;       }
;   }
.LBB0_558:
	s_or_b64 exec, exec, s[0:1]
	s_or_b32 s0, s21, 32
	v_or_b32_e32 v96, s0, v142
	s_waitcnt lgkmcnt(0)
	v_add_u32_e32 v249, 0x90000, v248
	global_load_dwordx4 v[192:195], v249, s[16:17] nt
	global_load_dwordx4 v[196:199], v249, s[16:17] offset:16 nt
	global_load_dwordx4 v[200:203], v249, s[16:17] offset:128 nt
	global_load_dwordx4 v[204:207], v249, s[16:17] offset:144 nt
	v_mov_b32_e32 v114, 0
	v_mov_b32_e32 v97, 0
	v_mov_b32_e32 v115, 0
	v_mov_b32_e32 v116, 0
	s_waitcnt vmcnt(16)
	v_pk_add_f32 v[92:93], v[92:93], v[216:217]
	v_pk_add_f32 v[88:89], v[88:89], v[220:221]
	v_cvt_pk_bf16_f32 v102, v92, v93
	v_mul_f32_e32 v93, v93, v93
	v_pk_add_f32 v[84:85], v[84:85], v[224:225]
	v_fmac_f32_e32 v93, v92, v92
	v_mul_f32_e32 v92, v85, v85
	v_pk_add_f32 v[94:95], v[94:95], v[218:219]
	v_pk_add_f32 v[98:99], v[86:87], v[226:227]
	v_fmac_f32_e32 v92, v84, v84
	v_fmac_f32_e32 v93, v94, v94
	v_fmac_f32_e32 v92, v98, v98
	v_pk_add_f32 v[80:81], v[80:81], v[228:229]
	v_fmac_f32_e32 v93, v95, v95
	v_fmac_f32_e32 v92, v99, v99
	v_fmac_f32_e32 v93, v88, v88
	v_fmac_f32_e32 v92, v80, v80
	v_pk_add_f32 v[90:91], v[90:91], v[222:223]
	v_pk_add_f32 v[100:101], v[82:83], v[230:231]
	v_fmac_f32_e32 v93, v89, v89
	v_fmac_f32_e32 v92, v81, v81
	v_fmac_f32_e32 v93, v90, v90
	v_fmac_f32_e32 v92, v100, v100
	v_fmac_f32_e32 v93, v91, v91
	v_fmac_f32_e32 v92, v101, v101
	v_cvt_pk_bf16_f32 v83, v80, v81
	v_add_f32_e32 v80, v93, v92
	ds_bpermute_b32 v81, v214, v80
	v_cvt_pk_bf16_f32 v105, v90, v91
	v_cvt_pk_bf16_f32 v82, v100, v101
	v_cvt_pk_bf16_f32 v86, v98, v99
	v_cvt_pk_bf16_f32 v85, v84, v85
	s_waitcnt lgkmcnt(0)
	v_add_f32_e32 v80, v80, v81
	ds_bpermute_b32 v81, v213, v80
	v_or_b32_e32 v90, s0, v145
	v_cvt_pk_bf16_f32 v103, v94, v95
	v_cvt_pk_bf16_f32 v104, v88, v89
	v_mov_b32_dpp v97, v85 row_ror:8 row_mask:0xf bank_mask:0xf
	v_mov_b32_dpp v114, v86 row_ror:8 row_mask:0xf bank_mask:0xf
	v_mov_b32_dpp v115, v83 row_ror:8 row_mask:0xf bank_mask:0xf
	v_mov_b32_dpp v116, v82 row_ror:8 row_mask:0xf bank_mask:0xf
	v_lshlrev_b32_e32 v90, 11, v90
	v_cndmask_b32_e64 v82, v102, v97, s[6:7]
	v_cndmask_b32_e64 v83, v103, v114, s[6:7]
	v_cndmask_b32_e64 v84, v104, v115, s[6:7]
	v_cndmask_b32_e64 v85, v105, v116, s[6:7]
	v_add_u32_e32 v91, v153, v90
	v_cndmask_b32_e64 v86, v97, v102, s[6:7]
	v_cndmask_b32_e64 v87, v114, v103, s[6:7]
	v_cndmask_b32_e64 v88, v115, v104, s[6:7]
	v_cndmask_b32_e64 v89, v116, v105, s[6:7]
	global_store_dwordx4 v91, v[82:85], s[24:25]
	s_nop 1
	v_add_u32_e32 v82, v152, v90
	global_store_dwordx4 v82, v[86:89], s[24:25]
	s_and_saveexec_b64 s[0:1], s[4:5]
	s_cbranch_execz .LBB0_560
	v_ashrrev_i32_e32 v97, 31, v96
	s_waitcnt lgkmcnt(0)
	v_add_f32_e32 v82, v80, v81
	v_lshl_add_u64 v[80:81], v[96:97], 2, s[78:79]
	global_atomic_add_f32 v[80:81], v82, off
.LBB0_560:
	s_or_b64 exec, exec, s[0:1]
	s_or_b32 s0, s21, 48
	v_or_b32_e32 v80, s0, v142
	s_waitcnt lgkmcnt(0)
	v_add_u32_e32 v249, 0xa0000, v248
	global_load_dwordx4 v[216:219], v249, s[16:17] nt
	global_load_dwordx4 v[220:223], v249, s[16:17] offset:16 nt
	global_load_dwordx4 v[224:227], v249, s[16:17] offset:128 nt
	global_load_dwordx4 v[228:231], v249, s[16:17] offset:144 nt
	v_mov_b32_e32 v98, 0
	v_mov_b32_e32 v81, 0
	v_mov_b32_e32 v99, 0
	v_mov_b32_e32 v100, 0
	s_waitcnt vmcnt(18)
	v_pk_add_f32 v[76:77], v[76:77], v[232:233]
	v_pk_add_f32 v[72:73], v[72:73], v[236:237]
	v_cvt_pk_bf16_f32 v86, v76, v77
	v_mul_f32_e32 v77, v77, v77
	v_pk_add_f32 v[68:69], v[68:69], v[240:241]
	v_fmac_f32_e32 v77, v76, v76
	v_mul_f32_e32 v76, v69, v69
	v_pk_add_f32 v[78:79], v[78:79], v[234:235]
	v_pk_add_f32 v[82:83], v[70:71], v[242:243]
	v_fmac_f32_e32 v76, v68, v68
	v_fmac_f32_e32 v77, v78, v78
	v_fmac_f32_e32 v76, v82, v82
	v_pk_add_f32 v[64:65], v[64:65], v[244:245]
	v_fmac_f32_e32 v77, v79, v79
	v_fmac_f32_e32 v76, v83, v83
	v_fmac_f32_e32 v77, v72, v72
	v_fmac_f32_e32 v76, v64, v64
	v_pk_add_f32 v[74:75], v[74:75], v[238:239]
	v_pk_add_f32 v[84:85], v[66:67], v[246:247]
	v_fmac_f32_e32 v77, v73, v73
	v_fmac_f32_e32 v76, v65, v65
	v_fmac_f32_e32 v77, v74, v74
	v_fmac_f32_e32 v76, v84, v84
	v_fmac_f32_e32 v77, v75, v75
	v_fmac_f32_e32 v76, v85, v85
	v_cvt_pk_bf16_f32 v67, v64, v65
	v_add_f32_e32 v64, v77, v76
	ds_bpermute_b32 v65, v214, v64
	v_cvt_pk_bf16_f32 v89, v74, v75
	v_cvt_pk_bf16_f32 v66, v84, v85
	v_cvt_pk_bf16_f32 v70, v82, v83
	v_cvt_pk_bf16_f32 v69, v68, v69
	s_waitcnt lgkmcnt(0)
	v_add_f32_e32 v64, v64, v65
	ds_bpermute_b32 v65, v213, v64
	v_or_b32_e32 v74, s0, v145
	v_cvt_pk_bf16_f32 v87, v78, v79
	v_cvt_pk_bf16_f32 v88, v72, v73
	v_mov_b32_dpp v81, v69 row_ror:8 row_mask:0xf bank_mask:0xf
	v_mov_b32_dpp v98, v70 row_ror:8 row_mask:0xf bank_mask:0xf
	v_mov_b32_dpp v99, v67 row_ror:8 row_mask:0xf bank_mask:0xf
	v_mov_b32_dpp v100, v66 row_ror:8 row_mask:0xf bank_mask:0xf
	v_lshlrev_b32_e32 v74, 11, v74
	v_cndmask_b32_e64 v66, v86, v81, s[6:7]
	v_cndmask_b32_e64 v67, v87, v98, s[6:7]
	v_cndmask_b32_e64 v68, v88, v99, s[6:7]
	v_cndmask_b32_e64 v69, v89, v100, s[6:7]
	v_add_u32_e32 v75, v153, v74
	v_cndmask_b32_e64 v70, v81, v86, s[6:7]
	v_cndmask_b32_e64 v71, v98, v87, s[6:7]
	v_cndmask_b32_e64 v72, v99, v88, s[6:7]
	v_cndmask_b32_e64 v73, v100, v89, s[6:7]
	global_store_dwordx4 v75, v[66:69], s[24:25]
	s_nop 1
	v_add_u32_e32 v66, v152, v74
	global_store_dwordx4 v66, v[70:73], s[24:25]
	s_and_saveexec_b64 s[0:1], s[4:5]
	s_cbranch_execz .LBB0_562
	v_ashrrev_i32_e32 v81, 31, v80
	s_waitcnt lgkmcnt(0)
	v_add_f32_e32 v66, v64, v65
	v_lshl_add_u64 v[64:65], v[80:81], 2, s[78:79]
	global_atomic_add_f32 v[64:65], v66, off
; template <class T> DI T gld_nt(const void* base, unsigned off) { return __builtin_nontemporal_load((const T*)((const char*)base + off)); }
; DI u32x4 pk8(const f32x4& a, const f32x4& b) { u32x4 w; w.x = pk2(a[0], a[1]); w.y = pk2(a[2], a[3]); w.z = pk2(b[0], b[1]); w.w = pk2(b[2], b[3]); return w; }
; DI void unpk8(const u32x4& w, f32x4& a, f32x4& b) { a[0] = bf_lo(w.x); a[1] = bf_hi(w.x); a[2] = bf_lo(w.y); a[3] = bf_hi(w.y); b[0] = bf_lo(w.z); b[1] = bf_hi(w.z); b[2] = bf_lo(w.w); b[3] = bf_hi(w.w); }
;   DI void operator()(g8::Acc& acc, int pm, int pn, int wr, int wc, int fr, int fq) const {
;     using namespace g8;
; #pragma unroll
;     for (int ai = 0; ai < 2; ++ai)
; #pragma unroll
;       for (int m = 0; m < 4; ++m) {
;         const int row = pm * BM + ai * HALF + wr * 64 + m * 16 + fr; float s = 0.f; u32x4 wv[2];
; #pragma unroll
;         for (int bj = 0; bj < 2; ++bj) {
;           const int col8 = pn * BM + wc * 64 + bj * 32 + fq * 8; const unsigned eo = (unsigned)row * DM + (unsigned)col8;
;           f32x4 r0, r1;
;           if (resf) { r0 = gld_nt<f32x4>(resf, eo * 4u); r1 = gld_nt<f32x4>(resf, eo * 4u + 16u); }
;           else unpk8(gld_nt<u32x4>(resb, eo * 2u), r0, r1);
;           const f32x4 o0 = r0 + acc[ai][bj][m][0], o1 = r1 + acc[ai][bj][m][1];
;           if (outf) { gst<f32x4>(outf, eo * 4u, o0); gst<f32x4>(outf, eo * 4u + 16u, o1); }
;           wv[bj] = pk8(o0, o1);
;           s += o0[0] * o0[0] + o0[1] * o0[1] + o0[2] * o0[2] + o0[3] * o0[3] + o1[0] * o1[0] + o1[1] * o1[1] + o1[2] * o1[2] + o1[3] * o1[3];
;         }
;         if (outb) st_rows16(outb, DM * 2u, (unsigned)(row - fr), (unsigned)(pn * BM + wc * 64), fr, fq, wv[0], wv[1]);
;         s += __shfl_xor(s, 16); s += __shfl_xor(s, 32);
;         if (fq == 0) atomicAdd(ssq + row, s);
;         __builtin_amdgcn_sched_barrier(0);
;       }
;   }
.LBB0_562:
	s_or_b64 exec, exec, s[0:1]
	s_add_i32 s0, s21, 0x80
	v_or_b32_e32 v64, s0, v142
	s_waitcnt lgkmcnt(0)
	v_add_u32_e32 v249, 0xb0000, v248
	global_load_dwordx4 v[232:235], v249, s[16:17] nt
	global_load_dwordx4 v[236:239], v249, s[16:17] offset:16 nt
	global_load_dwordx4 v[240:243], v249, s[16:17] offset:128 nt
	global_load_dwordx4 v[244:247], v249, s[16:17] offset:144 nt
	v_mov_b32_e32 v82, 0
	v_mov_b32_e32 v65, 0
	v_mov_b32_e32 v83, 0
	v_mov_b32_e32 v84, 0
	s_waitcnt vmcnt(18)
	v_pk_add_f32 v[60:61], v[60:61], v[176:177]
	v_pk_add_f32 v[56:57], v[56:57], v[180:181]
	v_cvt_pk_bf16_f32 v70, v60, v61
	v_mul_f32_e32 v61, v61, v61
	v_pk_add_f32 v[52:53], v[52:53], v[184:185]
	v_fmac_f32_e32 v61, v60, v60
	v_mul_f32_e32 v60, v53, v53
	v_pk_add_f32 v[62:63], v[62:63], v[178:179]
	v_pk_add_f32 v[66:67], v[54:55], v[186:187]
	v_fmac_f32_e32 v60, v52, v52
	v_fmac_f32_e32 v61, v62, v62
	v_fmac_f32_e32 v60, v66, v66
	v_pk_add_f32 v[48:49], v[48:49], v[188:189]
	v_fmac_f32_e32 v61, v63, v63
	v_fmac_f32_e32 v60, v67, v67
	v_fmac_f32_e32 v61, v56, v56
	v_fmac_f32_e32 v60, v48, v48
	v_pk_add_f32 v[58:59], v[58:59], v[182:183]
	v_pk_add_f32 v[68:69], v[50:51], v[190:191]
	v_fmac_f32_e32 v61, v57, v57
	v_fmac_f32_e32 v60, v49, v49
	v_fmac_f32_e32 v61, v58, v58
	v_fmac_f32_e32 v60, v68, v68
	v_fmac_f32_e32 v61, v59, v59
	v_fmac_f32_e32 v60, v69, v69
	v_cvt_pk_bf16_f32 v51, v48, v49
	v_add_f32_e32 v48, v61, v60
	ds_bpermute_b32 v49, v214, v48
	v_cvt_pk_bf16_f32 v73, v58, v59
	v_cvt_pk_bf16_f32 v50, v68, v69
	v_cvt_pk_bf16_f32 v54, v66, v67
	v_cvt_pk_bf16_f32 v53, v52, v53
	s_waitcnt lgkmcnt(0)
	v_add_f32_e32 v48, v48, v49
	ds_bpermute_b32 v49, v213, v48
	v_or_b32_e32 v58, s0, v145
	v_cvt_pk_bf16_f32 v71, v62, v63
	v_cvt_pk_bf16_f32 v72, v56, v57
	v_mov_b32_dpp v65, v53 row_ror:8 row_mask:0xf bank_mask:0xf
	v_mov_b32_dpp v82, v54 row_ror:8 row_mask:0xf bank_mask:0xf
	v_mov_b32_dpp v83, v51 row_ror:8 row_mask:0xf bank_mask:0xf
	v_mov_b32_dpp v84, v50 row_ror:8 row_mask:0xf bank_mask:0xf
	v_lshlrev_b32_e32 v58, 11, v58
	v_cndmask_b32_e64 v50, v70, v65, s[6:7]
	v_cndmask_b32_e64 v51, v71, v82, s[6:7]
	v_cndmask_b32_e64 v52, v72, v83, s[6:7]
	v_cndmask_b32_e64 v53, v73, v84, s[6:7]
	v_add_u32_e32 v59, v153, v58
	v_cndmask_b32_e64 v54, v65, v70, s[6:7]
	v_cndmask_b32_e64 v55, v82, v71, s[6:7]
	v_cndmask_b32_e64 v56, v83, v72, s[6:7]
	v_cndmask_b32_e64 v57, v84, v73, s[6:7]
	global_store_dwordx4 v59, v[50:53], s[24:25]
	s_nop 1
	v_add_u32_e32 v50, v152, v58
	global_store_dwordx4 v50, v[54:57], s[24:25]
	s_and_saveexec_b64 s[0:1], s[4:5]
	s_cbranch_execz .LBB0_564
	v_ashrrev_i32_e32 v65, 31, v64
	s_waitcnt lgkmcnt(0)
	v_add_f32_e32 v50, v48, v49
	v_lshl_add_u64 v[48:49], v[64:65], 2, s[78:79]
	global_atomic_add_f32 v[48:49], v50, off
.LBB0_564:
	s_or_b64 exec, exec, s[0:1]
	s_add_i32 s0, s21, 0x90
	v_or_b32_e32 v48, s0, v142
	s_waitcnt lgkmcnt(0)
	v_mov_b32_e32 v66, 0
	v_mov_b32_e32 v49, 0
	v_mov_b32_e32 v67, 0
	v_mov_b32_e32 v68, 0
	s_waitcnt vmcnt(14)
	v_pk_add_f32 v[44:45], v[44:45], v[192:193]
	v_pk_add_f32 v[40:41], v[40:41], v[196:197]
	v_cvt_pk_bf16_f32 v54, v44, v45
	v_mul_f32_e32 v45, v45, v45
	v_pk_add_f32 v[36:37], v[36:37], v[200:201]
	v_fmac_f32_e32 v45, v44, v44
	v_mul_f32_e32 v44, v37, v37
	v_pk_add_f32 v[46:47], v[46:47], v[194:195]
	v_pk_add_f32 v[50:51], v[38:39], v[202:203]
	v_fmac_f32_e32 v44, v36, v36
	v_fmac_f32_e32 v45, v46, v46
	v_fmac_f32_e32 v44, v50, v50
	v_pk_add_f32 v[32:33], v[32:33], v[204:205]
	v_fmac_f32_e32 v45, v47, v47
	v_fmac_f32_e32 v44, v51, v51
	v_fmac_f32_e32 v45, v40, v40
	v_fmac_f32_e32 v44, v32, v32
	v_pk_add_f32 v[42:43], v[42:43], v[198:199]
	v_pk_add_f32 v[52:53], v[34:35], v[206:207]
	v_fmac_f32_e32 v45, v41, v41
	v_fmac_f32_e32 v44, v33, v33
	v_fmac_f32_e32 v45, v42, v42
	v_fmac_f32_e32 v44, v52, v52
	v_fmac_f32_e32 v45, v43, v43
	v_fmac_f32_e32 v44, v53, v53
	v_cvt_pk_bf16_f32 v35, v32, v33
	v_add_f32_e32 v32, v45, v44
	ds_bpermute_b32 v33, v214, v32
	v_cvt_pk_bf16_f32 v57, v42, v43
	v_cvt_pk_bf16_f32 v34, v52, v53
	v_cvt_pk_bf16_f32 v38, v50, v51
	v_cvt_pk_bf16_f32 v37, v36, v37
	s_waitcnt lgkmcnt(0)
	v_add_f32_e32 v32, v32, v33
	ds_bpermute_b32 v33, v213, v32
	v_or_b32_e32 v42, s0, v145
	v_cvt_pk_bf16_f32 v55, v46, v47
	v_cvt_pk_bf16_f32 v56, v40, v41
	v_mov_b32_dpp v49, v37 row_ror:8 row_mask:0xf bank_mask:0xf
	v_mov_b32_dpp v66, v38 row_ror:8 row_mask:0xf bank_mask:0xf
	v_mov_b32_dpp v67, v35 row_ror:8 row_mask:0xf bank_mask:0xf
	v_mov_b32_dpp v68, v34 row_ror:8 row_mask:0xf bank_mask:0xf
	v_lshlrev_b32_e32 v42, 11, v42
	v_cndmask_b32_e64 v34, v54, v49, s[6:7]
	v_cndmask_b32_e64 v35, v55, v66, s[6:7]
	v_cndmask_b32_e64 v36, v56, v67, s[6:7]
	v_cndmask_b32_e64 v37, v57, v68, s[6:7]
	v_add_u32_e32 v43, v153, v42
	v_cndmask_b32_e64 v38, v49, v54, s[6:7]
	v_cndmask_b32_e64 v39, v66, v55, s[6:7]
	v_cndmask_b32_e64 v40, v67, v56, s[6:7]
	v_cndmask_b32_e64 v41, v68, v57, s[6:7]
	global_store_dwordx4 v43, v[34:37], s[24:25]
	s_nop 1
	v_add_u32_e32 v34, v152, v42
	global_store_dwordx4 v34, v[38:41], s[24:25]
	s_and_saveexec_b64 s[0:1], s[4:5]
	s_cbranch_execz .LBB0_566
	v_ashrrev_i32_e32 v49, 31, v48
	s_waitcnt lgkmcnt(0)
	v_add_f32_e32 v34, v32, v33
	v_lshl_add_u64 v[32:33], v[48:49], 2, s[78:79]
	global_atomic_add_f32 v[32:33], v34, off
; template <class T> DI T gld_nt(const void* base, unsigned off) { return __builtin_nontemporal_load((const T*)((const char*)base + off)); }
; DI u32x4 pk8(const f32x4& a, const f32x4& b) { u32x4 w; w.x = pk2(a[0], a[1]); w.y = pk2(a[2], a[3]); w.z = pk2(b[0], b[1]); w.w = pk2(b[2], b[3]); return w; }
; DI void unpk8(const u32x4& w, f32x4& a, f32x4& b) { a[0] = bf_lo(w.x); a[1] = bf_hi(w.x); a[2] = bf_lo(w.y); a[3] = bf_hi(w.y); b[0] = bf_lo(w.z); b[1] = bf_hi(w.z); b[2] = bf_lo(w.w); b[3] = bf_hi(w.w); }
;   DI void operator()(g8::Acc& acc, int pm, int pn, int wr, int wc, int fr, int fq) const {
;     using namespace g8;
; #pragma unroll
;     for (int ai = 0; ai < 2; ++ai)
; #pragma unroll
;       for (int m = 0; m < 4; ++m) {
;         const int row = pm * BM + ai * HALF + wr * 64 + m * 16 + fr; float s = 0.f; u32x4 wv[2];
; #pragma unroll
;         for (int bj = 0; bj < 2; ++bj) {
;           const int col8 = pn * BM + wc * 64 + bj * 32 + fq * 8; const unsigned eo = (unsigned)row * DM + (unsigned)col8;
;           f32x4 r0, r1;
;           if (resf) { r0 = gld_nt<f32x4>(resf, eo * 4u); r1 = gld_nt<f32x4>(resf, eo * 4u + 16u); }
;           else unpk8(gld_nt<u32x4>(resb, eo * 2u), r0, r1);
;           const f32x4 o0 = r0 + acc[ai][bj][m][0], o1 = r1 + acc[ai][bj][m][1];
;           if (outf) { gst<f32x4>(outf, eo * 4u, o0); gst<f32x4>(outf, eo * 4u + 16u, o1); }
;           wv[bj] = pk8(o0, o1);
;           s += o0[0] * o0[0] + o0[1] * o0[1] + o0[2] * o0[2] + o0[3] * o0[3] + o1[0] * o1[0] + o1[1] * o1[1] + o1[2] * o1[2] + o1[3] * o1[3];
;         }
;         if (outb) st_rows16(outb, DM * 2u, (unsigned)(row - fr), (unsigned)(pn * BM + wc * 64), fr, fq, wv[0], wv[1]);
;         s += __shfl_xor(s, 16); s += __shfl_xor(s, 32);
;         if (fq == 0) atomicAdd(ssq + row, s);
;         __builtin_amdgcn_sched_barrier(0);
;       }
;   }
.LBB0_566:
	s_or_b64 exec, exec, s[0:1]
	s_add_i32 s0, s21, 0xa0
	v_or_b32_e32 v32, s0, v142
	s_waitcnt lgkmcnt(0)
	v_mov_b32_e32 v50, 0
	v_mov_b32_e32 v33, 0
	v_mov_b32_e32 v51, 0
	v_mov_b32_e32 v52, 0
	s_waitcnt vmcnt(10)
	v_pk_add_f32 v[28:29], v[28:29], v[216:217]
	v_pk_add_f32 v[24:25], v[24:25], v[220:221]
	v_cvt_pk_bf16_f32 v38, v28, v29
	v_mul_f32_e32 v29, v29, v29
	v_pk_add_f32 v[20:21], v[20:21], v[224:225]
	v_fmac_f32_e32 v29, v28, v28
	v_mul_f32_e32 v28, v21, v21
	v_pk_add_f32 v[30:31], v[30:31], v[218:219]
	v_pk_add_f32 v[34:35], v[22:23], v[226:227]
	v_fmac_f32_e32 v28, v20, v20
	v_fmac_f32_e32 v29, v30, v30
	v_fmac_f32_e32 v28, v34, v34
	v_pk_add_f32 v[16:17], v[16:17], v[228:229]
	v_fmac_f32_e32 v29, v31, v31
	v_fmac_f32_e32 v28, v35, v35
	v_fmac_f32_e32 v29, v24, v24
	v_fmac_f32_e32 v28, v16, v16
	v_pk_add_f32 v[26:27], v[26:27], v[222:223]
	v_pk_add_f32 v[36:37], v[18:19], v[230:231]
	v_fmac_f32_e32 v29, v25, v25
	v_fmac_f32_e32 v28, v17, v17
	v_fmac_f32_e32 v29, v26, v26
	v_fmac_f32_e32 v28, v36, v36
	v_fmac_f32_e32 v29, v27, v27
	v_fmac_f32_e32 v28, v37, v37
	v_cvt_pk_bf16_f32 v19, v16, v17
	v_add_f32_e32 v16, v29, v28
	ds_bpermute_b32 v17, v214, v16
	v_cvt_pk_bf16_f32 v41, v26, v27
	v_cvt_pk_bf16_f32 v18, v36, v37
	v_cvt_pk_bf16_f32 v22, v34, v35
	v_cvt_pk_bf16_f32 v21, v20, v21
	s_waitcnt lgkmcnt(0)
	v_add_f32_e32 v16, v16, v17
	ds_bpermute_b32 v17, v213, v16
	v_or_b32_e32 v26, s0, v145
	v_cvt_pk_bf16_f32 v39, v30, v31
	v_cvt_pk_bf16_f32 v40, v24, v25
	v_mov_b32_dpp v33, v21 row_ror:8 row_mask:0xf bank_mask:0xf
	v_mov_b32_dpp v50, v22 row_ror:8 row_mask:0xf bank_mask:0xf
	v_mov_b32_dpp v51, v19 row_ror:8 row_mask:0xf bank_mask:0xf
	v_mov_b32_dpp v52, v18 row_ror:8 row_mask:0xf bank_mask:0xf
	v_lshlrev_b32_e32 v26, 11, v26
	v_cndmask_b32_e64 v18, v38, v33, s[6:7]
	v_cndmask_b32_e64 v19, v39, v50, s[6:7]
	v_cndmask_b32_e64 v20, v40, v51, s[6:7]
	v_cndmask_b32_e64 v21, v41, v52, s[6:7]
	v_add_u32_e32 v27, v153, v26
	v_cndmask_b32_e64 v22, v33, v38, s[6:7]
	v_cndmask_b32_e64 v23, v50, v39, s[6:7]
	v_cndmask_b32_e64 v24, v51, v40, s[6:7]
	v_cndmask_b32_e64 v25, v52, v41, s[6:7]
	global_store_dwordx4 v27, v[18:21], s[24:25]
	s_nop 1
	v_add_u32_e32 v18, v152, v26
	global_store_dwordx4 v18, v[22:25], s[24:25]
	s_and_saveexec_b64 s[0:1], s[4:5]
	s_cbranch_execz .LBB0_568
	v_ashrrev_i32_e32 v33, 31, v32
	s_waitcnt lgkmcnt(0)
	v_add_f32_e32 v18, v16, v17
	v_lshl_add_u64 v[16:17], v[32:33], 2, s[78:79]
	global_atomic_add_f32 v[16:17], v18, off
.LBB0_568:
	s_or_b64 exec, exec, s[0:1]
	s_addk_i32 s21, 0xb0
	v_or_b32_e32 v16, s21, v142
	s_waitcnt lgkmcnt(0)
	v_mov_b32_e32 v34, 0
	v_mov_b32_e32 v17, 0
	v_mov_b32_e32 v35, 0
	v_mov_b32_e32 v36, 0
	s_waitcnt vmcnt(6)
	v_pk_add_f32 v[12:13], v[12:13], v[232:233]
	v_pk_add_f32 v[8:9], v[8:9], v[236:237]
	v_cvt_pk_bf16_f32 v22, v12, v13
	v_mul_f32_e32 v13, v13, v13
	v_pk_add_f32 v[4:5], v[4:5], v[240:241]
	v_fmac_f32_e32 v13, v12, v12
	v_mul_f32_e32 v12, v5, v5
	v_pk_add_f32 v[14:15], v[14:15], v[234:235]
	v_pk_add_f32 v[18:19], v[6:7], v[242:243]
	v_fmac_f32_e32 v12, v4, v4
	v_fmac_f32_e32 v13, v14, v14
	v_fmac_f32_e32 v12, v18, v18
	v_pk_add_f32 v[0:1], v[0:1], v[244:245]
	v_fmac_f32_e32 v13, v15, v15
	v_fmac_f32_e32 v12, v19, v19
	v_fmac_f32_e32 v13, v8, v8
	v_fmac_f32_e32 v12, v0, v0
	v_pk_add_f32 v[10:11], v[10:11], v[238:239]
	v_pk_add_f32 v[20:21], v[2:3], v[246:247]
	v_fmac_f32_e32 v13, v9, v9
	v_fmac_f32_e32 v12, v1, v1
	v_fmac_f32_e32 v13, v10, v10
	v_fmac_f32_e32 v12, v20, v20
	v_fmac_f32_e32 v13, v11, v11
	v_fmac_f32_e32 v12, v21, v21
	v_cvt_pk_bf16_f32 v3, v0, v1
	v_add_f32_e32 v0, v13, v12
	ds_bpermute_b32 v1, v214, v0
	v_cvt_pk_bf16_f32 v25, v10, v11
	v_cvt_pk_bf16_f32 v2, v20, v21
	v_cvt_pk_bf16_f32 v6, v18, v19
	v_cvt_pk_bf16_f32 v5, v4, v5
	s_waitcnt lgkmcnt(0)
	v_add_f32_e32 v0, v0, v1
	ds_bpermute_b32 v1, v213, v0
	v_or_b32_e32 v10, s21, v145
	v_cvt_pk_bf16_f32 v23, v14, v15
	v_cvt_pk_bf16_f32 v24, v8, v9
	v_mov_b32_dpp v17, v5 row_ror:8 row_mask:0xf bank_mask:0xf
	v_mov_b32_dpp v34, v6 row_ror:8 row_mask:0xf bank_mask:0xf
	v_mov_b32_dpp v35, v3 row_ror:8 row_mask:0xf bank_mask:0xf
	v_mov_b32_dpp v36, v2 row_ror:8 row_mask:0xf bank_mask:0xf
	v_lshlrev_b32_e32 v10, 11, v10
	v_cndmask_b32_e64 v2, v22, v17, s[6:7]
	v_cndmask_b32_e64 v3, v23, v34, s[6:7]
	v_cndmask_b32_e64 v4, v24, v35, s[6:7]
	v_cndmask_b32_e64 v5, v25, v36, s[6:7]
	v_add_u32_e32 v11, v153, v10
	v_cndmask_b32_e64 v6, v17, v22, s[6:7]
	v_cndmask_b32_e64 v7, v34, v23, s[6:7]
	v_cndmask_b32_e64 v8, v35, v24, s[6:7]
	v_cndmask_b32_e64 v9, v36, v25, s[6:7]
	global_store_dwordx4 v11, v[2:5], s[24:25]
	s_nop 1
	v_add_u32_e32 v2, v152, v10
	global_store_dwordx4 v2, v[6:9], s[24:25]
	s_and_saveexec_b64 s[0:1], s[4:5]
	s_cbranch_execz .LBB0_570
	v_ashrrev_i32_e32 v17, 31, v16
	s_waitcnt lgkmcnt(0)
	v_add_f32_e32 v2, v0, v1
	v_lshl_add_u64 v[0:1], v[16:17], 2, s[78:79]
	global_atomic_add_f32 v[0:1], v2, off

; DI int tidx() { int t = threadIdx.x; asm volatile("" : "+v"(t)); return t; }
; DI bf16_t* slot(const Params& p, int i) { return (bf16_t*)(p.ws + OFF_SLOT + (size_t)i * SLOT); }
; DI void xattn_unit(const bf16_t* __restrict__ Qg, const bf16_t* __restrict__ Kg, const bf16_t* __restrict__ Vg, bf16_t* __restrict__ Og, lds_t* shm) {
;     ...
;   auto issue_tile = [&](const bf16_t* src, int t, unsigned lds_base) __attribute__((always_inline)) {
;     const char* sb = (const char*)src + (size_t)t * tstep; lds_t* base = shm + lds_base + wid * 1024;
; #pragma unroll
;     for (int im = 0; im < 2; ++im) { glds16(sb + im * 256, soff[0], base + im * 16384); glds16(sb + im * 256, soff[1], base + im * 16384 + 8192); }
;   };
;   __syncthreads();
; #pragma unroll
;   for (int t = 0; t < 4; ++t) issue_tile(Kg, t, t * 32768);
;   issue_tile(Vg, 0, 131072);
;   const unsigned q4 = (lane & 15) >> 2, pp = lane & 3, blk = (lane >> 4) & 1;
;   const unsigned xk = (l31 >> 2) & 3, kbase = 2048u * (l31 >> 3) + 64u * (l31 & 7);
;   const unsigned ka0 = kbase + 16u * ((unsigned)h ^ xk), ka2 = kbase + 16u * ((2u + h) ^ xk);
;   const unsigned vrow = 64u * (4u * h + q4), cl = 2u * blk + (pp >> 1);
;   const unsigned va0 = vrow + 16u * (cl ^ (unsigned)h) + 8u * (pp & 1), va1 = vrow + 16u * (cl ^ ((unsigned)h ^ 2u)) + 8u * (pp & 1);
;   const unsigned qoff = ((unsigned)l31 * (unsigned)LDQ + 8u * h) * 2u;
;   f32x16 S[4][2];
; #pragma unroll
;   for (int t = 0; t < 4; ++t)
; #pragma unroll
;     for (int kb = 0; kb < 2; ++kb)
; #pragma unroll
;       for (int i = 0; i < 16; ++i) S[t][kb][i] = 0.f;
;   asm volatile("s_waitcnt vmcnt(0)" ::: "memory");
;   __syncthreads();
;   __builtin_amdgcn_sched_barrier(0);
; DI void cross_attn_own_tiles(const Params& p, lds_t* shm) {
;   const int wid = __builtin_amdgcn_readfirstlane(tidx() >> 6);
;   const bf16_t* Q = slot(p, 3); const bf16_t* KV = (const bf16_t*)(p.ws + OFF_KVX); bf16_t* O = slot(p, 0);
;   for (int i = 0;; ++i) {
;     int pm, pn; if (!g8::tile_coords(i * (int)gridDim.x + (int)blockIdx.x, T_TOK / 256, 4, pm, pn)) break;
;     const int b = pm >> 5, hd = pn; const size_t r0 = (size_t)pm * 256 + wid * 32;
;     xattn_unit(Q + r0 * DM + hd * 256, KV + (size_t)b * 256 * 2048 + hd * 256, KV + (size_t)b * 256 * 2048 + 1024 + hd * 256, O + r0 * DM + hd * 256, shm);
;   }
.LBB0_629:
	s_add_i32 s0, s29, s0
	s_ashr_i32 s1, s0, 31
	s_lshr_b32 s1, s1, 27
	s_add_i32 s1, s0, s1
	s_ashr_i32 s28, s1, 5
	s_and_b32 s1, s1, 0xffe0
	s_sub_i32 s0, s0, s1
	s_bfe_i32 s1, s0, 0x80000
	s_bfe_u32 s1, s1, 0x3000c
	s_add_i32 s1, s0, s1
	s_bfe_i32 s29, s1, 0x80000
	s_and_b32 s1, s1, 0xf8
	s_sub_i32 s0, s0, s1
	s_lshl_b32 s28, s28, 3
	s_sext_i32_i8 s0, s0
	s_add_i32 s0, s28, s0
	s_ashr_i32 s1, s0, 31
	s_ashr_i32 s28, s0, 5
	s_lshl_b64 s[0:1], s[0:1], 18
	s_add_u32 s0, s0, s4
	s_addc_u32 s1, s1, s5
	s_lshl_b64 s[0:1], s[0:1], 1
	s_sext_i32_i16 s29, s29
	s_add_u32 s36, s26, s0
	s_addc_u32 s37, s27, s1
	s_lshl_b32 s29, s29, 5
	s_and_b32 s30, s29, 0xffffff00
	s_ashr_i32 s31, s30, 31
	s_lshl_b64 s[30:31], s[30:31], 1
	s_add_u32 s38, s36, s30
	s_addc_u32 s39, s37, s31
	s_ashr_i32 s29, s28, 31
	s_lshl_b64 s[28:29], s[28:29], 20
	s_add_u32 s28, s50, s28
	s_addc_u32 s29, s51, s29
	s_add_u32 s36, s28, s30
	s_addc_u32 s37, s29, s31
	s_add_u32 s0, s44, s0
	s_addc_u32 s1, s45, s1
	s_add_u32 s30, s0, s30
	v_mov_b32_e32 v6, v212
	s_addc_u32 s31, s1, s31
	s_mov_b32 s1, 0xfffff8
	v_bfe_u32 v1, v6, 2, 3
	v_lshrrev_b32_e32 v2, 4, v6
	v_and_or_b32 v2, v2, s1, v1
	v_lshrrev_b32_e32 v8, 3, v6
	v_lshrrev_b32_e32 v3, 2, v2
	v_and_b32_e32 v0, 12, v8
	v_xor_b32_e32 v3, v3, v6
	v_lshlrev_b32_e32 v7, 4, v6
	v_and_or_b32 v3, v3, 3, v0
	v_lshlrev_b32_e32 v2, 12, v2
	v_lshl_or_b32 v160, v3, 4, v2
	v_add_u32_e32 v2, 0x2000, v7
	v_readfirstlane_b32 s0, v6
	v_lshrrev_b32_e32 v2, 8, v2
	v_and_or_b32 v1, v2, s1, v1
	s_lshl_b32 s0, s0, 4
	v_lshrrev_b32_e32 v2, 2, v1
	s_and_b32 s82, s0, 0xfffffc00
	v_xor_b32_e32 v2, v2, v6
	s_add_i32 s78, s82, 0
	v_and_or_b32 v0, v2, 3, v0
	v_lshlrev_b32_e32 v1, 12, v1
	s_mov_b32 m0, s78
	v_lshl_or_b32 v162, v0, 4, v1
	s_barrier
	v_lshl_add_u64 v[0:1], s[36:37], 0, v[160:161]
	global_load_lds_dwordx4 v160, s[36:37]
	s_add_i32 m0, s78, 0x2000
	s_mov_b64 s[0:1], 0x100
	global_load_lds_dwordx4 v162, s[36:37]
	s_add_i32 m0, s78, 0x4000
	v_lshl_add_u64 v[4:5], v[0:1], 0, s[0:1]
	v_mov_b32_e32 v163, v161
	global_load_lds_dwordx4 v[4:5], off
	s_add_i32 m0, s78, 0x6000
	v_lshl_add_u64 v[2:3], s[36:37], 0, v[162:163]
	s_add_u32 s28, s36, 0x40000
	v_lshl_add_u64 v[4:5], v[2:3], 0, s[0:1]
	s_addc_u32 s29, s37, 0
	s_add_i32 s67, s78, 0x8000
	global_load_lds_dwordx4 v[4:5], off
	s_mov_b32 m0, s67
	s_add_i32 s0, s78, 0xa000
	global_load_lds_dwordx4 v160, s[28:29]
	s_mov_b32 m0, s0
	v_bfe_u32 v163, v6, 5, 1
	global_load_lds_dwordx4 v162, s[28:29]
	s_add_u32 s28, s36, 0x40100
	s_addc_u32 s29, s37, 0
	s_add_i32 s1, s78, 0xc000
	s_add_i32 vcc_lo, s78, 0xe000
	s_mov_b32 m0, s1
	s_add_u32 s68, s36, 0x80000
	global_load_lds_dwordx4 v160, s[28:29]
	s_mov_b32 m0, vcc_lo
	s_addc_u32 s69, s37, 0
	s_add_i32 vcc_hi, s78, 0x10000
	global_load_lds_dwordx4 v162, s[28:29]
	s_mov_b32 m0, vcc_hi
	s_add_i32 s28, s78, 0x12000
	global_load_lds_dwordx4 v160, s[68:69]
	s_mov_b32 m0, s28
	s_add_u32 s76, s36, 0x80100
	global_load_lds_dwordx4 v162, s[68:69]
	s_addc_u32 s77, s37, 0
	s_add_i32 s29, s78, 0x14000
	s_add_i32 s68, s78, 0x16000
	s_mov_b32 m0, s29
	s_add_u32 s80, s36, 0xc0000
	global_load_lds_dwordx4 v160, s[76:77]
	s_mov_b32 m0, s68
	s_addc_u32 s81, s37, 0
	s_add_i32 s69, s78, 0x18000
	global_load_lds_dwordx4 v162, s[76:77]
	s_mov_b32 m0, s69
	s_add_i32 s76, s78, 0x1a000
	global_load_lds_dwordx4 v160, s[80:81]
	s_mov_b32 m0, s76
	v_and_b32_e32 v132, 0xc0, v7
	global_load_lds_dwordx4 v162, s[80:81]
	s_add_u32 s80, s36, 0xc0100
	s_addc_u32 s81, s37, 0
	s_add_i32 s77, s78, 0x1c000
	s_mov_b32 m0, s77
	s_add_i32 s78, s78, 0x1e000
	global_load_lds_dwordx4 v160, s[80:81]
	s_mov_b32 m0, s78
	s_add_i32 s79, s14, s82
	global_load_lds_dwordx4 v162, s[80:81]
	s_mov_b64 s[80:81], 0x800
	v_lshl_add_u64 v[4:5], v[0:1], 0, s[80:81]
	s_mov_b32 m0, s79
	v_or_b32_e32 v7, 2, v163
	global_load_lds_dwordx4 v[4:5], off
	s_add_i32 m0, s79, 0x2000
	v_lshl_add_u64 v[4:5], v[2:3], 0, s[80:81]
	s_mov_b64 s[80:81], 0x900
	global_load_lds_dwordx4 v[4:5], off
	s_add_i32 m0, s79, 0x4000
	v_lshl_add_u64 v[0:1], v[0:1], 0, s[80:81]
	global_load_lds_dwordx4 v[0:1], off
	s_add_i32 m0, s79, 0x6000
	v_lshl_add_u64 v[0:1], v[2:3], 0, s[80:81]
	global_load_lds_dwordx4 v[0:1], off
	v_lshlrev_b32_e32 v1, 6, v6
	v_and_b32_e32 v5, 0x1c0, v1
	v_and_b32_e32 v1, 2, v8
	v_bfe_u32 v2, v6, 1, 1
	v_bitop3_b32 v3, v1, v163, v2 bitop3:0x36
	v_bitop3_b32 v1, v1, v7, v2 bitop3:0x36
	s_waitcnt vmcnt(0)
	v_lshlrev_b32_e32 v165, 4, v1
	v_lshlrev_b32_e32 v1, 11, v6
	v_lshlrev_b32_e32 v0, 8, v6
	v_and_b32_e32 v164, 0xf800, v1
	v_lshrrev_b32_e32 v4, 5, v6
	v_lshlrev_b32_e32 v169, 3, v6
	v_bfe_u32 v130, v6, 2, 2
	v_and_b32_e32 v6, 0x1800, v0
	v_lshlrev_b32_e32 v166, 4, v3
	v_lshl_or_b32 v128, v163, 4, v164
	s_waitcnt vmcnt(0) lgkmcnt(0)
	s_barrier
; #define LDSP(T, p) ((__attribute__((address_space(3))) T*)(p))
; #define MFMA32(a, b, c) __builtin_amdgcn_mfma_f32_32x32x16_bf16((a), (b), (c), 0, 0, 0)
; DI void xattn_unit(const bf16_t* __restrict__ Qg, const bf16_t* __restrict__ Kg, const bf16_t* __restrict__ Vg, bf16_t* __restrict__ Og, lds_t* shm) {
;     ...
; #pragma unroll
;   for (int ss = 0; ss < 16; ++ss) {
;     const int cgl = 2 * ss, img = cgl >> 4;
;     const bf16x8 qv = gld<bf16x8>(Qg + 16 * ss, qoff);
; #pragma unroll
;     for (int t = 0; t < 4; ++t)
; #pragma unroll
;       for (int kb = 0; kb < 2; ++kb) {
;         const bf16x8 kf = *LDSP(const bf16x8, shm + t * 32768 + img * 16384 + kb * 8192 + 512 * ((cgl & 15) >> 2) + ((cgl & 2) ? ka2 : ka0));
;         S[t][kb] = MFMA32(kf, qv, S[t][kb]);
;       }
;   }
	global_load_dwordx4 v[172:175], v128, s[38:39]
	global_load_dwordx4 v[176:179], v128, s[38:39] offset:32
	global_load_dwordx4 v[180:183], v128, s[38:39] offset:64
	global_load_dwordx4 v[184:187], v128, s[38:39] offset:96
	global_load_dwordx4 v[188:191], v128, s[38:39] offset:128
	global_load_dwordx4 v[192:195], v128, s[38:39] offset:160
	global_load_dwordx4 v[196:199], v128, s[38:39] offset:192
	global_load_dwordx4 v[200:203], v128, s[38:39] offset:224
	global_load_dwordx4 v[204:207], v128, s[38:39] offset:256
	global_load_dwordx4 v[208:211], v128, s[38:39] offset:288
	global_load_dwordx4 v[216:219], v128, s[38:39] offset:320
	global_load_dwordx4 v[220:223], v128, s[38:39] offset:352
	global_load_dwordx4 v[224:227], v128, s[38:39] offset:384
	global_load_dwordx4 v[228:231], v128, s[38:39] offset:416
	global_load_dwordx4 v[232:235], v128, s[38:39] offset:448
	global_load_dwordx4 v[236:239], v128, s[38:39] offset:480
	v_bitop3_b32 v4, v4, v130, 1 bitop3:0x6c
	v_add3_u32 v131, 0, v6, v5
	v_lshl_add_u32 v129, v4, 4, v131
	v_bitop3_b32 v130, v163, v130, 2 bitop3:0x36
	v_lshl_add_u32 v133, v130, 4, v131
	v_lshl_or_b32 v170, v163, 8, v132
	v_add_u32_e32 v248, 0x10000, v129
	v_add_u32_e32 v249, 0x10000, v133
	ds_read_b128 v[144:147], v129
	ds_read_b128 v[148:151], v129 offset:8192
	ds_read_b128 v[152:155], v129 offset:32768
	ds_read_b128 v[156:159], v129 offset:40960
	s_waitcnt vmcnt(15) lgkmcnt(3)
	v_mfma_f32_32x32x16_bf16 v[112:127], v[144:147], v[172:175], 0
	ds_read_b128 v[144:147], v248
	s_waitcnt lgkmcnt(3)
	v_mfma_f32_32x32x16_bf16 v[96:111], v[148:151], v[172:175], 0
	ds_read_b128 v[148:151], v248 offset:8192
	s_waitcnt lgkmcnt(3)
	v_mfma_f32_32x32x16_bf16 v[80:95], v[152:155], v[172:175], 0
	ds_read_b128 v[152:155], v248 offset:32768
	s_waitcnt lgkmcnt(3)
	v_mfma_f32_32x32x16_bf16 v[64:79], v[156:159], v[172:175], 0
	ds_read_b128 v[156:159], v248 offset:40960
	s_waitcnt lgkmcnt(3)
	v_mfma_f32_32x32x16_bf16 v[48:63], v[144:147], v[172:175], 0
	ds_read_b128 v[144:147], v133
	s_waitcnt lgkmcnt(3)
	v_mfma_f32_32x32x16_bf16 v[32:47], v[148:151], v[172:175], 0
	ds_read_b128 v[148:151], v133 offset:8192
	s_waitcnt lgkmcnt(3)
	v_mfma_f32_32x32x16_bf16 v[16:31], v[152:155], v[172:175], 0
	ds_read_b128 v[152:155], v133 offset:32768
	s_waitcnt lgkmcnt(3)
	v_mfma_f32_32x32x16_bf16 v[0:15], v[156:159], v[172:175], 0
	ds_read_b128 v[156:159], v133 offset:40960
	s_waitcnt vmcnt(14) lgkmcnt(3)
	v_mfma_f32_32x32x16_bf16 v[112:127], v[144:147], v[176:179], v[112:127]
	ds_read_b128 v[144:147], v249
	s_waitcnt lgkmcnt(3)
	v_mfma_f32_32x32x16_bf16 v[96:111], v[148:151], v[176:179], v[96:111]
	ds_read_b128 v[148:151], v249 offset:8192
	s_waitcnt lgkmcnt(3)
	v_mfma_f32_32x32x16_bf16 v[80:95], v[152:155], v[176:179], v[80:95]
	ds_read_b128 v[152:155], v249 offset:32768
	s_waitcnt lgkmcnt(3)
	v_mfma_f32_32x32x16_bf16 v[64:79], v[156:159], v[176:179], v[64:79]
	ds_read_b128 v[156:159], v249 offset:40960
	s_waitcnt lgkmcnt(3)
	v_mfma_f32_32x32x16_bf16 v[48:63], v[144:147], v[176:179], v[48:63]
	ds_read_b128 v[144:147], v129 offset:512
	s_waitcnt lgkmcnt(3)
	v_mfma_f32_32x32x16_bf16 v[32:47], v[148:151], v[176:179], v[32:47]
	ds_read_b128 v[148:151], v129 offset:8704
	s_waitcnt lgkmcnt(3)
	v_mfma_f32_32x32x16_bf16 v[16:31], v[152:155], v[176:179], v[16:31]
	ds_read_b128 v[152:155], v129 offset:33280
	s_waitcnt lgkmcnt(3)
	v_mfma_f32_32x32x16_bf16 v[0:15], v[156:159], v[176:179], v[0:15]
	ds_read_b128 v[156:159], v129 offset:41472
	s_waitcnt vmcnt(13) lgkmcnt(3)
	v_mfma_f32_32x32x16_bf16 v[112:127], v[144:147], v[180:183], v[112:127]
	ds_read_b128 v[144:147], v248 offset:512
	s_waitcnt lgkmcnt(3)
	v_mfma_f32_32x32x16_bf16 v[96:111], v[148:151], v[180:183], v[96:111]
	ds_read_b128 v[148:151], v248 offset:8704
	s_waitcnt lgkmcnt(3)
	v_mfma_f32_32x32x16_bf16 v[80:95], v[152:155], v[180:183], v[80:95]
	ds_read_b128 v[152:155], v248 offset:33280
	s_waitcnt lgkmcnt(3)
	v_mfma_f32_32x32x16_bf16 v[64:79], v[156:159], v[180:183], v[64:79]
	ds_read_b128 v[156:159], v248 offset:41472
	s_waitcnt lgkmcnt(3)
	v_mfma_f32_32x32x16_bf16 v[48:63], v[144:147], v[180:183], v[48:63]
	ds_read_b128 v[144:147], v133 offset:512
	s_waitcnt lgkmcnt(3)
	v_mfma_f32_32x32x16_bf16 v[32:47], v[148:151], v[180:183], v[32:47]
	ds_read_b128 v[148:151], v133 offset:8704
	s_waitcnt lgkmcnt(3)
	v_mfma_f32_32x32x16_bf16 v[16:31], v[152:155], v[180:183], v[16:31]
	ds_read_b128 v[152:155], v133 offset:33280
	s_waitcnt lgkmcnt(3)
	v_mfma_f32_32x32x16_bf16 v[0:15], v[156:159], v[180:183], v[0:15]
	ds_read_b128 v[156:159], v133 offset:41472
	s_waitcnt vmcnt(12) lgkmcnt(3)
	v_mfma_f32_32x32x16_bf16 v[112:127], v[144:147], v[184:187], v[112:127]
	ds_read_b128 v[144:147], v249 offset:512
	s_waitcnt lgkmcnt(3)
	v_mfma_f32_32x32x16_bf16 v[96:111], v[148:151], v[184:187], v[96:111]
	ds_read_b128 v[148:151], v249 offset:8704
	s_waitcnt lgkmcnt(3)
	v_mfma_f32_32x32x16_bf16 v[80:95], v[152:155], v[184:187], v[80:95]
	ds_read_b128 v[152:155], v249 offset:33280
	s_waitcnt lgkmcnt(3)
	v_mfma_f32_32x32x16_bf16 v[64:79], v[156:159], v[184:187], v[64:79]
	ds_read_b128 v[156:159], v249 offset:41472
	s_waitcnt lgkmcnt(3)
	v_mfma_f32_32x32x16_bf16 v[48:63], v[144:147], v[184:187], v[48:63]
	ds_read_b128 v[144:147], v129 offset:1024
	s_waitcnt lgkmcnt(3)
	v_mfma_f32_32x32x16_bf16 v[32:47], v[148:151], v[184:187], v[32:47]
	ds_read_b128 v[148:151], v129 offset:9216
	s_waitcnt lgkmcnt(3)
	v_mfma_f32_32x32x16_bf16 v[16:31], v[152:155], v[184:187], v[16:31]
	ds_read_b128 v[152:155], v129 offset:33792
	s_waitcnt lgkmcnt(3)
	v_mfma_f32_32x32x16_bf16 v[0:15], v[156:159], v[184:187], v[0:15]
	ds_read_b128 v[156:159], v129 offset:41984
	s_waitcnt vmcnt(11) lgkmcnt(3)
; #define LDSP(T, p) ((__attribute__((address_space(3))) T*)(p))
; #define MFMA32(a, b, c) __builtin_amdgcn_mfma_f32_32x32x16_bf16((a), (b), (c), 0, 0, 0)
; DI void xattn_unit(const bf16_t* __restrict__ Qg, const bf16_t* __restrict__ Kg, const bf16_t* __restrict__ Vg, bf16_t* __restrict__ Og, lds_t* shm) {
;     ...
; #pragma unroll
;   for (int ss = 0; ss < 16; ++ss) {
;     const int cgl = 2 * ss, img = cgl >> 4;
;     const bf16x8 qv = gld<bf16x8>(Qg + 16 * ss, qoff);
; #pragma unroll
;     for (int t = 0; t < 4; ++t)
; #pragma unroll
;       for (int kb = 0; kb < 2; ++kb) {
;         const bf16x8 kf = *LDSP(const bf16x8, shm + t * 32768 + img * 16384 + kb * 8192 + 512 * ((cgl & 15) >> 2) + ((cgl & 2) ? ka2 : ka0));
;         S[t][kb] = MFMA32(kf, qv, S[t][kb]);
;       }
;   }
	v_mfma_f32_32x32x16_bf16 v[112:127], v[144:147], v[188:191], v[112:127]
	ds_read_b128 v[144:147], v248 offset:1024
	s_waitcnt lgkmcnt(3)
	v_mfma_f32_32x32x16_bf16 v[96:111], v[148:151], v[188:191], v[96:111]
	ds_read_b128 v[148:151], v248 offset:9216
	s_waitcnt lgkmcnt(3)
	v_mfma_f32_32x32x16_bf16 v[80:95], v[152:155], v[188:191], v[80:95]
	ds_read_b128 v[152:155], v248 offset:33792
	s_waitcnt lgkmcnt(3)
	v_mfma_f32_32x32x16_bf16 v[64:79], v[156:159], v[188:191], v[64:79]
	ds_read_b128 v[156:159], v248 offset:41984
	s_waitcnt lgkmcnt(3)
	v_mfma_f32_32x32x16_bf16 v[48:63], v[144:147], v[188:191], v[48:63]
	ds_read_b128 v[144:147], v133 offset:1024
	s_waitcnt lgkmcnt(3)
	v_mfma_f32_32x32x16_bf16 v[32:47], v[148:151], v[188:191], v[32:47]
	ds_read_b128 v[148:151], v133 offset:9216
	s_waitcnt lgkmcnt(3)
	v_mfma_f32_32x32x16_bf16 v[16:31], v[152:155], v[188:191], v[16:31]
	ds_read_b128 v[152:155], v133 offset:33792
	s_waitcnt lgkmcnt(3)
	v_mfma_f32_32x32x16_bf16 v[0:15], v[156:159], v[188:191], v[0:15]
	ds_read_b128 v[156:159], v133 offset:41984
	s_waitcnt vmcnt(10) lgkmcnt(3)
	v_mfma_f32_32x32x16_bf16 v[112:127], v[144:147], v[192:195], v[112:127]
	ds_read_b128 v[144:147], v249 offset:1024
	s_waitcnt lgkmcnt(3)
	v_mfma_f32_32x32x16_bf16 v[96:111], v[148:151], v[192:195], v[96:111]
	ds_read_b128 v[148:151], v249 offset:9216
	s_waitcnt lgkmcnt(3)
	v_mfma_f32_32x32x16_bf16 v[80:95], v[152:155], v[192:195], v[80:95]
	ds_read_b128 v[152:155], v249 offset:33792
	s_waitcnt lgkmcnt(3)
	v_mfma_f32_32x32x16_bf16 v[64:79], v[156:159], v[192:195], v[64:79]
	ds_read_b128 v[156:159], v249 offset:41984
	s_waitcnt lgkmcnt(3)
	v_mfma_f32_32x32x16_bf16 v[48:63], v[144:147], v[192:195], v[48:63]
	ds_read_b128 v[144:147], v129 offset:1536
	s_waitcnt lgkmcnt(3)
	v_mfma_f32_32x32x16_bf16 v[32:47], v[148:151], v[192:195], v[32:47]
	ds_read_b128 v[148:151], v129 offset:9728
	s_waitcnt lgkmcnt(3)
	v_mfma_f32_32x32x16_bf16 v[16:31], v[152:155], v[192:195], v[16:31]
	ds_read_b128 v[152:155], v129 offset:34304
	s_waitcnt lgkmcnt(3)
	v_mfma_f32_32x32x16_bf16 v[0:15], v[156:159], v[192:195], v[0:15]
	ds_read_b128 v[156:159], v129 offset:42496
	s_waitcnt vmcnt(9) lgkmcnt(3)
	v_mfma_f32_32x32x16_bf16 v[112:127], v[144:147], v[196:199], v[112:127]
	ds_read_b128 v[144:147], v248 offset:1536
	s_waitcnt lgkmcnt(3)
	v_mfma_f32_32x32x16_bf16 v[96:111], v[148:151], v[196:199], v[96:111]
	ds_read_b128 v[148:151], v248 offset:9728
	s_waitcnt lgkmcnt(3)
	v_mfma_f32_32x32x16_bf16 v[80:95], v[152:155], v[196:199], v[80:95]
	ds_read_b128 v[152:155], v248 offset:34304
	s_waitcnt lgkmcnt(3)
	v_mfma_f32_32x32x16_bf16 v[64:79], v[156:159], v[196:199], v[64:79]
	ds_read_b128 v[156:159], v248 offset:42496
	s_waitcnt lgkmcnt(3)
	v_mfma_f32_32x32x16_bf16 v[48:63], v[144:147], v[196:199], v[48:63]
	ds_read_b128 v[144:147], v133 offset:1536
	s_waitcnt lgkmcnt(3)
	v_mfma_f32_32x32x16_bf16 v[32:47], v[148:151], v[196:199], v[32:47]
	ds_read_b128 v[148:151], v133 offset:9728
	s_waitcnt lgkmcnt(3)
	v_mfma_f32_32x32x16_bf16 v[16:31], v[152:155], v[196:199], v[16:31]
	ds_read_b128 v[152:155], v133 offset:34304
	s_waitcnt lgkmcnt(3)
	v_mfma_f32_32x32x16_bf16 v[0:15], v[156:159], v[196:199], v[0:15]
	ds_read_b128 v[156:159], v133 offset:42496
	s_waitcnt vmcnt(8) lgkmcnt(3)
	v_mfma_f32_32x32x16_bf16 v[112:127], v[144:147], v[200:203], v[112:127]
	ds_read_b128 v[144:147], v249 offset:1536
	s_waitcnt lgkmcnt(3)
	v_mfma_f32_32x32x16_bf16 v[96:111], v[148:151], v[200:203], v[96:111]
	ds_read_b128 v[148:151], v249 offset:9728
	s_waitcnt lgkmcnt(3)
	v_mfma_f32_32x32x16_bf16 v[80:95], v[152:155], v[200:203], v[80:95]
	ds_read_b128 v[152:155], v249 offset:34304
	s_waitcnt lgkmcnt(3)
	v_mfma_f32_32x32x16_bf16 v[64:79], v[156:159], v[200:203], v[64:79]
	ds_read_b128 v[156:159], v249 offset:42496
	s_waitcnt lgkmcnt(3)
	v_mfma_f32_32x32x16_bf16 v[48:63], v[144:147], v[200:203], v[48:63]
	ds_read_b128 v[144:147], v129 offset:16384
	s_waitcnt lgkmcnt(3)
	v_mfma_f32_32x32x16_bf16 v[32:47], v[148:151], v[200:203], v[32:47]
	ds_read_b128 v[148:151], v129 offset:24576
	s_waitcnt lgkmcnt(3)
	v_mfma_f32_32x32x16_bf16 v[16:31], v[152:155], v[200:203], v[16:31]
	ds_read_b128 v[152:155], v129 offset:49152
	s_waitcnt lgkmcnt(3)
	v_mfma_f32_32x32x16_bf16 v[0:15], v[156:159], v[200:203], v[0:15]
	ds_read_b128 v[156:159], v129 offset:57344
	s_waitcnt vmcnt(7) lgkmcnt(3)
	v_mfma_f32_32x32x16_bf16 v[112:127], v[144:147], v[204:207], v[112:127]
	ds_read_b128 v[144:147], v248 offset:16384
	s_waitcnt lgkmcnt(3)
	v_mfma_f32_32x32x16_bf16 v[96:111], v[148:151], v[204:207], v[96:111]
	ds_read_b128 v[148:151], v248 offset:24576
	s_waitcnt lgkmcnt(3)
	v_mfma_f32_32x32x16_bf16 v[80:95], v[152:155], v[204:207], v[80:95]
	ds_read_b128 v[152:155], v248 offset:49152
	s_waitcnt lgkmcnt(3)
	v_mfma_f32_32x32x16_bf16 v[64:79], v[156:159], v[204:207], v[64:79]
	ds_read_b128 v[156:159], v248 offset:57344
	s_waitcnt lgkmcnt(3)
	v_mfma_f32_32x32x16_bf16 v[48:63], v[144:147], v[204:207], v[48:63]
	ds_read_b128 v[144:147], v133 offset:16384
	s_waitcnt lgkmcnt(3)
	v_mfma_f32_32x32x16_bf16 v[32:47], v[148:151], v[204:207], v[32:47]
	ds_read_b128 v[148:151], v133 offset:24576
	s_waitcnt lgkmcnt(3)
	v_mfma_f32_32x32x16_bf16 v[16:31], v[152:155], v[204:207], v[16:31]
	ds_read_b128 v[152:155], v133 offset:49152
	s_waitcnt lgkmcnt(3)
	v_mfma_f32_32x32x16_bf16 v[0:15], v[156:159], v[204:207], v[0:15]
	ds_read_b128 v[156:159], v133 offset:57344
	s_waitcnt vmcnt(6) lgkmcnt(3)
	v_mfma_f32_32x32x16_bf16 v[112:127], v[144:147], v[208:211], v[112:127]
	ds_read_b128 v[144:147], v249 offset:16384
	s_waitcnt lgkmcnt(3)
; #define LDSP(T, p) ((__attribute__((address_space(3))) T*)(p))
; #define MFMA32(a, b, c) __builtin_amdgcn_mfma_f32_32x32x16_bf16((a), (b), (c), 0, 0, 0)
; DI void xattn_unit(const bf16_t* __restrict__ Qg, const bf16_t* __restrict__ Kg, const bf16_t* __restrict__ Vg, bf16_t* __restrict__ Og, lds_t* shm) {
;     ...
; #pragma unroll
;   for (int ss = 0; ss < 16; ++ss) {
;     const int cgl = 2 * ss, img = cgl >> 4;
;     const bf16x8 qv = gld<bf16x8>(Qg + 16 * ss, qoff);
; #pragma unroll
;     for (int t = 0; t < 4; ++t)
; #pragma unroll
;       for (int kb = 0; kb < 2; ++kb) {
;         const bf16x8 kf = *LDSP(const bf16x8, shm + t * 32768 + img * 16384 + kb * 8192 + 512 * ((cgl & 15) >> 2) + ((cgl & 2) ? ka2 : ka0));
;         S[t][kb] = MFMA32(kf, qv, S[t][kb]);
;       }
;   }
	v_mfma_f32_32x32x16_bf16 v[96:111], v[148:151], v[208:211], v[96:111]
	ds_read_b128 v[148:151], v249 offset:24576
	s_waitcnt lgkmcnt(3)
	v_mfma_f32_32x32x16_bf16 v[80:95], v[152:155], v[208:211], v[80:95]
	ds_read_b128 v[152:155], v249 offset:49152
	s_waitcnt lgkmcnt(3)
	v_mfma_f32_32x32x16_bf16 v[64:79], v[156:159], v[208:211], v[64:79]
	ds_read_b128 v[156:159], v249 offset:57344
	s_waitcnt lgkmcnt(3)
	v_mfma_f32_32x32x16_bf16 v[48:63], v[144:147], v[208:211], v[48:63]
	ds_read_b128 v[144:147], v129 offset:16896
	s_waitcnt lgkmcnt(3)
	v_mfma_f32_32x32x16_bf16 v[32:47], v[148:151], v[208:211], v[32:47]
	ds_read_b128 v[148:151], v129 offset:25088
	s_waitcnt lgkmcnt(3)
	v_mfma_f32_32x32x16_bf16 v[16:31], v[152:155], v[208:211], v[16:31]
	ds_read_b128 v[152:155], v129 offset:49664
	s_waitcnt lgkmcnt(3)
	v_mfma_f32_32x32x16_bf16 v[0:15], v[156:159], v[208:211], v[0:15]
	ds_read_b128 v[156:159], v129 offset:57856
	s_waitcnt vmcnt(5) lgkmcnt(3)
	v_mfma_f32_32x32x16_bf16 v[112:127], v[144:147], v[216:219], v[112:127]
	ds_read_b128 v[144:147], v248 offset:16896
	s_waitcnt lgkmcnt(3)
	v_mfma_f32_32x32x16_bf16 v[96:111], v[148:151], v[216:219], v[96:111]
	ds_read_b128 v[148:151], v248 offset:25088
	s_waitcnt lgkmcnt(3)
	v_mfma_f32_32x32x16_bf16 v[80:95], v[152:155], v[216:219], v[80:95]
	ds_read_b128 v[152:155], v248 offset:49664
	s_waitcnt lgkmcnt(3)
	v_mfma_f32_32x32x16_bf16 v[64:79], v[156:159], v[216:219], v[64:79]
	ds_read_b128 v[156:159], v248 offset:57856
	s_waitcnt lgkmcnt(3)
	v_mfma_f32_32x32x16_bf16 v[48:63], v[144:147], v[216:219], v[48:63]
	ds_read_b128 v[144:147], v133 offset:16896
	s_waitcnt lgkmcnt(3)
	v_mfma_f32_32x32x16_bf16 v[32:47], v[148:151], v[216:219], v[32:47]
	ds_read_b128 v[148:151], v133 offset:25088
	s_waitcnt lgkmcnt(3)
	v_mfma_f32_32x32x16_bf16 v[16:31], v[152:155], v[216:219], v[16:31]
	ds_read_b128 v[152:155], v133 offset:49664
	s_waitcnt lgkmcnt(3)
	v_mfma_f32_32x32x16_bf16 v[0:15], v[156:159], v[216:219], v[0:15]
	ds_read_b128 v[156:159], v133 offset:57856
	s_waitcnt vmcnt(4) lgkmcnt(3)
	v_mfma_f32_32x32x16_bf16 v[112:127], v[144:147], v[220:223], v[112:127]
	ds_read_b128 v[144:147], v249 offset:16896
	s_waitcnt lgkmcnt(3)
	v_mfma_f32_32x32x16_bf16 v[96:111], v[148:151], v[220:223], v[96:111]
	ds_read_b128 v[148:151], v249 offset:25088
	s_waitcnt lgkmcnt(3)
	v_mfma_f32_32x32x16_bf16 v[80:95], v[152:155], v[220:223], v[80:95]
	ds_read_b128 v[152:155], v249 offset:49664
	s_waitcnt lgkmcnt(3)
	v_mfma_f32_32x32x16_bf16 v[64:79], v[156:159], v[220:223], v[64:79]
	ds_read_b128 v[156:159], v249 offset:57856
	s_waitcnt lgkmcnt(3)
	v_mfma_f32_32x32x16_bf16 v[48:63], v[144:147], v[220:223], v[48:63]
	ds_read_b128 v[144:147], v129 offset:17408
	s_waitcnt lgkmcnt(3)
	v_mfma_f32_32x32x16_bf16 v[32:47], v[148:151], v[220:223], v[32:47]
	ds_read_b128 v[148:151], v129 offset:25600
	s_waitcnt lgkmcnt(3)
	v_mfma_f32_32x32x16_bf16 v[16:31], v[152:155], v[220:223], v[16:31]
	ds_read_b128 v[152:155], v129 offset:50176
	s_waitcnt lgkmcnt(3)
	v_mfma_f32_32x32x16_bf16 v[0:15], v[156:159], v[220:223], v[0:15]
	ds_read_b128 v[156:159], v129 offset:58368
	s_waitcnt vmcnt(3) lgkmcnt(3)
	v_mfma_f32_32x32x16_bf16 v[112:127], v[144:147], v[224:227], v[112:127]
	ds_read_b128 v[144:147], v248 offset:17408
	s_waitcnt lgkmcnt(3)
	v_mfma_f32_32x32x16_bf16 v[96:111], v[148:151], v[224:227], v[96:111]
	ds_read_b128 v[148:151], v248 offset:25600
	s_waitcnt lgkmcnt(3)
	v_mfma_f32_32x32x16_bf16 v[80:95], v[152:155], v[224:227], v[80:95]
	ds_read_b128 v[152:155], v248 offset:50176
	s_waitcnt lgkmcnt(3)
	v_mfma_f32_32x32x16_bf16 v[64:79], v[156:159], v[224:227], v[64:79]
	ds_read_b128 v[156:159], v248 offset:58368
	s_waitcnt lgkmcnt(3)
	v_mfma_f32_32x32x16_bf16 v[48:63], v[144:147], v[224:227], v[48:63]
	ds_read_b128 v[144:147], v133 offset:17408
	s_waitcnt lgkmcnt(3)
	v_mfma_f32_32x32x16_bf16 v[32:47], v[148:151], v[224:227], v[32:47]
	ds_read_b128 v[148:151], v133 offset:25600
	s_waitcnt lgkmcnt(3)
	v_mfma_f32_32x32x16_bf16 v[16:31], v[152:155], v[224:227], v[16:31]
	ds_read_b128 v[152:155], v133 offset:50176
	s_waitcnt lgkmcnt(3)
	v_mfma_f32_32x32x16_bf16 v[0:15], v[156:159], v[224:227], v[0:15]
	ds_read_b128 v[156:159], v133 offset:58368
	s_waitcnt vmcnt(2) lgkmcnt(3)
	v_mfma_f32_32x32x16_bf16 v[112:127], v[144:147], v[228:231], v[112:127]
	ds_read_b128 v[144:147], v249 offset:17408
	s_waitcnt lgkmcnt(3)
	v_mfma_f32_32x32x16_bf16 v[96:111], v[148:151], v[228:231], v[96:111]
	ds_read_b128 v[148:151], v249 offset:25600
	s_waitcnt lgkmcnt(3)
	v_mfma_f32_32x32x16_bf16 v[80:95], v[152:155], v[228:231], v[80:95]
	ds_read_b128 v[152:155], v249 offset:50176
	s_waitcnt lgkmcnt(3)
	v_mfma_f32_32x32x16_bf16 v[64:79], v[156:159], v[228:231], v[64:79]
	ds_read_b128 v[156:159], v249 offset:58368
	s_waitcnt lgkmcnt(3)
	v_mfma_f32_32x32x16_bf16 v[48:63], v[144:147], v[228:231], v[48:63]
	ds_read_b128 v[144:147], v129 offset:17920
	s_waitcnt lgkmcnt(3)
	v_mfma_f32_32x32x16_bf16 v[32:47], v[148:151], v[228:231], v[32:47]
	ds_read_b128 v[148:151], v129 offset:26112
	s_waitcnt lgkmcnt(3)
	v_mfma_f32_32x32x16_bf16 v[16:31], v[152:155], v[228:231], v[16:31]
	ds_read_b128 v[152:155], v129 offset:50688
	s_waitcnt lgkmcnt(3)
	v_mfma_f32_32x32x16_bf16 v[0:15], v[156:159], v[228:231], v[0:15]
	ds_read_b128 v[156:159], v129 offset:58880
	s_waitcnt vmcnt(1) lgkmcnt(3)
	v_mfma_f32_32x32x16_bf16 v[112:127], v[144:147], v[232:235], v[112:127]
	ds_read_b128 v[144:147], v248 offset:17920
	s_waitcnt lgkmcnt(3)
	v_mfma_f32_32x32x16_bf16 v[96:111], v[148:151], v[232:235], v[96:111]
	ds_read_b128 v[148:151], v248 offset:26112
	s_waitcnt lgkmcnt(3)
; #define LDSP(T, p) ((__attribute__((address_space(3))) T*)(p))
; DI unsigned pk2(float lo, float hi) { bf2_t v = __builtin_convertvector((f32x2){lo, hi}, bf2_t); return __builtin_bit_cast(unsigned, v); }
; #define MFMA32(a, b, c) __builtin_amdgcn_mfma_f32_32x32x16_bf16((a), (b), (c), 0, 0, 0)
; DI void xattn_unit(const bf16_t* __restrict__ Qg, const bf16_t* __restrict__ Kg, const bf16_t* __restrict__ Vg, bf16_t* __restrict__ Og, lds_t* shm) {
;     ...
; #pragma unroll
;   for (int ss = 0; ss < 16; ++ss) {
;     const int cgl = 2 * ss, img = cgl >> 4;
;     const bf16x8 qv = gld<bf16x8>(Qg + 16 * ss, qoff);
; #pragma unroll
;     for (int t = 0; t < 4; ++t)
; #pragma unroll
;       for (int kb = 0; kb < 2; ++kb) {
;         const bf16x8 kf = *LDSP(const bf16x8, shm + t * 32768 + img * 16384 + kb * 8192 + 512 * ((cgl & 15) >> 2) + ((cgl & 2) ? ka2 : ka0));
;         S[t][kb] = MFMA32(kf, qv, S[t][kb]);
;       }
;   }
;   float mx = S[0][0][0];
; #pragma unroll
;   for (int t = 0; t < 4; ++t)
; #pragma unroll
;     for (int kb = 0; kb < 2; ++kb)
; #pragma unroll
;       for (int i = 0; i < 16; ++i) mx = fmaxf(mx, S[t][kb][i]);
;   { const auto sw = __builtin_amdgcn_permlane32_swap(__float_as_uint(mx), __float_as_uint(mx), false, false); mx = fmaxf(__uint_as_float(sw[0]), __uint_as_float(sw[1])); }
;   float rs = 0.f;
;   bf16x8 P[4][2][2];
; #pragma unroll
;   for (int t = 0; t < 4; ++t)
; #pragma unroll
;     for (int kb = 0; kb < 2; ++kb)
; #pragma unroll
;       for (int s2 = 0; s2 < 2; ++s2) {
;         float e[8];
; #pragma unroll
;         for (int j = 0; j < 8; ++j) { e[j] = __builtin_amdgcn_exp2f(S[t][kb][8 * s2 + j] - mx); rs += e[j]; }
;         u32x4 w; w.x = pk2(e[0], e[1]); w.y = pk2(e[2], e[3]); w.z = pk2(e[4], e[5]); w.w = pk2(e[6], e[7]);
;         P[t][kb][s2] = __builtin_bit_cast(bf16x8, w);
;       }
	v_mfma_f32_32x32x16_bf16 v[80:95], v[152:155], v[232:235], v[80:95]
	ds_read_b128 v[152:155], v248 offset:50688
	s_waitcnt lgkmcnt(3)
	v_mfma_f32_32x32x16_bf16 v[64:79], v[156:159], v[232:235], v[64:79]
	ds_read_b128 v[156:159], v248 offset:58880
	s_waitcnt lgkmcnt(3)
	v_mfma_f32_32x32x16_bf16 v[48:63], v[144:147], v[232:235], v[48:63]
	ds_read_b128 v[144:147], v133 offset:17920
	s_waitcnt lgkmcnt(3)
	v_mfma_f32_32x32x16_bf16 v[32:47], v[148:151], v[232:235], v[32:47]
	ds_read_b128 v[148:151], v133 offset:26112
	s_waitcnt lgkmcnt(3)
	v_mfma_f32_32x32x16_bf16 v[16:31], v[152:155], v[232:235], v[16:31]
	ds_read_b128 v[152:155], v133 offset:50688
	s_waitcnt lgkmcnt(3)
	v_mfma_f32_32x32x16_bf16 v[0:15], v[156:159], v[232:235], v[0:15]
	ds_read_b128 v[156:159], v133 offset:58880
	s_waitcnt vmcnt(0) lgkmcnt(3)
	v_mfma_f32_32x32x16_bf16 v[112:127], v[144:147], v[236:239], v[112:127]
	ds_read_b128 v[144:147], v249 offset:17920
	s_waitcnt lgkmcnt(3)
	v_mfma_f32_32x32x16_bf16 v[96:111], v[148:151], v[236:239], v[96:111]
	ds_read_b128 v[148:151], v249 offset:26112
	s_waitcnt lgkmcnt(3)
	v_mfma_f32_32x32x16_bf16 v[80:95], v[152:155], v[236:239], v[80:95]
	ds_read_b128 v[152:155], v249 offset:50688
	s_waitcnt lgkmcnt(3)
	v_mfma_f32_32x32x16_bf16 v[64:79], v[156:159], v[236:239], v[64:79]
	ds_read_b128 v[156:159], v249 offset:58880
	s_waitcnt lgkmcnt(3)
	v_mfma_f32_32x32x16_bf16 v[48:63], v[144:147], v[236:239], v[48:63]
	s_waitcnt lgkmcnt(2)
	v_mfma_f32_32x32x16_bf16 v[32:47], v[148:151], v[236:239], v[32:47]
	s_waitcnt lgkmcnt(1)
	v_mfma_f32_32x32x16_bf16 v[16:31], v[152:155], v[236:239], v[16:31]
	s_waitcnt lgkmcnt(0)
	v_mfma_f32_32x32x16_bf16 v[0:15], v[156:159], v[236:239], v[0:15]
	v_max_f32_e32 v128, v113, v113
	v_max_f32_e32 v129, v112, v112
	v_max_f32_e32 v128, v129, v128
	v_max3_f32 v128, v128, v114, v115
	v_max3_f32 v128, v128, v116, v117
	v_max3_f32 v128, v128, v118, v119
	v_max3_f32 v128, v128, v120, v121
	v_max3_f32 v128, v128, v122, v123
	v_max3_f32 v128, v128, v124, v125
	v_max3_f32 v128, v128, v126, v127
	v_max3_f32 v128, v128, v96, v97
	v_max3_f32 v128, v128, v98, v99
	v_max3_f32 v128, v128, v100, v101
	v_max3_f32 v128, v128, v102, v103
	v_max3_f32 v128, v128, v104, v105
	v_max3_f32 v128, v128, v106, v107
	v_max3_f32 v128, v128, v108, v109
	v_max3_f32 v128, v128, v110, v111
	v_max3_f32 v128, v128, v80, v81
	v_max3_f32 v128, v128, v82, v83
	v_max3_f32 v128, v128, v84, v85
	v_max3_f32 v128, v128, v86, v87
	v_max3_f32 v128, v128, v88, v89
	v_max3_f32 v128, v128, v90, v91
	v_max3_f32 v128, v128, v92, v93
	v_max3_f32 v128, v128, v94, v95
	v_max3_f32 v128, v128, v64, v65
	v_max3_f32 v128, v128, v66, v67
	v_max3_f32 v128, v128, v68, v69
	v_max3_f32 v128, v128, v70, v71
	v_max3_f32 v128, v128, v72, v73
	v_max3_f32 v128, v128, v74, v75
	v_max3_f32 v128, v128, v76, v77
	v_max3_f32 v128, v128, v78, v79
	v_max3_f32 v128, v128, v48, v49
	v_max3_f32 v128, v128, v50, v51
	v_max3_f32 v128, v128, v52, v53
	v_max3_f32 v128, v128, v54, v55
	v_max3_f32 v128, v128, v56, v57
	v_max3_f32 v128, v128, v58, v59
	v_max3_f32 v128, v128, v60, v61
	v_max3_f32 v128, v128, v62, v63
	v_max3_f32 v128, v128, v32, v33
	v_max3_f32 v128, v128, v34, v35
	v_max3_f32 v128, v128, v36, v37
	v_max3_f32 v128, v128, v38, v39
	v_max3_f32 v128, v128, v40, v41
	v_max3_f32 v128, v128, v42, v43
	v_max3_f32 v128, v128, v44, v45
	v_max3_f32 v128, v128, v46, v47
	v_max3_f32 v128, v128, v16, v17
	v_max3_f32 v128, v128, v18, v19
	v_max3_f32 v128, v128, v20, v21
	v_max3_f32 v128, v128, v22, v23
	v_max3_f32 v128, v128, v24, v25
	v_max3_f32 v128, v128, v26, v27
	v_max3_f32 v128, v128, v28, v29
	v_max3_f32 v128, v128, v30, v31
	v_max3_f32 v128, v128, v0, v1
	v_max3_f32 v128, v128, v2, v3
	v_max3_f32 v128, v128, v4, v5
	v_max3_f32 v128, v128, v6, v7
	v_max3_f32 v128, v128, v8, v9
	v_max3_f32 v128, v128, v10, v11
	v_max3_f32 v128, v128, v12, v13
	v_max3_f32 v128, v128, v14, v15
	v_mov_b32_e32 v129, v128
	s_nop 1
	v_permlane32_swap_b32_e32 v128, v129
	v_max_f32_e32 v129, v129, v129
	v_max_f32_e32 v128, v128, v128
	v_max_f32_e32 v167, v128, v129
	v_sub_f32_e32 v112, v112, v167
	v_exp_f32_e32 v112, v112
	v_sub_f32_e32 v113, v113, v167
	v_exp_f32_e32 v113, v113
	v_sub_f32_e32 v114, v114, v167
	v_exp_f32_e32 v114, v114
	v_sub_f32_e32 v115, v115, v167
	v_exp_f32_e32 v227, v115
	v_sub_f32_e32 v115, v116, v167
	v_add_f32_e32 v128, 0, v112
	v_exp_f32_e32 v115, v115
	v_sub_f32_e32 v116, v117, v167
	v_add_f32_e32 v128, v113, v128
	v_exp_f32_e32 v116, v116
	v_sub_f32_e32 v117, v118, v167
	v_add_f32_e32 v128, v114, v128
	v_exp_f32_e32 v117, v117
	v_sub_f32_e32 v118, v119, v167
	v_add_f32_e32 v128, v227, v128
	v_exp_f32_e32 v118, v118
	v_sub_f32_e32 v120, v120, v167
	v_add_f32_e32 v128, v115, v128
	v_exp_f32_e32 v217, v120
	v_sub_f32_e32 v120, v121, v167
	v_add_f32_e32 v128, v116, v128
	v_exp_f32_e32 v221, v120
	v_sub_f32_e32 v120, v122, v167
	v_add_f32_e32 v128, v117, v128
	v_exp_f32_e32 v210, v120
	v_sub_f32_e32 v120, v123, v167
	v_add_f32_e32 v119, v118, v128
	v_exp_f32_e32 v218, v120
	v_sub_f32_e32 v120, v124, v167
	v_add_f32_e32 v119, v217, v119
	v_exp_f32_e32 v215, v120
	v_sub_f32_e32 v120, v125, v167
	v_add_f32_e32 v119, v221, v119
	v_exp_f32_e32 v220, v120
	v_sub_f32_e32 v120, v126, v167
	v_add_f32_e32 v119, v210, v119
	v_exp_f32_e32 v208, v120
	v_sub_f32_e32 v120, v127, v167
	v_add_f32_e32 v119, v218, v119
	v_exp_f32_e32 v216, v120
	v_sub_f32_e32 v96, v96, v167
	v_add_f32_e32 v119, v215, v119
	v_exp_f32_e32 v197, v96
	v_sub_f32_e32 v97, v97, v167
	v_add_f32_e32 v119, v220, v119
	v_exp_f32_e32 v201, v97
	v_sub_f32_e32 v97, v98, v167
	v_add_f32_e32 v119, v208, v119
	v_exp_f32_e32 v194, v97
; DI unsigned pk2(float lo, float hi) { bf2_t v = __builtin_convertvector((f32x2){lo, hi}, bf2_t); return __builtin_bit_cast(unsigned, v); }
; DI void xattn_unit(const bf16_t* __restrict__ Qg, const bf16_t* __restrict__ Kg, const bf16_t* __restrict__ Vg, bf16_t* __restrict__ Og, lds_t* shm) {
;     ...
;   float rs = 0.f;
;   bf16x8 P[4][2][2];
; #pragma unroll
;   for (int t = 0; t < 4; ++t)
; #pragma unroll
;     for (int kb = 0; kb < 2; ++kb)
; #pragma unroll
;       for (int s2 = 0; s2 < 2; ++s2) {
;         float e[8];
; #pragma unroll
;         for (int j = 0; j < 8; ++j) { e[j] = __builtin_amdgcn_exp2f(S[t][kb][8 * s2 + j] - mx); rs += e[j]; }
;         u32x4 w; w.x = pk2(e[0], e[1]); w.y = pk2(e[2], e[3]); w.z = pk2(e[4], e[5]); w.w = pk2(e[6], e[7]);
;         P[t][kb][s2] = __builtin_bit_cast(bf16x8, w);
;       }
	v_sub_f32_e32 v97, v99, v167
	v_add_f32_e32 v119, v216, v119
	v_exp_f32_e32 v198, v97
	v_sub_f32_e32 v97, v100, v167
	v_add_f32_e32 v96, v197, v119
	v_exp_f32_e32 v195, v97
	v_sub_f32_e32 v97, v101, v167
	v_add_f32_e32 v96, v201, v96
	v_exp_f32_e32 v199, v97
	v_sub_f32_e32 v97, v102, v167
	v_add_f32_e32 v96, v194, v96
	v_exp_f32_e32 v191, v97
	v_sub_f32_e32 v97, v103, v167
	v_add_f32_e32 v96, v198, v96
	v_exp_f32_e32 v193, v97
	v_sub_f32_e32 v97, v104, v167
	v_add_f32_e32 v96, v195, v96
	v_exp_f32_e32 v179, v97
	v_sub_f32_e32 v97, v105, v167
	v_add_f32_e32 v96, v199, v96
	v_exp_f32_e32 v183, v97
	v_sub_f32_e32 v97, v106, v167
	v_add_f32_e32 v96, v191, v96
	v_exp_f32_e32 v177, v97
	v_sub_f32_e32 v97, v107, v167
	v_add_f32_e32 v96, v193, v96
	v_exp_f32_e32 v180, v97
	v_sub_f32_e32 v97, v108, v167
	v_add_f32_e32 v96, v179, v96
	v_exp_f32_e32 v178, v97
	v_sub_f32_e32 v97, v109, v167
	v_add_f32_e32 v96, v183, v96
	v_exp_f32_e32 v181, v97
	v_sub_f32_e32 v97, v110, v167
	v_add_f32_e32 v96, v177, v96
	v_exp_f32_e32 v174, v97
	v_sub_f32_e32 v97, v111, v167
	v_add_f32_e32 v96, v180, v96
	v_exp_f32_e32 v176, v97
	v_sub_f32_e32 v80, v80, v167
	v_add_f32_e32 v96, v178, v96
	v_exp_f32_e32 v80, v80
	v_sub_f32_e32 v81, v81, v167
	v_add_f32_e32 v96, v181, v96
	v_exp_f32_e32 v81, v81
	v_sub_f32_e32 v82, v82, v167
	v_add_f32_e32 v96, v174, v96
	v_exp_f32_e32 v82, v82
	v_sub_f32_e32 v83, v83, v167
	v_add_f32_e32 v96, v176, v96
	v_exp_f32_e32 v83, v83
	v_sub_f32_e32 v84, v84, v167
	v_add_f32_e32 v96, v80, v96
	v_exp_f32_e32 v84, v84
	v_sub_f32_e32 v85, v85, v167
	v_add_f32_e32 v96, v81, v96
	v_exp_f32_e32 v85, v85
	v_sub_f32_e32 v86, v86, v167
	v_add_f32_e32 v96, v82, v96
	v_exp_f32_e32 v86, v86
	v_sub_f32_e32 v87, v87, v167
	v_add_f32_e32 v96, v83, v96
	v_exp_f32_e32 v87, v87
	v_cvt_pk_bf16_f32 v128, v80, v81
	v_sub_f32_e32 v80, v88, v167
	v_add_f32_e32 v96, v84, v96
	v_cvt_pk_bf16_f32 v129, v82, v83
	v_exp_f32_e32 v80, v80
	v_sub_f32_e32 v82, v89, v167
	v_add_f32_e32 v96, v85, v96
	v_exp_f32_e32 v82, v82
	v_sub_f32_e32 v83, v90, v167
	v_add_f32_e32 v96, v86, v96
	v_cvt_pk_bf16_f32 v130, v84, v85
	v_exp_f32_e32 v83, v83
	v_sub_f32_e32 v84, v91, v167
	v_add_f32_e32 v96, v87, v96
	v_exp_f32_e32 v84, v84
	v_sub_f32_e32 v85, v92, v167
	v_cvt_pk_bf16_f32 v131, v86, v87
	v_add_f32_e32 v81, v80, v96
	v_exp_f32_e32 v85, v85
	v_sub_f32_e32 v86, v93, v167
	v_add_f32_e32 v81, v82, v81
	v_exp_f32_e32 v86, v86
	v_sub_f32_e32 v87, v94, v167
	v_add_f32_e32 v81, v83, v81
	v_exp_f32_e32 v87, v87
	v_sub_f32_e32 v88, v95, v167
	v_add_f32_e32 v81, v84, v81
	v_exp_f32_e32 v88, v88
	v_sub_f32_e32 v64, v64, v167
	v_add_f32_e32 v81, v85, v81
	v_exp_f32_e32 v64, v64
	v_sub_f32_e32 v65, v65, v167
	v_add_f32_e32 v81, v86, v81
	v_exp_f32_e32 v65, v65
	v_sub_f32_e32 v66, v66, v167
	v_add_f32_e32 v81, v87, v81
	v_exp_f32_e32 v66, v66
	v_sub_f32_e32 v67, v67, v167
	v_add_f32_e32 v81, v88, v81
	v_exp_f32_e32 v67, v67
	v_sub_f32_e32 v68, v68, v167
	v_cvt_pk_bf16_f32 v132, v80, v82
	v_add_f32_e32 v80, v64, v81
	v_exp_f32_e32 v68, v68
	v_sub_f32_e32 v69, v69, v167
	v_add_f32_e32 v80, v65, v80
	v_exp_f32_e32 v69, v69
	v_sub_f32_e32 v70, v70, v167
	v_add_f32_e32 v80, v66, v80
	v_exp_f32_e32 v70, v70
	v_sub_f32_e32 v71, v71, v167
	v_add_f32_e32 v80, v67, v80
	v_exp_f32_e32 v71, v71
	v_cvt_pk_bf16_f32 v136, v64, v65
	v_sub_f32_e32 v64, v72, v167
	v_add_f32_e32 v80, v68, v80
	v_cvt_pk_bf16_f32 v137, v66, v67
	v_exp_f32_e32 v64, v64
	v_sub_f32_e32 v66, v73, v167
	v_add_f32_e32 v80, v69, v80
	v_exp_f32_e32 v66, v66
	v_sub_f32_e32 v67, v74, v167
	v_add_f32_e32 v80, v70, v80
	v_cvt_pk_bf16_f32 v138, v68, v69
	v_exp_f32_e32 v67, v67
	v_sub_f32_e32 v68, v75, v167
	v_add_f32_e32 v80, v71, v80
	v_exp_f32_e32 v68, v68
	v_sub_f32_e32 v69, v76, v167
	v_cvt_pk_bf16_f32 v139, v70, v71
	v_add_f32_e32 v65, v64, v80
	v_exp_f32_e32 v69, v69
	v_sub_f32_e32 v70, v77, v167
	v_add_f32_e32 v65, v66, v65
	v_exp_f32_e32 v70, v70
	v_sub_f32_e32 v71, v78, v167
	v_add_f32_e32 v65, v67, v65
	v_exp_f32_e32 v71, v71
	v_sub_f32_e32 v72, v79, v167
	v_add_f32_e32 v65, v68, v65
	v_exp_f32_e32 v72, v72
	v_sub_f32_e32 v48, v48, v167
	v_add_f32_e32 v65, v69, v65
	v_exp_f32_e32 v48, v48
	v_sub_f32_e32 v49, v49, v167
	v_add_f32_e32 v65, v70, v65
	v_exp_f32_e32 v49, v49
	v_sub_f32_e32 v50, v50, v167
	v_add_f32_e32 v65, v71, v65
	v_exp_f32_e32 v50, v50
	v_sub_f32_e32 v51, v51, v167
	v_add_f32_e32 v65, v72, v65
	v_exp_f32_e32 v51, v51
	v_sub_f32_e32 v52, v52, v167
	v_cvt_pk_bf16_f32 v156, v64, v66
	v_add_f32_e32 v64, v48, v65
	v_exp_f32_e32 v52, v52
	v_sub_f32_e32 v53, v53, v167
	v_add_f32_e32 v64, v49, v64
	v_exp_f32_e32 v53, v53
	v_sub_f32_e32 v54, v54, v167
	v_add_f32_e32 v64, v50, v64
	v_exp_f32_e32 v54, v54
	v_sub_f32_e32 v55, v55, v167
	v_add_f32_e32 v64, v51, v64
	v_exp_f32_e32 v55, v55
	v_cvt_pk_bf16_f32 v152, v48, v49
	v_sub_f32_e32 v48, v56, v167
	v_add_f32_e32 v64, v52, v64
	v_cvt_pk_bf16_f32 v153, v50, v51
	v_exp_f32_e32 v48, v48
	v_sub_f32_e32 v50, v57, v167
	v_add_f32_e32 v64, v53, v64
	v_exp_f32_e32 v50, v50
	v_sub_f32_e32 v51, v58, v167
	v_add_f32_e32 v64, v54, v64
	v_cvt_pk_bf16_f32 v154, v52, v53
	v_exp_f32_e32 v51, v51
	v_sub_f32_e32 v52, v59, v167
	v_add_f32_e32 v64, v55, v64
	v_exp_f32_e32 v52, v52
	v_sub_f32_e32 v53, v60, v167
	v_cvt_pk_bf16_f32 v155, v54, v55
	v_add_f32_e32 v49, v48, v64
	v_exp_f32_e32 v53, v53
	v_sub_f32_e32 v54, v61, v167
	v_add_f32_e32 v49, v50, v49
	v_exp_f32_e32 v54, v54
	v_sub_f32_e32 v55, v62, v167
	v_add_f32_e32 v49, v51, v49
	v_exp_f32_e32 v55, v55
	v_sub_f32_e32 v56, v63, v167
	v_add_f32_e32 v49, v52, v49
	v_exp_f32_e32 v56, v56
	v_sub_f32_e32 v32, v32, v167
	v_add_f32_e32 v49, v53, v49
; DI unsigned pk2(float lo, float hi) { bf2_t v = __builtin_convertvector((f32x2){lo, hi}, bf2_t); return __builtin_bit_cast(unsigned, v); }
; DI void xattn_unit(const bf16_t* __restrict__ Qg, const bf16_t* __restrict__ Kg, const bf16_t* __restrict__ Vg, bf16_t* __restrict__ Og, lds_t* shm) {
;     ...
;   float rs = 0.f;
;   bf16x8 P[4][2][2];
; #pragma unroll
;   for (int t = 0; t < 4; ++t)
; #pragma unroll
;     for (int kb = 0; kb < 2; ++kb)
; #pragma unroll
;       for (int s2 = 0; s2 < 2; ++s2) {
;         float e[8];
; #pragma unroll
;         for (int j = 0; j < 8; ++j) { e[j] = __builtin_amdgcn_exp2f(S[t][kb][8 * s2 + j] - mx); rs += e[j]; }
;         u32x4 w; w.x = pk2(e[0], e[1]); w.y = pk2(e[2], e[3]); w.z = pk2(e[4], e[5]); w.w = pk2(e[6], e[7]);
;         P[t][kb][s2] = __builtin_bit_cast(bf16x8, w);
;       }
;   const float l = rs + __shfl_xor(rs, 32);
;   __builtin_amdgcn_sched_barrier(0);
;   __syncthreads();
;   __builtin_amdgcn_sched_barrier(0);
	v_exp_f32_e32 v32, v32
	v_sub_f32_e32 v33, v33, v167
	v_add_f32_e32 v49, v54, v49
	v_exp_f32_e32 v33, v33
	v_sub_f32_e32 v34, v34, v167
	v_add_f32_e32 v49, v55, v49
	v_exp_f32_e32 v34, v34
	v_sub_f32_e32 v35, v35, v167
	v_add_f32_e32 v49, v56, v49
	v_exp_f32_e32 v35, v35
	v_sub_f32_e32 v36, v36, v167
	v_cvt_pk_bf16_f32 v148, v48, v50
	v_add_f32_e32 v48, v32, v49
	v_exp_f32_e32 v36, v36
	v_sub_f32_e32 v37, v37, v167
	v_add_f32_e32 v48, v33, v48
	v_exp_f32_e32 v37, v37
	v_sub_f32_e32 v38, v38, v167
	v_add_f32_e32 v48, v34, v48
	v_exp_f32_e32 v38, v38
	v_sub_f32_e32 v39, v39, v167
	v_add_f32_e32 v48, v35, v48
	v_exp_f32_e32 v39, v39
	v_cvt_pk_bf16_f32 v140, v32, v33
	v_sub_f32_e32 v32, v40, v167
	v_add_f32_e32 v48, v36, v48
	v_cvt_pk_bf16_f32 v141, v34, v35
	v_exp_f32_e32 v32, v32
	v_sub_f32_e32 v34, v41, v167
	v_add_f32_e32 v48, v37, v48
	v_exp_f32_e32 v34, v34
	v_sub_f32_e32 v35, v42, v167
	v_add_f32_e32 v48, v38, v48
	v_cvt_pk_bf16_f32 v142, v36, v37
	v_exp_f32_e32 v35, v35
	v_sub_f32_e32 v36, v43, v167
	v_add_f32_e32 v48, v39, v48
	v_exp_f32_e32 v36, v36
	v_sub_f32_e32 v37, v44, v167
	v_cvt_pk_bf16_f32 v143, v38, v39
	v_add_f32_e32 v33, v32, v48
	v_exp_f32_e32 v37, v37
	v_sub_f32_e32 v38, v45, v167
	v_add_f32_e32 v33, v34, v33
	v_exp_f32_e32 v38, v38
	v_sub_f32_e32 v39, v46, v167
	v_add_f32_e32 v33, v35, v33
	v_exp_f32_e32 v39, v39
	v_sub_f32_e32 v40, v47, v167
	v_add_f32_e32 v33, v36, v33
	v_exp_f32_e32 v40, v40
	v_sub_f32_e32 v16, v16, v167
	v_add_f32_e32 v33, v37, v33
	v_exp_f32_e32 v171, v16
	v_sub_f32_e32 v17, v17, v167
	v_add_f32_e32 v33, v38, v33
	v_exp_f32_e32 v172, v17
	v_sub_f32_e32 v17, v18, v167
	v_add_f32_e32 v33, v39, v33
	v_exp_f32_e32 v173, v17
	v_sub_f32_e32 v17, v19, v167
	v_add_f32_e32 v33, v40, v33
	v_exp_f32_e32 v175, v17
	v_sub_f32_e32 v17, v20, v167
	v_add_f32_e32 v16, v171, v33
	v_exp_f32_e32 v182, v17
	v_sub_f32_e32 v17, v21, v167
	v_add_f32_e32 v16, v172, v16
	v_exp_f32_e32 v184, v17
	v_sub_f32_e32 v17, v22, v167
	v_add_f32_e32 v16, v173, v16
	v_exp_f32_e32 v185, v17
	v_sub_f32_e32 v17, v23, v167
	v_add_f32_e32 v16, v175, v16
	v_exp_f32_e32 v186, v17
	v_sub_f32_e32 v17, v24, v167
	v_add_f32_e32 v16, v182, v16
	v_exp_f32_e32 v187, v17
	v_sub_f32_e32 v17, v25, v167
	v_add_f32_e32 v16, v184, v16
	v_exp_f32_e32 v188, v17
	v_sub_f32_e32 v17, v26, v167
	v_add_f32_e32 v16, v185, v16
	v_exp_f32_e32 v189, v17
	v_sub_f32_e32 v17, v27, v167
	v_add_f32_e32 v16, v186, v16
	v_exp_f32_e32 v190, v17
	v_sub_f32_e32 v17, v28, v167
	v_add_f32_e32 v16, v187, v16
	v_exp_f32_e32 v192, v17
	v_sub_f32_e32 v17, v29, v167
	v_add_f32_e32 v16, v188, v16
	v_exp_f32_e32 v196, v17
	v_sub_f32_e32 v17, v30, v167
	v_add_f32_e32 v16, v189, v16
	v_exp_f32_e32 v200, v17
	v_sub_f32_e32 v17, v31, v167
	v_add_f32_e32 v16, v190, v16
	v_exp_f32_e32 v202, v17
	v_sub_f32_e32 v0, v0, v167
	v_add_f32_e32 v16, v192, v16
	v_exp_f32_e32 v203, v0
	v_sub_f32_e32 v1, v1, v167
	v_add_f32_e32 v16, v196, v16
	v_exp_f32_e32 v204, v1
	v_sub_f32_e32 v1, v2, v167
	v_add_f32_e32 v16, v200, v16
	v_exp_f32_e32 v205, v1
	v_sub_f32_e32 v1, v3, v167
	v_add_f32_e32 v16, v202, v16
	v_exp_f32_e32 v206, v1
	v_sub_f32_e32 v1, v4, v167
	v_add_f32_e32 v0, v203, v16
	v_exp_f32_e32 v207, v1
	v_sub_f32_e32 v1, v5, v167
	v_add_f32_e32 v0, v204, v0
	v_exp_f32_e32 v209, v1
	v_sub_f32_e32 v1, v6, v167
	v_add_f32_e32 v0, v205, v0
	v_exp_f32_e32 v211, v1
	v_sub_f32_e32 v1, v7, v167
	v_add_f32_e32 v0, v206, v0
	v_exp_f32_e32 v219, v1
	v_sub_f32_e32 v1, v8, v167
	v_add_f32_e32 v0, v207, v0
	v_exp_f32_e32 v222, v1
	v_sub_f32_e32 v1, v9, v167
	v_add_f32_e32 v0, v209, v0
	v_exp_f32_e32 v223, v1
	v_sub_f32_e32 v1, v10, v167
	v_add_f32_e32 v0, v211, v0
	v_exp_f32_e32 v224, v1
	v_sub_f32_e32 v1, v11, v167
	v_add_f32_e32 v0, v219, v0
	v_exp_f32_e32 v225, v1
	v_sub_f32_e32 v1, v12, v167
	v_add_f32_e32 v0, v222, v0
	v_exp_f32_e32 v226, v1
	v_sub_f32_e32 v1, v13, v167
	v_add_f32_e32 v0, v223, v0
	v_exp_f32_e32 v228, v1
	v_sub_f32_e32 v1, v14, v167
	v_add_f32_e32 v0, v224, v0
	v_exp_f32_e32 v229, v1
	v_sub_f32_e32 v1, v15, v167
	v_add_f32_e32 v0, v225, v0
	v_exp_f32_e32 v230, v1
	v_add_f32_e32 v0, v226, v0
	v_add_f32_e32 v0, v228, v0
	v_add_f32_e32 v0, v229, v0
	v_add_f32_e32 v167, v230, v0
	v_cvt_pk_bf16_f32 v133, v83, v84
	v_cvt_pk_bf16_f32 v134, v85, v86
	v_cvt_pk_bf16_f32 v135, v87, v88
	v_cvt_pk_bf16_f32 v157, v67, v68
	v_cvt_pk_bf16_f32 v158, v69, v70
	v_cvt_pk_bf16_f32 v159, v71, v72
	v_cvt_pk_bf16_f32 v149, v51, v52
	v_cvt_pk_bf16_f32 v150, v53, v54
	v_cvt_pk_bf16_f32 v151, v55, v56
	v_cvt_pk_bf16_f32 v144, v32, v34
	v_cvt_pk_bf16_f32 v145, v35, v36
	v_cvt_pk_bf16_f32 v146, v37, v38
	v_cvt_pk_bf16_f32 v147, v39, v40
	ds_bpermute_b32 v168, v213, v167
	s_waitcnt lgkmcnt(0)
	s_barrier
; #define MFMA32(a, b, c) __builtin_amdgcn_mfma_f32_32x32x16_bf16((a), (b), (c), 0, 0, 0)
; DI void xattn_unit(const bf16_t* __restrict__ Qg, const bf16_t* __restrict__ Kg, const bf16_t* __restrict__ Vg, bf16_t* __restrict__ Og, lds_t* shm) {
;     ...
; #pragma unroll
;   for (int t = 1; t < 4; ++t) issue_tile(Vg, t, t * 32768);
;   f32x16 O[NC];
; #pragma unroll
;   for (int c = 0; c < NC; ++c)
; #pragma unroll
;     for (int i = 0; i < 16; ++i) O[c][i] = 0.f;
; #pragma unroll
;   for (int t = 0; t < 4; ++t) {
;     if (t == 1) { __builtin_amdgcn_sched_barrier(0); asm volatile("s_waitcnt vmcnt(0)" ::: "memory"); __syncthreads(); __builtin_amdgcn_sched_barrier(0); }
;     const unsigned vbase = (t == 0) ? 131072u : (unsigned)t * 32768u;
; #pragma unroll
;     for (int ks = 0; ks < 4; ++ks)
; #pragma unroll
;       for (int c = 0; c < NC; ++c) {
;         const unsigned vo = vbase + (c >> 2) * 16384 + 512 * (c & 3) + 4096 * ks;
;         const bf16x8 vf = tr_pair(shm + vo + va0, shm + vo + 2048 + va1);
;         O[c] = MFMA32(vf, P[t][ks >> 1][ks & 1], O[c]);
;       }
	s_add_u32 s38, s36, 0x40800
	s_mov_b32 m0, s67
	s_addc_u32 s39, s37, 0
	global_load_lds_dwordx4 v160, s[38:39]
	s_mov_b32 m0, s0
	v_add_u32_e32 v2, s14, v170
	global_load_lds_dwordx4 v162, s[38:39]
	s_add_u32 s38, s36, 0x40900
	s_addc_u32 s39, s37, 0
	s_mov_b32 m0, s1
	s_add_u32 s0, s36, 0x80800
	global_load_lds_dwordx4 v160, s[38:39]
	s_mov_b32 m0, vcc_lo
	s_addc_u32 s1, s37, 0
	global_load_lds_dwordx4 v162, s[38:39]
	s_mov_b32 m0, vcc_hi
	v_cvt_pk_bf16_f32 v0, v112, v113
	global_load_lds_dwordx4 v160, s[0:1]
	s_mov_b32 m0, s28
	v_cvt_pk_bf16_f32 v1, v114, v227
	global_load_lds_dwordx4 v162, s[0:1]
	s_add_u32 s0, s36, 0x80900
	s_addc_u32 s1, s37, 0
	s_mov_b32 m0, s29
	v_cvt_pk_bf16_f32 v232, v217, v221
	global_load_lds_dwordx4 v160, s[0:1]
	s_mov_b32 m0, s68
	v_cvt_pk_bf16_f32 v233, v210, v218
	global_load_lds_dwordx4 v162, s[0:1]
	s_add_u32 s0, s36, 0xc0800
	s_addc_u32 s1, s37, 0
	s_mov_b32 m0, s69
	v_cvt_pk_bf16_f32 v234, v215, v220
	global_load_lds_dwordx4 v160, s[0:1]
	s_mov_b32 m0, s76
	v_cvt_pk_bf16_f32 v235, v208, v216
	global_load_lds_dwordx4 v162, s[0:1]
	s_add_u32 s0, s36, 0xc0900
	s_addc_u32 s1, s37, 0
	s_mov_b32 m0, s77
	s_nop 0
	global_load_lds_dwordx4 v160, s[0:1]
	s_mov_b32 m0, s78
	v_and_b32_e32 v160, 8, v169
	global_load_lds_dwordx4 v162, s[0:1]
	v_readlane_b32 s0, v254, 14
	v_add3_u32 v2, v2, v166, v160
	s_nop 0
	v_add_u32_e32 v3, s0, v170
	v_add3_u32 v3, v3, v165, v160
	ds_read_b64_tr_b16 v[4:5], v2
	ds_read_b64_tr_b16 v[6:7], v3
	v_readlane_b32 s0, v254, 25
	v_cvt_pk_bf16_f32 v2, v115, v116
	v_cvt_pk_bf16_f32 v3, v117, v118
	v_add_u32_e32 v8, s0, v170
	v_readlane_b32 s0, v254, 26
	v_add3_u32 v8, v8, v166, v160
	s_waitcnt lgkmcnt(0)
	v_mfma_f32_32x32x16_bf16 v[112:127], v[4:7], v[0:3], 0
	v_add_u32_e32 v9, s0, v170
	v_readlane_b32 s0, v254, 27
	v_add3_u32 v10, v9, v165, v160
	ds_read_b64_tr_b16 v[8:9], v8
	ds_read_b64_tr_b16 v[10:11], v10
	v_add_u32_e32 v4, s0, v170
	v_readlane_b32 s0, v254, 28
	v_add3_u32 v4, v4, v166, v160
	s_waitcnt lgkmcnt(0)
	v_mfma_f32_32x32x16_bf16 v[96:111], v[8:11], v[0:3], 0
	v_add_u32_e32 v5, s0, v170
	v_add3_u32 v6, v5, v165, v160
	ds_read_b64_tr_b16 v[4:5], v4
	ds_read_b64_tr_b16 v[6:7], v6
	v_readlane_b32 s0, v254, 29
	s_nop 1
	v_add_u32_e32 v8, s0, v170
	v_readlane_b32 s0, v254, 30
	v_add3_u32 v8, v8, v166, v160
	s_waitcnt lgkmcnt(0)
	v_mfma_f32_32x32x16_bf16 v[80:95], v[4:7], v[0:3], 0
	v_add_u32_e32 v9, s0, v170
	v_readlane_b32 s0, v254, 31
	v_add3_u32 v10, v9, v165, v160
	ds_read_b64_tr_b16 v[8:9], v8
	ds_read_b64_tr_b16 v[10:11], v10
	v_add_u32_e32 v4, s0, v170
	v_readlane_b32 s0, v254, 32
	v_add3_u32 v4, v4, v166, v160
	s_waitcnt lgkmcnt(0)
	v_mfma_f32_32x32x16_bf16 v[64:79], v[8:11], v[0:3], 0
	v_add_u32_e32 v5, s0, v170
	v_add3_u32 v6, v5, v165, v160
	ds_read_b64_tr_b16 v[4:5], v4
	ds_read_b64_tr_b16 v[6:7], v6
	v_readlane_b32 s0, v254, 33
	s_nop 1
	v_add_u32_e32 v8, s0, v170
	v_readlane_b32 s0, v254, 34
	v_add3_u32 v8, v8, v166, v160
	s_waitcnt lgkmcnt(0)
	v_mfma_f32_32x32x16_bf16 v[48:63], v[4:7], v[0:3], 0
	v_add_u32_e32 v9, s0, v170
	v_readlane_b32 s0, v254, 35
	v_add3_u32 v10, v9, v165, v160
	ds_read_b64_tr_b16 v[8:9], v8
	ds_read_b64_tr_b16 v[10:11], v10
	v_add_u32_e32 v4, s0, v170
	v_readlane_b32 s0, v254, 36
	v_add3_u32 v4, v4, v166, v160
	s_waitcnt lgkmcnt(0)
	v_mfma_f32_32x32x16_bf16 v[32:47], v[8:11], v[0:3], 0
	v_add_u32_e32 v5, s0, v170
	v_add3_u32 v6, v5, v165, v160
	ds_read_b64_tr_b16 v[4:5], v4
	ds_read_b64_tr_b16 v[6:7], v6
	v_readlane_b32 s0, v254, 37
	s_nop 1
	v_add_u32_e32 v8, s0, v170
	v_readlane_b32 s0, v254, 38
	s_waitcnt lgkmcnt(0)
	v_mfma_f32_32x32x16_bf16 v[16:31], v[4:7], v[0:3], 0
	v_add3_u32 v8, v8, v166, v160
	v_add_u32_e32 v9, s0, v170
	v_readlane_b32 s0, v254, 39
	v_add3_u32 v10, v9, v165, v160
	ds_read_b64_tr_b16 v[8:9], v8
	ds_read_b64_tr_b16 v[10:11], v10
	v_add_u32_e32 v4, s0, v170
	v_readlane_b32 s0, v254, 40
	v_add3_u32 v4, v4, v166, v160
	s_nop 0
	v_add_u32_e32 v5, s0, v170
	v_readlane_b32 s0, v254, 41
	v_add3_u32 v5, v5, v165, v160
	ds_read_b64_tr_b16 v[236:237], v4
	ds_read_b64_tr_b16 v[238:239], v5
	v_add_u32_e32 v162, s0, v170
	v_readlane_b32 s0, v254, 42
	v_add3_u32 v162, v162, v166, v160
	s_waitcnt lgkmcnt(0)
	v_mfma_f32_32x32x16_bf16 v[112:127], v[236:239], v[232:235], v[112:127]
	v_add_u32_e32 v169, s0, v170
	v_add3_u32 v169, v169, v165, v160
	ds_read_b64_tr_b16 v[240:241], v162
	ds_read_b64_tr_b16 v[242:243], v169
	v_readlane_b32 s0, v254, 43
	s_nop 1
	v_add_u32_e32 v162, s0, v170
	v_readlane_b32 s0, v254, 44
	v_add3_u32 v162, v162, v166, v160
	s_waitcnt lgkmcnt(0)
	v_mfma_f32_32x32x16_bf16 v[96:111], v[240:243], v[232:235], v[96:111]
	v_add_u32_e32 v169, s0, v170
	v_readlane_b32 s0, v254, 45
	v_add3_u32 v169, v169, v165, v160
	ds_read_b64_tr_b16 v[236:237], v162
	ds_read_b64_tr_b16 v[238:239], v169
	v_add_u32_e32 v162, s0, v170
	v_readlane_b32 s0, v254, 46
	v_add3_u32 v162, v162, v166, v160
	s_waitcnt lgkmcnt(0)
	v_mfma_f32_32x32x16_bf16 v[80:95], v[236:239], v[232:235], v[80:95]
	v_add_u32_e32 v169, s0, v170
	v_add3_u32 v169, v169, v165, v160
	ds_read_b64_tr_b16 v[240:241], v162
	ds_read_b64_tr_b16 v[242:243], v169
	v_readlane_b32 s0, v254, 47
	s_nop 1
	v_add_u32_e32 v162, s0, v170
	v_readlane_b32 s0, v254, 48
	v_add3_u32 v162, v162, v166, v160
	s_waitcnt lgkmcnt(0)
	v_mfma_f32_32x32x16_bf16 v[64:79], v[240:243], v[232:235], v[64:79]
	v_add_u32_e32 v169, s0, v170
	v_readlane_b32 s0, v254, 49
	v_add3_u32 v169, v169, v165, v160
	ds_read_b64_tr_b16 v[236:237], v162
	ds_read_b64_tr_b16 v[238:239], v169
	v_add_u32_e32 v162, s0, v170
	v_readlane_b32 s0, v254, 50
	v_add3_u32 v162, v162, v166, v160
	v_mfma_f32_32x32x16_bf16 v[0:15], v[8:11], v[0:3], 0
	v_add_u32_e32 v169, s0, v170
	v_add3_u32 v169, v169, v165, v160
	ds_read_b64_tr_b16 v[240:241], v162
	ds_read_b64_tr_b16 v[242:243], v169
	v_readlane_b32 s0, v254, 51
	s_nop 1
	v_add_u32_e32 v162, s0, v170
	v_readlane_b32 s0, v254, 52
	v_add3_u32 v162, v162, v166, v160
	s_waitcnt lgkmcnt(0)
; #define MFMA32(a, b, c) __builtin_amdgcn_mfma_f32_32x32x16_bf16((a), (b), (c), 0, 0, 0)
; DI void xattn_unit(const bf16_t* __restrict__ Qg, const bf16_t* __restrict__ Kg, const bf16_t* __restrict__ Vg, bf16_t* __restrict__ Og, lds_t* shm) {
;     ...
;   for (int t = 0; t < 4; ++t) {
;     if (t == 1) { __builtin_amdgcn_sched_barrier(0); asm volatile("s_waitcnt vmcnt(0)" ::: "memory"); __syncthreads(); __builtin_amdgcn_sched_barrier(0); }
;     const unsigned vbase = (t == 0) ? 131072u : (unsigned)t * 32768u;
; #pragma unroll
;     for (int ks = 0; ks < 4; ++ks)
; #pragma unroll
;       for (int c = 0; c < NC; ++c) {
;         const unsigned vo = vbase + (c >> 2) * 16384 + 512 * (c & 3) + 4096 * ks;
;         const bf16x8 vf = tr_pair(shm + vo + va0, shm + vo + 2048 + va1);
;         O[c] = MFMA32(vf, P[t][ks >> 1][ks & 1], O[c]);
;       }
	v_mfma_f32_32x32x16_bf16 v[32:47], v[240:243], v[232:235], v[32:47]
	v_add_u32_e32 v169, s0, v170
	v_readlane_b32 s0, v254, 53
	v_add3_u32 v169, v169, v165, v160
	ds_read_b64_tr_b16 v[244:245], v162
	ds_read_b64_tr_b16 v[246:247], v169
	v_add_u32_e32 v162, s0, v170
	v_readlane_b32 s0, v254, 54
	v_add3_u32 v162, v162, v166, v160
	s_waitcnt lgkmcnt(0)
	v_mfma_f32_32x32x16_bf16 v[16:31], v[244:247], v[232:235], v[16:31]
	v_add_u32_e32 v169, s0, v170
	v_add3_u32 v169, v169, v165, v160
	ds_read_b64_tr_b16 v[240:241], v162
	ds_read_b64_tr_b16 v[242:243], v169
	v_readlane_b32 s0, v254, 55
	s_nop 1
	v_add_u32_e32 v162, s0, v170
	v_readlane_b32 s0, v254, 56
	v_add3_u32 v162, v162, v166, v160
	v_mfma_f32_32x32x16_bf16 v[48:63], v[236:239], v[232:235], v[48:63]
	v_add_u32_e32 v169, s0, v170
	v_readlane_b32 s0, v254, 57
	v_add3_u32 v169, v169, v165, v160
	ds_read_b64_tr_b16 v[244:245], v162
	ds_read_b64_tr_b16 v[246:247], v169
	v_add_u32_e32 v162, s0, v170
	v_readlane_b32 s0, v254, 58
	v_add3_u32 v162, v162, v166, v160
	s_waitcnt lgkmcnt(0)
	v_mfma_f32_32x32x16_bf16 v[0:15], v[240:243], v[232:235], v[0:15]
	v_add_u32_e32 v169, s0, v170
	v_add3_u32 v169, v169, v165, v160
	ds_read_b64_tr_b16 v[232:233], v162
	ds_read_b64_tr_b16 v[234:235], v169
	v_readlane_b32 s0, v254, 59
	v_cvt_pk_bf16_f32 v236, v197, v201
	v_cvt_pk_bf16_f32 v237, v194, v198
	v_add_u32_e32 v162, s0, v170
	v_readlane_b32 s0, v254, 60
	v_cvt_pk_bf16_f32 v238, v195, v199
	v_cvt_pk_bf16_f32 v239, v191, v193
	v_add3_u32 v162, v162, v166, v160
	v_add_u32_e32 v169, s0, v170
	v_readlane_b32 s0, v254, 61
	s_waitcnt lgkmcnt(0)
	v_mfma_f32_32x32x16_bf16 v[96:111], v[232:235], v[236:239], v[96:111]
	v_add3_u32 v169, v169, v165, v160
	ds_read_b64_tr_b16 v[232:233], v162
	ds_read_b64_tr_b16 v[234:235], v169
	v_add_u32_e32 v162, s0, v170
	v_readlane_b32 s0, v254, 62
	v_add3_u32 v162, v162, v166, v160
	s_nop 0
	v_add_u32_e32 v169, s0, v170
	v_add3_u32 v169, v169, v165, v160
	ds_read_b64_tr_b16 v[240:241], v162
	ds_read_b64_tr_b16 v[242:243], v169
	v_readlane_b32 s0, v254, 63
	s_waitcnt lgkmcnt(0)
	v_mfma_f32_32x32x16_bf16 v[80:95], v[232:235], v[236:239], v[80:95]
	v_add_u32_e32 v162, s0, v170
	v_readlane_b32 s0, v255, 0
	v_add3_u32 v162, v162, v166, v160
	s_nop 0
	v_add_u32_e32 v169, s0, v170
	v_readlane_b32 s0, v255, 1
	v_add3_u32 v169, v169, v165, v160
	ds_read_b64_tr_b16 v[232:233], v162
	ds_read_b64_tr_b16 v[234:235], v169
	v_add_u32_e32 v162, s0, v170
	v_readlane_b32 s0, v255, 2
	v_add3_u32 v162, v162, v166, v160
	v_mfma_f32_32x32x16_bf16 v[64:79], v[240:243], v[236:239], v[64:79]
	v_add_u32_e32 v169, s0, v170
	v_add3_u32 v169, v169, v165, v160
	ds_read_b64_tr_b16 v[240:241], v162
	ds_read_b64_tr_b16 v[242:243], v169
	v_readlane_b32 s0, v255, 3
	s_nop 1
	v_add_u32_e32 v162, s0, v170
	v_readlane_b32 s0, v255, 4
	v_add3_u32 v162, v162, v166, v160
	v_mfma_f32_32x32x16_bf16 v[112:127], v[244:247], v[236:239], v[112:127]
	v_add_u32_e32 v169, s0, v170
	v_readlane_b32 s0, v255, 5
	v_add3_u32 v169, v169, v165, v160
	ds_read_b64_tr_b16 v[244:245], v162
	ds_read_b64_tr_b16 v[246:247], v169
	v_add_u32_e32 v162, s0, v170
	v_readlane_b32 s0, v255, 6
	v_add3_u32 v162, v162, v166, v160
	s_waitcnt lgkmcnt(0)
	v_mfma_f32_32x32x16_bf16 v[32:47], v[240:243], v[236:239], v[32:47]
	v_add_u32_e32 v169, s0, v170
	v_add3_u32 v169, v169, v165, v160
	ds_read_b64_tr_b16 v[240:241], v162
	ds_read_b64_tr_b16 v[242:243], v169
	v_readlane_b32 s0, v255, 7
	s_nop 1
	v_add_u32_e32 v162, s0, v170
	v_readlane_b32 s0, v255, 8
	v_add3_u32 v162, v162, v166, v160
	v_mfma_f32_32x32x16_bf16 v[48:63], v[232:235], v[236:239], v[48:63]
	v_add_u32_e32 v169, s0, v170
	v_readlane_b32 s0, v255, 9
	v_cvt_pk_bf16_f32 v232, v179, v183
	v_cvt_pk_bf16_f32 v233, v177, v180
	v_cvt_pk_bf16_f32 v234, v178, v181
	v_add3_u32 v169, v169, v165, v160
	ds_read_b64_tr_b16 v[178:179], v162
	ds_read_b64_tr_b16 v[180:181], v169
	v_add_u32_e32 v162, s0, v170
	v_readlane_b32 s0, v255, 10
	v_add3_u32 v162, v162, v166, v160
	v_mfma_f32_32x32x16_bf16 v[16:31], v[244:247], v[236:239], v[16:31]
	v_add_u32_e32 v169, s0, v170
	v_add3_u32 v169, v169, v165, v160
	v_readlane_b32 s0, v255, 11
	v_cvt_pk_bf16_f32 v235, v174, v176
	s_waitcnt lgkmcnt(0)
	v_mfma_f32_32x32x16_bf16 v[0:15], v[240:243], v[236:239], v[0:15]
	ds_read_b64_tr_b16 v[236:237], v162
	ds_read_b64_tr_b16 v[238:239], v169
	v_add_u32_e32 v162, s0, v170
	v_readlane_b32 s0, v255, 12
	v_add3_u32 v162, v162, v166, v160
	s_nop 0
	v_add_u32_e32 v169, s0, v170
	v_readlane_b32 s0, v255, 13
	v_mfma_f32_32x32x16_bf16 v[112:127], v[178:181], v[232:235], v[112:127]
	v_add3_u32 v169, v169, v165, v160
	ds_read_b64_tr_b16 v[176:177], v162
	ds_read_b64_tr_b16 v[178:179], v169
	v_add_u32_e32 v162, s0, v170
	v_readlane_b32 s0, v255, 14
	v_add3_u32 v162, v162, v166, v160
	s_nop 0
	v_add_u32_e32 v169, s0, v170
	s_waitcnt lgkmcnt(0)
	v_mfma_f32_32x32x16_bf16 v[96:111], v[236:239], v[232:235], v[96:111]
	v_add3_u32 v169, v169, v165, v160
	ds_read_b64_tr_b16 v[236:237], v162
	ds_read_b64_tr_b16 v[238:239], v169
	v_readlane_b32 s0, v255, 15
	s_nop 1
	v_add_u32_e32 v162, s0, v170
	v_readlane_b32 s0, v255, 16
	v_add3_u32 v162, v162, v166, v160
	v_mfma_f32_32x32x16_bf16 v[80:95], v[176:179], v[232:235], v[80:95]
	v_add_u32_e32 v169, s0, v170
	v_readlane_b32 s0, v255, 17
	v_add3_u32 v169, v169, v165, v160
	ds_read_b64_tr_b16 v[176:177], v162
	ds_read_b64_tr_b16 v[178:179], v169
	v_add_u32_e32 v162, s0, v170
	v_readlane_b32 s0, v255, 18
	v_add3_u32 v162, v162, v166, v160
	s_waitcnt lgkmcnt(0)
	v_mfma_f32_32x32x16_bf16 v[64:79], v[236:239], v[232:235], v[64:79]
	v_add_u32_e32 v169, s0, v170
	v_add3_u32 v169, v169, v165, v160
	ds_read_b64_tr_b16 v[236:237], v162
	ds_read_b64_tr_b16 v[238:239], v169
	v_readlane_b32 s0, v255, 19
	s_nop 1
	v_add_u32_e32 v162, s0, v170
	v_readlane_b32 s0, v255, 20
	v_add3_u32 v162, v162, v166, v160
	v_mfma_f32_32x32x16_bf16 v[48:63], v[176:179], v[232:235], v[48:63]
	v_add_u32_e32 v169, s0, v170
	v_readlane_b32 s0, v255, 21
	v_add3_u32 v169, v169, v165, v160
	ds_read_b64_tr_b16 v[176:177], v162
	ds_read_b64_tr_b16 v[178:179], v169
	v_add_u32_e32 v162, s0, v170
	v_readlane_b32 s0, v255, 22
	v_add3_u32 v162, v162, v166, v160
	s_waitcnt lgkmcnt(0)
	v_mfma_f32_32x32x16_bf16 v[32:47], v[236:239], v[232:235], v[32:47]
	v_add_u32_e32 v169, s0, v170
	v_add3_u32 v169, v169, v165, v160
	ds_read_b64_tr_b16 v[236:237], v162
	ds_read_b64_tr_b16 v[238:239], v169
	v_mfma_f32_32x32x16_bf16 v[16:31], v[176:179], v[232:235], v[16:31]
	s_waitcnt lgkmcnt(0)
	v_mfma_f32_32x32x16_bf16 v[0:15], v[236:239], v[232:235], v[0:15]
	s_waitcnt vmcnt(0)
	s_waitcnt vmcnt(0)
	s_barrier
; #define MFMA32(a, b, c) __builtin_amdgcn_mfma_f32_32x32x16_bf16((a), (b), (c), 0, 0, 0)
; DI void xattn_unit(const bf16_t* __restrict__ Qg, const bf16_t* __restrict__ Kg, const bf16_t* __restrict__ Vg, bf16_t* __restrict__ Og, lds_t* shm) {
;     ...
;   for (int t = 0; t < 4; ++t) {
;     if (t == 1) { __builtin_amdgcn_sched_barrier(0); asm volatile("s_waitcnt vmcnt(0)" ::: "memory"); __syncthreads(); __builtin_amdgcn_sched_barrier(0); }
;     const unsigned vbase = (t == 0) ? 131072u : (unsigned)t * 32768u;
; #pragma unroll
;     for (int ks = 0; ks < 4; ++ks)
; #pragma unroll
;       for (int c = 0; c < NC; ++c) {
;         const unsigned vo = vbase + (c >> 2) * 16384 + 512 * (c & 3) + 4096 * ks;
;         const bf16x8 vf = tr_pair(shm + vo + va0, shm + vo + 2048 + va1);
;         O[c] = MFMA32(vf, P[t][ks >> 1][ks & 1], O[c]);
;       }
	v_add_u32_e32 v162, 0, v170
	v_add3_u32 v169, v162, v166, v160
	v_add3_u32 v162, v162, v165, v160
	ds_read_b64_tr_b16 v[176:177], v169 offset:32768
	ds_read_b64_tr_b16 v[178:179], v162 offset:34816
	s_add_i32 s0, 0, 0x10000
	s_add_i32 s2, s2, 1
	v_readlane_b32 s68, v254, 0
	s_waitcnt lgkmcnt(0)
	v_mfma_f32_32x32x16_bf16 v[112:127], v[176:179], v[128:131], v[112:127]
	ds_read_b64_tr_b16 v[176:177], v169 offset:33280
	ds_read_b64_tr_b16 v[178:179], v162 offset:35328
	s_waitcnt lgkmcnt(0)
	v_mfma_f32_32x32x16_bf16 v[96:111], v[176:179], v[128:131], v[96:111]
	ds_read_b64_tr_b16 v[176:177], v169 offset:33792
	ds_read_b64_tr_b16 v[178:179], v162 offset:35840
	s_waitcnt lgkmcnt(0)
	v_mfma_f32_32x32x16_bf16 v[80:95], v[176:179], v[128:131], v[80:95]
	ds_read_b64_tr_b16 v[176:177], v169 offset:34304
	ds_read_b64_tr_b16 v[178:179], v162 offset:36352
	s_waitcnt lgkmcnt(0)
	v_mfma_f32_32x32x16_bf16 v[64:79], v[176:179], v[128:131], v[64:79]
	ds_read_b64_tr_b16 v[176:177], v169 offset:49152
	ds_read_b64_tr_b16 v[178:179], v162 offset:51200
	s_waitcnt lgkmcnt(0)
	v_mfma_f32_32x32x16_bf16 v[48:63], v[176:179], v[128:131], v[48:63]
	ds_read_b64_tr_b16 v[176:177], v169 offset:49664
	ds_read_b64_tr_b16 v[178:179], v162 offset:51712
	s_waitcnt lgkmcnt(0)
	v_mfma_f32_32x32x16_bf16 v[32:47], v[176:179], v[128:131], v[32:47]
	ds_read_b64_tr_b16 v[176:177], v169 offset:50176
	ds_read_b64_tr_b16 v[178:179], v162 offset:52224
	s_waitcnt lgkmcnt(0)
	v_mfma_f32_32x32x16_bf16 v[16:31], v[176:179], v[128:131], v[16:31]
	ds_read_b64_tr_b16 v[176:177], v169 offset:50688
	ds_read_b64_tr_b16 v[178:179], v162 offset:52736
	s_waitcnt lgkmcnt(0)
	v_mfma_f32_32x32x16_bf16 v[0:15], v[176:179], v[128:131], v[0:15]
	ds_read_b64_tr_b16 v[128:129], v169 offset:36864
	ds_read_b64_tr_b16 v[130:131], v162 offset:38912
	s_waitcnt lgkmcnt(0)
	v_mfma_f32_32x32x16_bf16 v[112:127], v[128:131], v[132:135], v[112:127]
	ds_read_b64_tr_b16 v[128:129], v169 offset:37376
	ds_read_b64_tr_b16 v[130:131], v162 offset:39424
	s_waitcnt lgkmcnt(0)
	v_mfma_f32_32x32x16_bf16 v[96:111], v[128:131], v[132:135], v[96:111]
	ds_read_b64_tr_b16 v[128:129], v169 offset:37888
	ds_read_b64_tr_b16 v[130:131], v162 offset:39936
	s_waitcnt lgkmcnt(0)
	v_mfma_f32_32x32x16_bf16 v[80:95], v[128:131], v[132:135], v[80:95]
	ds_read_b64_tr_b16 v[128:129], v169 offset:38400
	ds_read_b64_tr_b16 v[130:131], v162 offset:40448
	s_waitcnt lgkmcnt(0)
	v_mfma_f32_32x32x16_bf16 v[64:79], v[128:131], v[132:135], v[64:79]
	ds_read_b64_tr_b16 v[128:129], v169 offset:53248
	ds_read_b64_tr_b16 v[130:131], v162 offset:55296
	s_waitcnt lgkmcnt(0)
	v_mfma_f32_32x32x16_bf16 v[48:63], v[128:131], v[132:135], v[48:63]
	ds_read_b64_tr_b16 v[128:129], v169 offset:53760
	ds_read_b64_tr_b16 v[130:131], v162 offset:55808
	s_waitcnt lgkmcnt(0)
	v_mfma_f32_32x32x16_bf16 v[32:47], v[128:131], v[132:135], v[32:47]
	ds_read_b64_tr_b16 v[128:129], v169 offset:54272
	ds_read_b64_tr_b16 v[130:131], v162 offset:56320
	s_waitcnt lgkmcnt(0)
	v_mfma_f32_32x32x16_bf16 v[16:31], v[128:131], v[132:135], v[16:31]
	ds_read_b64_tr_b16 v[128:129], v169 offset:54784
	ds_read_b64_tr_b16 v[130:131], v162 offset:56832
	s_waitcnt lgkmcnt(0)
	v_mfma_f32_32x32x16_bf16 v[0:15], v[128:131], v[132:135], v[0:15]
	ds_read_b64_tr_b16 v[128:129], v169 offset:40960
	ds_read_b64_tr_b16 v[130:131], v162 offset:43008
	v_cvt_pk_bf16_f32 v132, v203, v204
	v_cvt_pk_bf16_f32 v133, v205, v206
	v_cvt_pk_bf16_f32 v134, v207, v209
	v_cvt_pk_bf16_f32 v135, v211, v219
	s_waitcnt lgkmcnt(0)
	v_mfma_f32_32x32x16_bf16 v[112:127], v[128:131], v[136:139], v[112:127]
	ds_read_b64_tr_b16 v[128:129], v169 offset:41472
	ds_read_b64_tr_b16 v[130:131], v162 offset:43520
	s_waitcnt lgkmcnt(0)
	v_mfma_f32_32x32x16_bf16 v[96:111], v[128:131], v[136:139], v[96:111]
	ds_read_b64_tr_b16 v[128:129], v169 offset:41984
	ds_read_b64_tr_b16 v[130:131], v162 offset:44032
	s_waitcnt lgkmcnt(0)
	v_mfma_f32_32x32x16_bf16 v[80:95], v[128:131], v[136:139], v[80:95]
	ds_read_b64_tr_b16 v[128:129], v169 offset:42496
	ds_read_b64_tr_b16 v[130:131], v162 offset:44544
	s_waitcnt lgkmcnt(0)
	v_mfma_f32_32x32x16_bf16 v[64:79], v[128:131], v[136:139], v[64:79]
	ds_read_b64_tr_b16 v[128:129], v169 offset:57344
	ds_read_b64_tr_b16 v[130:131], v162 offset:59392
	s_waitcnt lgkmcnt(0)
	v_mfma_f32_32x32x16_bf16 v[48:63], v[128:131], v[136:139], v[48:63]
	ds_read_b64_tr_b16 v[128:129], v169 offset:57856
	ds_read_b64_tr_b16 v[130:131], v162 offset:59904
	s_waitcnt lgkmcnt(0)
	v_mfma_f32_32x32x16_bf16 v[32:47], v[128:131], v[136:139], v[32:47]
	ds_read_b64_tr_b16 v[128:129], v169 offset:58368
	ds_read_b64_tr_b16 v[130:131], v162 offset:60416
	s_waitcnt lgkmcnt(0)
	v_mfma_f32_32x32x16_bf16 v[16:31], v[128:131], v[136:139], v[16:31]
	ds_read_b64_tr_b16 v[128:129], v169 offset:58880
	ds_read_b64_tr_b16 v[130:131], v162 offset:60928
	s_waitcnt lgkmcnt(0)
	v_mfma_f32_32x32x16_bf16 v[0:15], v[128:131], v[136:139], v[0:15]
	ds_read_b64_tr_b16 v[128:129], v169 offset:45056
	ds_read_b64_tr_b16 v[130:131], v162 offset:47104
	v_cvt_pk_bf16_f32 v136, v187, v188
	v_cvt_pk_bf16_f32 v137, v189, v190
	v_cvt_pk_bf16_f32 v138, v192, v196
	v_cvt_pk_bf16_f32 v139, v200, v202
	s_waitcnt lgkmcnt(0)
	v_mfma_f32_32x32x16_bf16 v[112:127], v[128:131], v[156:159], v[112:127]
	ds_read_b64_tr_b16 v[128:129], v169 offset:45568
	ds_read_b64_tr_b16 v[130:131], v162 offset:47616
	s_waitcnt lgkmcnt(0)
	v_mfma_f32_32x32x16_bf16 v[96:111], v[128:131], v[156:159], v[96:111]
	ds_read_b64_tr_b16 v[128:129], v169 offset:46080
	ds_read_b64_tr_b16 v[130:131], v162 offset:48128
	s_waitcnt lgkmcnt(0)
; #define MFMA32(a, b, c) __builtin_amdgcn_mfma_f32_32x32x16_bf16((a), (b), (c), 0, 0, 0)
; DI void xattn_unit(const bf16_t* __restrict__ Qg, const bf16_t* __restrict__ Kg, const bf16_t* __restrict__ Vg, bf16_t* __restrict__ Og, lds_t* shm) {
;     ...
; #pragma unroll
;   for (int t = 0; t < 4; ++t) {
;     if (t == 1) { __builtin_amdgcn_sched_barrier(0); asm volatile("s_waitcnt vmcnt(0)" ::: "memory"); __syncthreads(); __builtin_amdgcn_sched_barrier(0); }
;     const unsigned vbase = (t == 0) ? 131072u : (unsigned)t * 32768u;
; #pragma unroll
;     for (int ks = 0; ks < 4; ++ks)
; #pragma unroll
;       for (int c = 0; c < NC; ++c) {
;         const unsigned vo = vbase + (c >> 2) * 16384 + 512 * (c & 3) + 4096 * ks;
;         const bf16x8 vf = tr_pair(shm + vo + va0, shm + vo + 2048 + va1);
;         O[c] = MFMA32(vf, P[t][ks >> 1][ks & 1], O[c]);
;       }
;   }
	v_mfma_f32_32x32x16_bf16 v[80:95], v[128:131], v[156:159], v[80:95]
	ds_read_b64_tr_b16 v[128:129], v169 offset:46592
	ds_read_b64_tr_b16 v[130:131], v162 offset:48640
	s_waitcnt lgkmcnt(0)
	v_mfma_f32_32x32x16_bf16 v[64:79], v[128:131], v[156:159], v[64:79]
	ds_read_b64_tr_b16 v[128:129], v169 offset:61440
	ds_read_b64_tr_b16 v[130:131], v162 offset:63488
	s_waitcnt lgkmcnt(0)
	v_mfma_f32_32x32x16_bf16 v[48:63], v[128:131], v[156:159], v[48:63]
	ds_read_b64_tr_b16 v[128:129], v169 offset:61952
	ds_read_b64_tr_b16 v[130:131], v162 offset:64000
	s_waitcnt lgkmcnt(0)
	v_mfma_f32_32x32x16_bf16 v[32:47], v[128:131], v[156:159], v[32:47]
	ds_read_b64_tr_b16 v[128:129], v169 offset:62464
	ds_read_b64_tr_b16 v[130:131], v162 offset:64512
	s_waitcnt lgkmcnt(0)
	v_mfma_f32_32x32x16_bf16 v[16:31], v[128:131], v[156:159], v[16:31]
	ds_read_b64_tr_b16 v[128:129], v169 offset:62976
	ds_read_b64_tr_b16 v[130:131], v162 offset:65024
	s_waitcnt lgkmcnt(0)
	v_mfma_f32_32x32x16_bf16 v[0:15], v[128:131], v[156:159], v[0:15]
	v_add_u32_e32 v128, s0, v170
	v_readlane_b32 s0, v255, 23
	v_add3_u32 v128, v128, v166, v160
	s_nop 0
	v_add_u32_e32 v129, s0, v170
	v_add3_u32 v130, v129, v165, v160
	ds_read_b64_tr_b16 v[128:129], v128
	ds_read_b64_tr_b16 v[130:131], v130
	s_add_i32 s0, 0, 0x10200
	s_waitcnt lgkmcnt(0)
	v_mfma_f32_32x32x16_bf16 v[112:127], v[128:131], v[152:155], v[112:127]
	v_add_u32_e32 v128, s0, v170
	v_readlane_b32 s0, v255, 24
	v_add3_u32 v128, v128, v166, v160
	s_nop 0
	v_add_u32_e32 v129, s0, v170
	v_add3_u32 v130, v129, v165, v160
	ds_read_b64_tr_b16 v[128:129], v128
	ds_read_b64_tr_b16 v[130:131], v130
	s_add_i32 s0, 0, 0x10400
	s_waitcnt lgkmcnt(0)
	v_mfma_f32_32x32x16_bf16 v[96:111], v[128:131], v[152:155], v[96:111]
	v_add_u32_e32 v128, s0, v170
	v_readlane_b32 s0, v255, 25
	v_add3_u32 v128, v128, v166, v160
	s_nop 0
	v_add_u32_e32 v129, s0, v170
	v_add3_u32 v130, v129, v165, v160
	ds_read_b64_tr_b16 v[128:129], v128
	ds_read_b64_tr_b16 v[130:131], v130
	s_add_i32 s0, 0, 0x10600
	s_waitcnt lgkmcnt(0)
	v_mfma_f32_32x32x16_bf16 v[80:95], v[128:131], v[152:155], v[80:95]
	v_add_u32_e32 v128, s0, v170
	v_readlane_b32 s0, v255, 26
	v_add3_u32 v128, v128, v166, v160
	s_nop 0
	v_add_u32_e32 v129, s0, v170
	v_add3_u32 v130, v129, v165, v160
	ds_read_b64_tr_b16 v[128:129], v128
	ds_read_b64_tr_b16 v[130:131], v130
	s_add_i32 s0, 0, 0x14000
	s_waitcnt lgkmcnt(0)
	v_mfma_f32_32x32x16_bf16 v[64:79], v[128:131], v[152:155], v[64:79]
	v_add_u32_e32 v128, s0, v170
	v_readlane_b32 s0, v255, 27
	v_add3_u32 v128, v128, v166, v160
	s_nop 0
	v_add_u32_e32 v129, s0, v170
	v_add3_u32 v130, v129, v165, v160
	ds_read_b64_tr_b16 v[128:129], v128
	ds_read_b64_tr_b16 v[130:131], v130
	s_add_i32 s0, 0, 0x14200
	s_waitcnt lgkmcnt(0)
	v_mfma_f32_32x32x16_bf16 v[48:63], v[128:131], v[152:155], v[48:63]
	v_add_u32_e32 v128, s0, v170
	v_readlane_b32 s0, v255, 28
	v_add3_u32 v128, v128, v166, v160
	s_nop 0
	v_add_u32_e32 v129, s0, v170
	v_add3_u32 v130, v129, v165, v160
	ds_read_b64_tr_b16 v[128:129], v128
	ds_read_b64_tr_b16 v[130:131], v130
	s_add_i32 s0, 0, 0x14400
	s_waitcnt lgkmcnt(0)
	v_mfma_f32_32x32x16_bf16 v[32:47], v[128:131], v[152:155], v[32:47]
	v_add_u32_e32 v128, s0, v170
	v_readlane_b32 s0, v255, 29
	v_add3_u32 v128, v128, v166, v160
	s_nop 0
	v_add_u32_e32 v129, s0, v170
	v_add3_u32 v130, v129, v165, v160
	ds_read_b64_tr_b16 v[128:129], v128
	ds_read_b64_tr_b16 v[130:131], v130
	s_add_i32 s0, 0, 0x14600
	s_waitcnt lgkmcnt(0)
	v_mfma_f32_32x32x16_bf16 v[16:31], v[128:131], v[152:155], v[16:31]
	v_add_u32_e32 v128, s0, v170
	v_readlane_b32 s0, v255, 30
	v_add3_u32 v128, v128, v166, v160
	s_nop 0
	v_add_u32_e32 v129, s0, v170
	v_add3_u32 v130, v129, v165, v160
	ds_read_b64_tr_b16 v[128:129], v128
	ds_read_b64_tr_b16 v[130:131], v130
	v_readlane_b32 s0, v255, 31
	s_waitcnt lgkmcnt(0)
	v_mfma_f32_32x32x16_bf16 v[0:15], v[128:131], v[152:155], v[0:15]
	v_add_u32_e32 v128, s0, v170
	v_readlane_b32 s0, v255, 32
	v_add3_u32 v128, v128, v166, v160
	s_nop 0
	v_add_u32_e32 v129, s0, v170
	v_add3_u32 v130, v129, v165, v160
	ds_read_b64_tr_b16 v[128:129], v128
	ds_read_b64_tr_b16 v[130:131], v130
	v_readlane_b32 s0, v255, 33
	s_waitcnt lgkmcnt(0)
	v_mfma_f32_32x32x16_bf16 v[112:127], v[128:131], v[148:151], v[112:127]
	v_add_u32_e32 v128, s0, v170
	v_readlane_b32 s0, v255, 34
	v_add3_u32 v128, v128, v166, v160
	s_nop 0
	v_add_u32_e32 v129, s0, v170
	v_add3_u32 v130, v129, v165, v160
	ds_read_b64_tr_b16 v[128:129], v128
	ds_read_b64_tr_b16 v[130:131], v130
	v_readlane_b32 s0, v255, 35
	s_waitcnt lgkmcnt(0)
	v_mfma_f32_32x32x16_bf16 v[96:111], v[128:131], v[148:151], v[96:111]
	v_add_u32_e32 v128, s0, v170
	v_readlane_b32 s0, v255, 36
	v_add3_u32 v128, v128, v166, v160
	s_nop 0
	v_add_u32_e32 v129, s0, v170
	v_add3_u32 v130, v129, v165, v160
	ds_read_b64_tr_b16 v[128:129], v128
	ds_read_b64_tr_b16 v[130:131], v130
	v_readlane_b32 s0, v255, 37
	s_waitcnt lgkmcnt(0)
	v_mfma_f32_32x32x16_bf16 v[80:95], v[128:131], v[148:151], v[80:95]
	v_add_u32_e32 v128, s0, v170
	v_readlane_b32 s0, v255, 38
	v_add3_u32 v128, v128, v166, v160
	s_nop 0
	v_add_u32_e32 v129, s0, v170
	v_add3_u32 v130, v129, v165, v160
	ds_read_b64_tr_b16 v[128:129], v128
	ds_read_b64_tr_b16 v[130:131], v130
	v_readlane_b32 s0, v255, 39
	s_waitcnt lgkmcnt(0)
	v_mfma_f32_32x32x16_bf16 v[64:79], v[128:131], v[148:151], v[64:79]
	v_add_u32_e32 v128, s0, v170
	v_readlane_b32 s0, v255, 40
	v_add3_u32 v128, v128, v166, v160
	s_nop 0
	v_add_u32_e32 v129, s0, v170
	v_add3_u32 v130, v129, v165, v160
	ds_read_b64_tr_b16 v[128:129], v128
	ds_read_b64_tr_b16 v[130:131], v130
	v_readlane_b32 s0, v255, 41
	s_waitcnt lgkmcnt(0)
; #define MFMA32(a, b, c) __builtin_amdgcn_mfma_f32_32x32x16_bf16((a), (b), (c), 0, 0, 0)
; DI void xattn_unit(const bf16_t* __restrict__ Qg, const bf16_t* __restrict__ Kg, const bf16_t* __restrict__ Vg, bf16_t* __restrict__ Og, lds_t* shm) {
;     ...
; #pragma unroll
;   for (int t = 0; t < 4; ++t) {
;     if (t == 1) { __builtin_amdgcn_sched_barrier(0); asm volatile("s_waitcnt vmcnt(0)" ::: "memory"); __syncthreads(); __builtin_amdgcn_sched_barrier(0); }
;     const unsigned vbase = (t == 0) ? 131072u : (unsigned)t * 32768u;
; #pragma unroll
;     for (int ks = 0; ks < 4; ++ks)
; #pragma unroll
;       for (int c = 0; c < NC; ++c) {
;         const unsigned vo = vbase + (c >> 2) * 16384 + 512 * (c & 3) + 4096 * ks;
;         const bf16x8 vf = tr_pair(shm + vo + va0, shm + vo + 2048 + va1);
;         O[c] = MFMA32(vf, P[t][ks >> 1][ks & 1], O[c]);
;       }
;   }
	v_mfma_f32_32x32x16_bf16 v[48:63], v[128:131], v[148:151], v[48:63]
	v_add_u32_e32 v128, s0, v170
	v_readlane_b32 s0, v255, 42
	v_add3_u32 v128, v128, v166, v160
	s_nop 0
	v_add_u32_e32 v129, s0, v170
	v_add3_u32 v130, v129, v165, v160
	ds_read_b64_tr_b16 v[128:129], v128
	ds_read_b64_tr_b16 v[130:131], v130
	v_readlane_b32 s0, v255, 43
	s_waitcnt lgkmcnt(0)
	v_mfma_f32_32x32x16_bf16 v[32:47], v[128:131], v[148:151], v[32:47]
	v_add_u32_e32 v128, s0, v170
	v_readlane_b32 s0, v255, 44
	v_add3_u32 v128, v128, v166, v160
	s_nop 0
	v_add_u32_e32 v129, s0, v170
	v_add3_u32 v130, v129, v165, v160
	ds_read_b64_tr_b16 v[128:129], v128
	ds_read_b64_tr_b16 v[130:131], v130
	v_readlane_b32 s0, v255, 45
	s_waitcnt lgkmcnt(0)
	v_mfma_f32_32x32x16_bf16 v[16:31], v[128:131], v[148:151], v[16:31]
	v_add_u32_e32 v128, s0, v170
	v_readlane_b32 s0, v255, 46
	v_add3_u32 v128, v128, v166, v160
	s_nop 0
	v_add_u32_e32 v129, s0, v170
	v_add3_u32 v130, v129, v165, v160
	ds_read_b64_tr_b16 v[128:129], v128
	ds_read_b64_tr_b16 v[130:131], v130
	s_add_i32 s0, 0, 0x12000
	s_waitcnt lgkmcnt(0)
	v_mfma_f32_32x32x16_bf16 v[0:15], v[128:131], v[148:151], v[0:15]
	v_add_u32_e32 v128, s0, v170
	v_readlane_b32 s0, v255, 47
	v_add3_u32 v128, v128, v166, v160
	s_nop 0
	v_add_u32_e32 v129, s0, v170
	v_add3_u32 v130, v129, v165, v160
	ds_read_b64_tr_b16 v[128:129], v128
	ds_read_b64_tr_b16 v[130:131], v130
	s_add_i32 s0, 0, 0x12200
	s_waitcnt lgkmcnt(0)
	v_mfma_f32_32x32x16_bf16 v[112:127], v[128:131], v[140:143], v[112:127]
	v_add_u32_e32 v128, s0, v170
	v_readlane_b32 s0, v255, 48
	v_add3_u32 v128, v128, v166, v160
	s_nop 0
	v_add_u32_e32 v129, s0, v170
	v_add3_u32 v130, v129, v165, v160
	ds_read_b64_tr_b16 v[128:129], v128
	ds_read_b64_tr_b16 v[130:131], v130
	s_add_i32 s0, 0, 0x12400
	s_waitcnt lgkmcnt(0)
	v_mfma_f32_32x32x16_bf16 v[96:111], v[128:131], v[140:143], v[96:111]
	v_add_u32_e32 v128, s0, v170
	v_readlane_b32 s0, v255, 49
	v_add3_u32 v128, v128, v166, v160
	s_nop 0
	v_add_u32_e32 v129, s0, v170
	v_add3_u32 v130, v129, v165, v160
	ds_read_b64_tr_b16 v[128:129], v128
	ds_read_b64_tr_b16 v[130:131], v130
	s_add_i32 s0, 0, 0x12600
	s_waitcnt lgkmcnt(0)
	v_mfma_f32_32x32x16_bf16 v[80:95], v[128:131], v[140:143], v[80:95]
	v_add_u32_e32 v128, s0, v170
	v_readlane_b32 s0, v255, 50
	v_add3_u32 v128, v128, v166, v160
	s_nop 0
	v_add_u32_e32 v129, s0, v170
	v_add3_u32 v130, v129, v165, v160
	ds_read_b64_tr_b16 v[128:129], v128
	ds_read_b64_tr_b16 v[130:131], v130
	s_add_i32 s0, 0, 0x16000
	s_waitcnt lgkmcnt(0)
	v_mfma_f32_32x32x16_bf16 v[64:79], v[128:131], v[140:143], v[64:79]
	v_add_u32_e32 v128, s0, v170
	v_readlane_b32 s0, v255, 51
	v_add3_u32 v128, v128, v166, v160
	s_nop 0
	v_add_u32_e32 v129, s0, v170
	v_add3_u32 v130, v129, v165, v160
	ds_read_b64_tr_b16 v[128:129], v128
	ds_read_b64_tr_b16 v[130:131], v130
	s_add_i32 s0, 0, 0x16200
	s_waitcnt lgkmcnt(0)
	v_mfma_f32_32x32x16_bf16 v[48:63], v[128:131], v[140:143], v[48:63]
	v_add_u32_e32 v128, s0, v170
	v_readlane_b32 s0, v255, 52
	v_add3_u32 v128, v128, v166, v160
	s_nop 0
	v_add_u32_e32 v129, s0, v170
	v_add3_u32 v130, v129, v165, v160
	ds_read_b64_tr_b16 v[128:129], v128
	ds_read_b64_tr_b16 v[130:131], v130
	s_add_i32 s0, 0, 0x16400
	s_waitcnt lgkmcnt(0)
	v_mfma_f32_32x32x16_bf16 v[32:47], v[128:131], v[140:143], v[32:47]
	v_add_u32_e32 v128, s0, v170
	v_readlane_b32 s0, v255, 53
	v_add3_u32 v128, v128, v166, v160
	s_nop 0
	v_add_u32_e32 v129, s0, v170
	v_add3_u32 v130, v129, v165, v160
	ds_read_b64_tr_b16 v[128:129], v128
	ds_read_b64_tr_b16 v[130:131], v130
	s_add_i32 s0, 0, 0x16600
	s_waitcnt lgkmcnt(0)
	v_mfma_f32_32x32x16_bf16 v[16:31], v[128:131], v[140:143], v[16:31]
	v_add_u32_e32 v128, s0, v170
	v_readlane_b32 s0, v255, 54
	v_add3_u32 v128, v128, v166, v160
	s_nop 0
	v_add_u32_e32 v129, s0, v170
	v_add3_u32 v130, v129, v165, v160
	ds_read_b64_tr_b16 v[128:129], v128
	ds_read_b64_tr_b16 v[130:131], v130
	v_readlane_b32 s0, v255, 55
	s_waitcnt lgkmcnt(0)
	v_mfma_f32_32x32x16_bf16 v[0:15], v[128:131], v[140:143], v[0:15]
	v_add_u32_e32 v128, s0, v170
	v_readlane_b32 s0, v255, 56
	v_add3_u32 v128, v128, v166, v160
	v_cvt_pk_bf16_f32 v140, v171, v172
	v_add_u32_e32 v129, s0, v170
	v_add3_u32 v130, v129, v165, v160
	ds_read_b64_tr_b16 v[128:129], v128
	ds_read_b64_tr_b16 v[130:131], v130
	v_readlane_b32 s0, v255, 57
	s_waitcnt lgkmcnt(0)
	v_mfma_f32_32x32x16_bf16 v[112:127], v[128:131], v[144:147], v[112:127]
	v_add_u32_e32 v128, s0, v170
	v_readlane_b32 s0, v255, 58
	v_add3_u32 v128, v128, v166, v160
	v_cvt_pk_bf16_f32 v141, v173, v175
	v_add_u32_e32 v129, s0, v170
	v_add3_u32 v130, v129, v165, v160
	ds_read_b64_tr_b16 v[128:129], v128
	ds_read_b64_tr_b16 v[130:131], v130
	v_readlane_b32 s0, v255, 59
	s_waitcnt lgkmcnt(0)
	v_mfma_f32_32x32x16_bf16 v[96:111], v[128:131], v[144:147], v[96:111]
	v_add_u32_e32 v128, s0, v170
	v_readlane_b32 s0, v255, 60
	v_add3_u32 v128, v128, v166, v160
	v_cvt_pk_bf16_f32 v142, v182, v184
	v_add_u32_e32 v129, s0, v170
	v_add3_u32 v130, v129, v165, v160
	ds_read_b64_tr_b16 v[128:129], v128
	ds_read_b64_tr_b16 v[130:131], v130
	v_readlane_b32 s0, v255, 61
	s_waitcnt lgkmcnt(0)
	v_mfma_f32_32x32x16_bf16 v[80:95], v[128:131], v[144:147], v[80:95]
	v_add_u32_e32 v128, s0, v170
	v_readlane_b32 s0, v255, 62
	v_add3_u32 v128, v128, v166, v160
	v_cvt_pk_bf16_f32 v143, v185, v186
	v_add_u32_e32 v129, s0, v170
	v_add3_u32 v130, v129, v165, v160
	ds_read_b64_tr_b16 v[128:129], v128
	ds_read_b64_tr_b16 v[130:131], v130
	s_waitcnt lgkmcnt(0)
; #define MFMA32(a, b, c) __builtin_amdgcn_mfma_f32_32x32x16_bf16((a), (b), (c), 0, 0, 0)
; DI void xattn_unit(const bf16_t* __restrict__ Qg, const bf16_t* __restrict__ Kg, const bf16_t* __restrict__ Vg, bf16_t* __restrict__ Og, lds_t* shm) {
;     ...
; #pragma unroll
;   for (int t = 0; t < 4; ++t) {
;     if (t == 1) { __builtin_amdgcn_sched_barrier(0); asm volatile("s_waitcnt vmcnt(0)" ::: "memory"); __syncthreads(); __builtin_amdgcn_sched_barrier(0); }
;     const unsigned vbase = (t == 0) ? 131072u : (unsigned)t * 32768u;
; #pragma unroll
;     for (int ks = 0; ks < 4; ++ks)
; #pragma unroll
;       for (int c = 0; c < NC; ++c) {
;         const unsigned vo = vbase + (c >> 2) * 16384 + 512 * (c & 3) + 4096 * ks;
;         const bf16x8 vf = tr_pair(shm + vo + va0, shm + vo + 2048 + va1);
;         O[c] = MFMA32(vf, P[t][ks >> 1][ks & 1], O[c]);
;       }
;   }
	v_mfma_f32_32x32x16_bf16 v[64:79], v[128:131], v[144:147], v[64:79]
	v_add_u32_e32 v128, s83, v170
	v_add_u32_e32 v129, s84, v170
	v_add3_u32 v128, v128, v166, v160
	v_add3_u32 v130, v129, v165, v160
	ds_read_b64_tr_b16 v[128:129], v128
	ds_read_b64_tr_b16 v[130:131], v130
	s_add_i32 s0, 0, 0x18000
	s_waitcnt lgkmcnt(0)
	v_mfma_f32_32x32x16_bf16 v[48:63], v[128:131], v[144:147], v[48:63]
	v_add_u32_e32 v128, s85, v170
	v_add_u32_e32 v129, s86, v170
	v_add3_u32 v128, v128, v166, v160
	v_add3_u32 v130, v129, v165, v160
	ds_read_b64_tr_b16 v[128:129], v128
	ds_read_b64_tr_b16 v[130:131], v130
	s_waitcnt lgkmcnt(0)
	v_mfma_f32_32x32x16_bf16 v[32:47], v[128:131], v[144:147], v[32:47]
	v_add_u32_e32 v128, s87, v170
	v_add_u32_e32 v129, s88, v170
	v_add3_u32 v128, v128, v166, v160
	v_add3_u32 v130, v129, v165, v160
	ds_read_b64_tr_b16 v[128:129], v128
	ds_read_b64_tr_b16 v[130:131], v130
	s_waitcnt lgkmcnt(0)
	v_mfma_f32_32x32x16_bf16 v[16:31], v[128:131], v[144:147], v[16:31]
	v_add_u32_e32 v128, s89, v170
	v_add_u32_e32 v129, s90, v170
	v_add3_u32 v128, v128, v166, v160
	v_add3_u32 v130, v129, v165, v160
	ds_read_b64_tr_b16 v[128:129], v128
	ds_read_b64_tr_b16 v[130:131], v130
	s_waitcnt lgkmcnt(0)
	v_mfma_f32_32x32x16_bf16 v[0:15], v[128:131], v[144:147], v[0:15]
	v_add_u32_e32 v144, s0, v170
	v_add_u32_e32 v145, s91, v170
	v_add3_u32 v144, v144, v166, v160
	v_add3_u32 v146, v145, v165, v160
	ds_read_b64_tr_b16 v[144:145], v144
	ds_read_b64_tr_b16 v[146:147], v146
	s_add_i32 s0, 0, 0x18200
	v_cvt_pk_bf16_f32 v128, v222, v223
	s_waitcnt lgkmcnt(0)
	v_mfma_f32_32x32x16_bf16 v[112:127], v[144:147], v[140:143], v[112:127]
	v_add_u32_e32 v144, s0, v170
	v_add_u32_e32 v145, s92, v170
	v_add3_u32 v144, v144, v166, v160
	v_add3_u32 v146, v145, v165, v160
	ds_read_b64_tr_b16 v[144:145], v144
	ds_read_b64_tr_b16 v[146:147], v146
	s_add_i32 s0, 0, 0x18400
	v_cvt_pk_bf16_f32 v129, v224, v225
	s_waitcnt lgkmcnt(0)
	v_mfma_f32_32x32x16_bf16 v[96:111], v[144:147], v[140:143], v[96:111]
	v_add_u32_e32 v144, s0, v170
	v_add_u32_e32 v145, s93, v170
	v_add3_u32 v144, v144, v166, v160
	v_add3_u32 v146, v145, v165, v160
	ds_read_b64_tr_b16 v[144:145], v144
	ds_read_b64_tr_b16 v[146:147], v146
	s_add_i32 s0, 0, 0x18600
	v_cvt_pk_bf16_f32 v130, v226, v228
	s_waitcnt lgkmcnt(0)
	v_mfma_f32_32x32x16_bf16 v[80:95], v[144:147], v[140:143], v[80:95]
	v_add_u32_e32 v144, s0, v170
	v_add_u32_e32 v145, s94, v170
	v_add3_u32 v144, v144, v166, v160
	v_add3_u32 v146, v145, v165, v160
	ds_read_b64_tr_b16 v[144:145], v144
	ds_read_b64_tr_b16 v[146:147], v146
	s_add_i32 s0, 0, 0x1c000
	v_cvt_pk_bf16_f32 v131, v229, v230
	s_waitcnt lgkmcnt(0)
	v_mfma_f32_32x32x16_bf16 v[64:79], v[144:147], v[140:143], v[64:79]
	v_add_u32_e32 v144, s0, v170
	v_add_u32_e32 v145, s95, v170
	v_add3_u32 v144, v144, v166, v160
	v_add3_u32 v146, v145, v165, v160
	ds_read_b64_tr_b16 v[144:145], v144
	ds_read_b64_tr_b16 v[146:147], v146
	s_add_i32 s0, 0, 0x1c200
	s_waitcnt lgkmcnt(0)
	v_mfma_f32_32x32x16_bf16 v[48:63], v[144:147], v[140:143], v[48:63]
	v_add_u32_e32 v144, s0, v170
	v_add_u32_e32 v145, s96, v170
	v_add3_u32 v144, v144, v166, v160
	v_add3_u32 v146, v145, v165, v160
	ds_read_b64_tr_b16 v[144:145], v144
	ds_read_b64_tr_b16 v[146:147], v146
	s_add_i32 s0, 0, 0x1c400
	s_waitcnt lgkmcnt(0)
	v_mfma_f32_32x32x16_bf16 v[32:47], v[144:147], v[140:143], v[32:47]
	v_add_u32_e32 v144, s0, v170
	v_add_u32_e32 v145, s97, v170
	v_add3_u32 v144, v144, v166, v160
	v_add3_u32 v146, v145, v165, v160
	ds_read_b64_tr_b16 v[144:145], v144
	ds_read_b64_tr_b16 v[146:147], v146
	s_add_i32 s0, 0, 0x1c600
	s_waitcnt lgkmcnt(0)
	v_mfma_f32_32x32x16_bf16 v[16:31], v[144:147], v[140:143], v[16:31]
	v_add_u32_e32 v144, s0, v170
	v_add_u32_e32 v145, s8, v170
	v_add3_u32 v144, v144, v166, v160
	v_add3_u32 v146, v145, v165, v160
	ds_read_b64_tr_b16 v[144:145], v144
	ds_read_b64_tr_b16 v[146:147], v146
	s_add_i32 s0, 0, 0x1a000
	s_waitcnt lgkmcnt(0)
	v_mfma_f32_32x32x16_bf16 v[0:15], v[144:147], v[140:143], v[0:15]
	v_add_u32_e32 v140, s9, v170
	v_add_u32_e32 v141, s10, v170
	v_add3_u32 v140, v140, v166, v160
	v_add3_u32 v142, v141, v165, v160
	ds_read_b64_tr_b16 v[140:141], v140
	ds_read_b64_tr_b16 v[142:143], v142
	s_waitcnt lgkmcnt(0)
	v_mfma_f32_32x32x16_bf16 v[112:127], v[140:143], v[136:139], v[112:127]
	v_add_u32_e32 v140, s11, v170
	v_add_u32_e32 v141, s18, v170
	v_add3_u32 v140, v140, v166, v160
	v_add3_u32 v142, v141, v165, v160
	ds_read_b64_tr_b16 v[140:141], v140
	ds_read_b64_tr_b16 v[142:143], v142
	s_waitcnt lgkmcnt(0)
	v_mfma_f32_32x32x16_bf16 v[96:111], v[140:143], v[136:139], v[96:111]
	v_add_u32_e32 v140, s19, v170
	v_add_u32_e32 v141, s34, v170
	v_add3_u32 v140, v140, v166, v160
	v_add3_u32 v142, v141, v165, v160
	ds_read_b64_tr_b16 v[140:141], v140
	ds_read_b64_tr_b16 v[142:143], v142
	s_waitcnt lgkmcnt(0)
	v_mfma_f32_32x32x16_bf16 v[80:95], v[140:143], v[136:139], v[80:95]
	v_add_u32_e32 v140, s20, v170
	v_add_u32_e32 v141, s21, v170
	v_add3_u32 v140, v140, v166, v160
	v_add3_u32 v142, v141, v165, v160
	ds_read_b64_tr_b16 v[140:141], v140
	ds_read_b64_tr_b16 v[142:143], v142
	s_waitcnt lgkmcnt(0)
	v_mfma_f32_32x32x16_bf16 v[64:79], v[140:143], v[136:139], v[64:79]
	v_add_u32_e32 v140, s22, v170
	v_add_u32_e32 v141, s23, v170
	v_add3_u32 v140, v140, v166, v160
	v_add3_u32 v142, v141, v165, v160
	ds_read_b64_tr_b16 v[140:141], v140
	ds_read_b64_tr_b16 v[142:143], v142
	s_waitcnt lgkmcnt(0)
	v_mfma_f32_32x32x16_bf16 v[48:63], v[140:143], v[136:139], v[48:63]
	v_add_u32_e32 v140, s3, v170
	v_add_u32_e32 v141, s15, v170
	v_add3_u32 v140, v140, v166, v160
	v_add3_u32 v142, v141, v165, v160
	ds_read_b64_tr_b16 v[140:141], v140
	ds_read_b64_tr_b16 v[142:143], v142
	s_waitcnt lgkmcnt(0)
; #define MFMA32(a, b, c) __builtin_amdgcn_mfma_f32_32x32x16_bf16((a), (b), (c), 0, 0, 0)
; DI void xattn_unit(const bf16_t* __restrict__ Qg, const bf16_t* __restrict__ Kg, const bf16_t* __restrict__ Vg, bf16_t* __restrict__ Og, lds_t* shm) {
;     ...
; #pragma unroll
;   for (int t = 0; t < 4; ++t) {
;     if (t == 1) { __builtin_amdgcn_sched_barrier(0); asm volatile("s_waitcnt vmcnt(0)" ::: "memory"); __syncthreads(); __builtin_amdgcn_sched_barrier(0); }
;     const unsigned vbase = (t == 0) ? 131072u : (unsigned)t * 32768u;
; #pragma unroll
;     for (int ks = 0; ks < 4; ++ks)
; #pragma unroll
;       for (int c = 0; c < NC; ++c) {
;         const unsigned vo = vbase + (c >> 2) * 16384 + 512 * (c & 3) + 4096 * ks;
;         const bf16x8 vf = tr_pair(shm + vo + va0, shm + vo + 2048 + va1);
;         O[c] = MFMA32(vf, P[t][ks >> 1][ks & 1], O[c]);
;       }
;   }
	v_mfma_f32_32x32x16_bf16 v[32:47], v[140:143], v[136:139], v[32:47]
	v_add_u32_e32 v140, s35, v170
	v_add_u32_e32 v141, s40, v170
	v_add3_u32 v140, v140, v166, v160
	v_add3_u32 v142, v141, v165, v160
	ds_read_b64_tr_b16 v[140:141], v140
	ds_read_b64_tr_b16 v[142:143], v142
	s_waitcnt lgkmcnt(0)
	v_mfma_f32_32x32x16_bf16 v[16:31], v[140:143], v[136:139], v[16:31]
	v_add_u32_e32 v140, s41, v170
	v_add_u32_e32 v141, s42, v170
	v_add3_u32 v140, v140, v166, v160
	v_add3_u32 v142, v141, v165, v160
	ds_read_b64_tr_b16 v[140:141], v140
	ds_read_b64_tr_b16 v[142:143], v142
	s_waitcnt lgkmcnt(0)
	v_mfma_f32_32x32x16_bf16 v[0:15], v[140:143], v[136:139], v[0:15]
	v_add_u32_e32 v136, s0, v170
	v_add_u32_e32 v137, s43, v170
	v_add3_u32 v136, v136, v166, v160
	v_add3_u32 v138, v137, v165, v160
	ds_read_b64_tr_b16 v[136:137], v136
	ds_read_b64_tr_b16 v[138:139], v138
	s_add_i32 s0, 0, 0x1a200
	s_waitcnt lgkmcnt(0)
	v_mfma_f32_32x32x16_bf16 v[112:127], v[136:139], v[132:135], v[112:127]
	v_add_u32_e32 v136, s0, v170
	v_add_u32_e32 v137, s46, v170
	v_add3_u32 v136, v136, v166, v160
	v_add3_u32 v138, v137, v165, v160
	ds_read_b64_tr_b16 v[136:137], v136
	ds_read_b64_tr_b16 v[138:139], v138
	s_add_i32 s0, 0, 0x1a400
	s_waitcnt lgkmcnt(0)
	v_mfma_f32_32x32x16_bf16 v[96:111], v[136:139], v[132:135], v[96:111]
	v_add_u32_e32 v136, s0, v170
	v_add_u32_e32 v137, s47, v170
	v_add3_u32 v136, v136, v166, v160
	v_add3_u32 v138, v137, v165, v160
	ds_read_b64_tr_b16 v[136:137], v136
	ds_read_b64_tr_b16 v[138:139], v138
	s_add_i32 s0, 0, 0x1a600
	s_waitcnt lgkmcnt(0)
	v_mfma_f32_32x32x16_bf16 v[80:95], v[136:139], v[132:135], v[80:95]
	v_add_u32_e32 v136, s0, v170
	v_add_u32_e32 v137, s48, v170
	v_add3_u32 v136, v136, v166, v160
	v_add3_u32 v138, v137, v165, v160
	ds_read_b64_tr_b16 v[136:137], v136
	ds_read_b64_tr_b16 v[138:139], v138
	s_add_i32 s0, 0, 0x1e000
	s_waitcnt lgkmcnt(0)
	v_mfma_f32_32x32x16_bf16 v[64:79], v[136:139], v[132:135], v[64:79]
	v_add_u32_e32 v136, s0, v170
	v_add_u32_e32 v137, s49, v170
	v_add3_u32 v136, v136, v166, v160
	v_add3_u32 v138, v137, v165, v160
	ds_read_b64_tr_b16 v[136:137], v136
	ds_read_b64_tr_b16 v[138:139], v138
	s_add_i32 s0, 0, 0x1e200
	s_waitcnt lgkmcnt(0)
	v_mfma_f32_32x32x16_bf16 v[48:63], v[136:139], v[132:135], v[48:63]
	v_add_u32_e32 v136, s0, v170
	v_add_u32_e32 v137, s52, v170
	v_add3_u32 v136, v136, v166, v160
	v_add3_u32 v138, v137, v165, v160
	ds_read_b64_tr_b16 v[136:137], v136
	ds_read_b64_tr_b16 v[138:139], v138
	s_add_i32 s0, 0, 0x1e400
	s_waitcnt lgkmcnt(0)
	v_mfma_f32_32x32x16_bf16 v[32:47], v[136:139], v[132:135], v[32:47]
	v_add_u32_e32 v136, s0, v170
	v_add_u32_e32 v137, s53, v170
	v_add3_u32 v136, v136, v166, v160
	v_add3_u32 v138, v137, v165, v160
	ds_read_b64_tr_b16 v[136:137], v136
	ds_read_b64_tr_b16 v[138:139], v138
	s_add_i32 s0, 0, 0x1e600
	s_waitcnt lgkmcnt(0)
	v_mfma_f32_32x32x16_bf16 v[16:31], v[136:139], v[132:135], v[16:31]
	v_add_u32_e32 v136, s0, v170
	v_add_u32_e32 v137, s54, v170
	v_add3_u32 v136, v136, v166, v160
	v_add3_u32 v138, v137, v165, v160
	ds_read_b64_tr_b16 v[136:137], v136
	ds_read_b64_tr_b16 v[138:139], v138
	s_waitcnt lgkmcnt(0)
	v_mfma_f32_32x32x16_bf16 v[0:15], v[136:139], v[132:135], v[0:15]
	v_add_u32_e32 v132, s55, v170
	v_add_u32_e32 v133, s56, v170
	v_add3_u32 v132, v132, v166, v160
	v_add3_u32 v134, v133, v165, v160
	ds_read_b64_tr_b16 v[132:133], v132
	ds_read_b64_tr_b16 v[134:135], v134
	s_waitcnt lgkmcnt(0)
	v_mfma_f32_32x32x16_bf16 v[112:127], v[132:135], v[128:131], v[112:127]
	v_add_u32_e32 v132, s57, v170
	v_add_u32_e32 v133, s58, v170
	v_add3_u32 v132, v132, v166, v160
	v_add3_u32 v134, v133, v165, v160
	ds_read_b64_tr_b16 v[132:133], v132
	ds_read_b64_tr_b16 v[134:135], v134
	s_waitcnt lgkmcnt(0)
	v_mfma_f32_32x32x16_bf16 v[96:111], v[132:135], v[128:131], v[96:111]
	v_add_u32_e32 v132, s59, v170
	v_add_u32_e32 v133, s60, v170
	v_add3_u32 v132, v132, v166, v160
	v_add3_u32 v134, v133, v165, v160
	ds_read_b64_tr_b16 v[132:133], v132
	ds_read_b64_tr_b16 v[134:135], v134
	s_waitcnt lgkmcnt(0)
	v_mfma_f32_32x32x16_bf16 v[80:95], v[132:135], v[128:131], v[80:95]
	v_add_u32_e32 v132, s61, v170
	v_add_u32_e32 v133, s62, v170
	v_add3_u32 v132, v132, v166, v160
	v_add3_u32 v134, v133, v165, v160
	ds_read_b64_tr_b16 v[132:133], v132
	ds_read_b64_tr_b16 v[134:135], v134
	s_waitcnt lgkmcnt(0)
	v_mfma_f32_32x32x16_bf16 v[64:79], v[132:135], v[128:131], v[64:79]
	v_add_u32_e32 v132, s63, v170
	v_add_u32_e32 v133, s64, v170
	v_add3_u32 v132, v132, v166, v160
	v_add3_u32 v134, v133, v165, v160
	ds_read_b64_tr_b16 v[132:133], v132
	ds_read_b64_tr_b16 v[134:135], v134
	s_waitcnt lgkmcnt(0)
	v_mfma_f32_32x32x16_bf16 v[48:63], v[132:135], v[128:131], v[48:63]
	v_add_u32_e32 v132, s65, v170
	v_add_u32_e32 v133, s6, v170
	v_add3_u32 v132, v132, v166, v160
	v_add3_u32 v134, v133, v165, v160
	ds_read_b64_tr_b16 v[132:133], v132
	ds_read_b64_tr_b16 v[134:135], v134
	s_waitcnt lgkmcnt(0)
	v_mfma_f32_32x32x16_bf16 v[32:47], v[132:135], v[128:131], v[32:47]
	v_add_u32_e32 v132, s7, v170
	v_add_u32_e32 v133, s66, v170
	v_add3_u32 v132, v132, v166, v160
	v_add3_u32 v134, v133, v165, v160
	ds_read_b64_tr_b16 v[132:133], v132
	ds_read_b64_tr_b16 v[134:135], v134
	s_waitcnt lgkmcnt(0)
	v_mfma_f32_32x32x16_bf16 v[16:31], v[132:135], v[128:131], v[16:31]
	v_add_u32_e32 v132, s16, v170
	v_add_u32_e32 v133, s17, v170
	v_add3_u32 v132, v132, v166, v160
	v_add3_u32 v134, v133, v165, v160
	ds_read_b64_tr_b16 v[132:133], v132
	ds_read_b64_tr_b16 v[134:135], v134
	s_waitcnt lgkmcnt(0)
; DI unsigned pk2(float lo, float hi) { bf2_t v = __builtin_convertvector((f32x2){lo, hi}, bf2_t); return __builtin_bit_cast(unsigned, v); }
; DI void xattn_unit(const bf16_t* __restrict__ Qg, const bf16_t* __restrict__ Kg, const bf16_t* __restrict__ Vg, bf16_t* __restrict__ Og, lds_t* shm) {
;     ...
;   const float inv = 1.0f / l;
;   const unsigned ooff = ((unsigned)l31 * (unsigned)LDQ + 4u * h) * 2u;
; #pragma unroll
;   for (int c = 0; c < NC; ++c)
; #pragma unroll
;     for (int g4 = 0; g4 < 4; ++g4) {
;       u32x2 w; w.x = pk2(O[c][4 * g4 + 0] * inv, O[c][4 * g4 + 1] * inv); w.y = pk2(O[c][4 * g4 + 2] * inv, O[c][4 * g4 + 3] * inv);
;       gst<u32x2>(Og + 32 * c + 8 * g4, ooff, w);
;     }
	v_mfma_f32_32x32x16_bf16 v[0:15], v[132:135], v[128:131], v[0:15]
	v_add_f32_e32 v128, v167, v168
	v_div_scale_f32 v129, s[0:1], v128, v128, 1.0
	v_rcp_f32_e32 v130, v129
	v_readlane_b32 s0, v254, 6
	s_mov_b32 s28, s0
	s_mul_i32 s0, s2, s0
	v_fma_f32 v131, -v129, v130, 1.0
	v_fmac_f32_e32 v130, v131, v130
	v_div_scale_f32 v131, vcc, 1.0, v128, 1.0
	v_mul_f32_e32 v132, v131, v130
	v_fma_f32 v133, -v129, v132, v131
	v_fmac_f32_e32 v132, v133, v130
	v_fma_f32 v129, -v129, v132, v131
	v_div_fmas_f32 v129, v129, v130, v132
	v_div_fixup_f32 v128, v129, v128, 1.0
	v_lshl_or_b32 v129, v163, 3, v164
	v_pk_mul_f32 v[112:113], v[128:129], v[112:113] op_sel_hi:[0,1]
	v_pk_mul_f32 v[114:115], v[128:129], v[114:115] op_sel_hi:[0,1]
	v_pk_mul_f32 v[96:97], v[128:129], v[96:97] op_sel_hi:[0,1]
	v_pk_mul_f32 v[98:99], v[128:129], v[98:99] op_sel_hi:[0,1]
	v_pk_mul_f32 v[80:81], v[128:129], v[80:81] op_sel_hi:[0,1]
	v_pk_mul_f32 v[82:83], v[128:129], v[82:83] op_sel_hi:[0,1]
	v_pk_mul_f32 v[64:65], v[128:129], v[64:65] op_sel_hi:[0,1]
	v_pk_mul_f32 v[66:67], v[128:129], v[66:67] op_sel_hi:[0,1]
	v_pk_mul_f32 v[48:49], v[128:129], v[48:49] op_sel_hi:[0,1]
	v_pk_mul_f32 v[50:51], v[128:129], v[50:51] op_sel_hi:[0,1]
	v_pk_mul_f32 v[32:33], v[128:129], v[32:33] op_sel_hi:[0,1]
	v_pk_mul_f32 v[34:35], v[128:129], v[34:35] op_sel_hi:[0,1]
	v_pk_mul_f32 v[16:17], v[128:129], v[16:17] op_sel_hi:[0,1]
	v_pk_mul_f32 v[18:19], v[128:129], v[18:19] op_sel_hi:[0,1]
	v_pk_mul_f32 v[0:1], v[128:129], v[0:1] op_sel_hi:[0,1]
	v_pk_mul_f32 v[2:3], v[128:129], v[2:3] op_sel_hi:[0,1]
	v_cvt_pk_bf16_f32 v112, v112, v113
	v_cvt_pk_bf16_f32 v113, v114, v115
	v_cvt_pk_bf16_f32 v96, v96, v97
	v_cvt_pk_bf16_f32 v97, v98, v99
	v_cvt_pk_bf16_f32 v80, v80, v81
	v_cvt_pk_bf16_f32 v81, v82, v83
	v_cvt_pk_bf16_f32 v64, v64, v65
	v_cvt_pk_bf16_f32 v65, v66, v67
	v_cvt_pk_bf16_f32 v48, v48, v49
	v_cvt_pk_bf16_f32 v49, v50, v51
	v_cvt_pk_bf16_f32 v32, v32, v33
	v_cvt_pk_bf16_f32 v33, v34, v35
	v_cvt_pk_bf16_f32 v16, v16, v17
	v_cvt_pk_bf16_f32 v17, v18, v19
	v_cvt_pk_bf16_f32 v0, v0, v1
	v_cvt_pk_bf16_f32 v1, v2, v3
	global_store_dwordx2 v129, v[112:113], s[30:31]
	v_pk_mul_f32 v[112:113], v[128:129], v[116:117] op_sel_hi:[0,1]
	v_pk_mul_f32 v[114:115], v[128:129], v[118:119] op_sel_hi:[0,1]
	global_store_dwordx2 v129, v[96:97], s[30:31] offset:64
	v_pk_mul_f32 v[96:97], v[128:129], v[100:101] op_sel_hi:[0,1]
	v_pk_mul_f32 v[98:99], v[128:129], v[102:103] op_sel_hi:[0,1]
	global_store_dwordx2 v129, v[80:81], s[30:31] offset:128
	v_pk_mul_f32 v[80:81], v[128:129], v[84:85] op_sel_hi:[0,1]
	v_pk_mul_f32 v[82:83], v[128:129], v[86:87] op_sel_hi:[0,1]
	global_store_dwordx2 v129, v[64:65], s[30:31] offset:192
	v_pk_mul_f32 v[64:65], v[128:129], v[68:69] op_sel_hi:[0,1]
	v_pk_mul_f32 v[66:67], v[128:129], v[70:71] op_sel_hi:[0,1]
	global_store_dwordx2 v129, v[48:49], s[30:31] offset:256
	v_pk_mul_f32 v[48:49], v[128:129], v[52:53] op_sel_hi:[0,1]
	v_pk_mul_f32 v[50:51], v[128:129], v[54:55] op_sel_hi:[0,1]
	global_store_dwordx2 v129, v[32:33], s[30:31] offset:320
	v_pk_mul_f32 v[32:33], v[128:129], v[36:37] op_sel_hi:[0,1]
	v_pk_mul_f32 v[34:35], v[128:129], v[38:39] op_sel_hi:[0,1]
	global_store_dwordx2 v129, v[16:17], s[30:31] offset:384
	v_pk_mul_f32 v[16:17], v[128:129], v[20:21] op_sel_hi:[0,1]
	v_pk_mul_f32 v[18:19], v[128:129], v[22:23] op_sel_hi:[0,1]
	global_store_dwordx2 v129, v[0:1], s[30:31] offset:448
	v_pk_mul_f32 v[0:1], v[128:129], v[4:5] op_sel_hi:[0,1]
	v_pk_mul_f32 v[2:3], v[128:129], v[6:7] op_sel_hi:[0,1]
	v_cvt_pk_bf16_f32 v112, v112, v113
	v_cvt_pk_bf16_f32 v113, v114, v115
	v_cvt_pk_bf16_f32 v96, v96, v97
	v_cvt_pk_bf16_f32 v97, v98, v99
	v_cvt_pk_bf16_f32 v80, v80, v81
	v_cvt_pk_bf16_f32 v81, v82, v83
	v_cvt_pk_bf16_f32 v64, v64, v65
	v_cvt_pk_bf16_f32 v65, v66, v67
	v_cvt_pk_bf16_f32 v48, v48, v49
	v_cvt_pk_bf16_f32 v49, v50, v51
	v_cvt_pk_bf16_f32 v32, v32, v33
	v_cvt_pk_bf16_f32 v33, v34, v35
	v_cvt_pk_bf16_f32 v16, v16, v17
	v_cvt_pk_bf16_f32 v17, v18, v19
	v_cvt_pk_bf16_f32 v0, v0, v1
	v_cvt_pk_bf16_f32 v1, v2, v3
	global_store_dwordx2 v129, v[112:113], s[30:31] offset:16
	v_pk_mul_f32 v[112:113], v[128:129], v[120:121] op_sel_hi:[0,1]
	v_pk_mul_f32 v[114:115], v[128:129], v[122:123] op_sel_hi:[0,1]
	global_store_dwordx2 v129, v[96:97], s[30:31] offset:80
; DI unsigned pk2(float lo, float hi) { bf2_t v = __builtin_convertvector((f32x2){lo, hi}, bf2_t); return __builtin_bit_cast(unsigned, v); }
; DI void xattn_unit(const bf16_t* __restrict__ Qg, const bf16_t* __restrict__ Kg, const bf16_t* __restrict__ Vg, bf16_t* __restrict__ Og, lds_t* shm) {
;     ...
;   const float inv = 1.0f / l;
;   const unsigned ooff = ((unsigned)l31 * (unsigned)LDQ + 4u * h) * 2u;
; #pragma unroll
;   for (int c = 0; c < NC; ++c)
; #pragma unroll
;     for (int g4 = 0; g4 < 4; ++g4) {
;       u32x2 w; w.x = pk2(O[c][4 * g4 + 0] * inv, O[c][4 * g4 + 1] * inv); w.y = pk2(O[c][4 * g4 + 2] * inv, O[c][4 * g4 + 3] * inv);
;       gst<u32x2>(Og + 32 * c + 8 * g4, ooff, w);
;     }
; DI void cross_attn_own_tiles(const Params& p, lds_t* shm) {
;     ...
;   for (int i = 0;; ++i) {
;     int pm, pn; if (!g8::tile_coords(i * (int)gridDim.x + (int)blockIdx.x, T_TOK / 256, 4, pm, pn)) break;
	v_pk_mul_f32 v[96:97], v[128:129], v[104:105] op_sel_hi:[0,1]
	v_pk_mul_f32 v[98:99], v[128:129], v[106:107] op_sel_hi:[0,1]
	global_store_dwordx2 v129, v[80:81], s[30:31] offset:144
	v_pk_mul_f32 v[80:81], v[128:129], v[88:89] op_sel_hi:[0,1]
	v_pk_mul_f32 v[82:83], v[128:129], v[90:91] op_sel_hi:[0,1]
	global_store_dwordx2 v129, v[64:65], s[30:31] offset:208
	v_pk_mul_f32 v[64:65], v[128:129], v[72:73] op_sel_hi:[0,1]
	v_pk_mul_f32 v[66:67], v[128:129], v[74:75] op_sel_hi:[0,1]
	global_store_dwordx2 v129, v[48:49], s[30:31] offset:272
	v_pk_mul_f32 v[48:49], v[128:129], v[56:57] op_sel_hi:[0,1]
	v_pk_mul_f32 v[50:51], v[128:129], v[58:59] op_sel_hi:[0,1]
	global_store_dwordx2 v129, v[32:33], s[30:31] offset:336
	v_pk_mul_f32 v[32:33], v[128:129], v[40:41] op_sel_hi:[0,1]
	v_pk_mul_f32 v[34:35], v[128:129], v[42:43] op_sel_hi:[0,1]
	global_store_dwordx2 v129, v[16:17], s[30:31] offset:400
	v_pk_mul_f32 v[16:17], v[128:129], v[24:25] op_sel_hi:[0,1]
	v_pk_mul_f32 v[18:19], v[128:129], v[26:27] op_sel_hi:[0,1]
	global_store_dwordx2 v129, v[0:1], s[30:31] offset:464
	v_pk_mul_f32 v[0:1], v[128:129], v[8:9] op_sel_hi:[0,1]
	v_pk_mul_f32 v[2:3], v[128:129], v[10:11] op_sel_hi:[0,1]
	v_cvt_pk_bf16_f32 v112, v112, v113
	v_cvt_pk_bf16_f32 v113, v114, v115
	v_cvt_pk_bf16_f32 v96, v96, v97
	v_cvt_pk_bf16_f32 v97, v98, v99
	v_cvt_pk_bf16_f32 v80, v80, v81
	v_cvt_pk_bf16_f32 v81, v82, v83
	v_cvt_pk_bf16_f32 v64, v64, v65
	v_cvt_pk_bf16_f32 v65, v66, v67
	v_cvt_pk_bf16_f32 v48, v48, v49
	v_cvt_pk_bf16_f32 v49, v50, v51
	v_cvt_pk_bf16_f32 v32, v32, v33
	v_cvt_pk_bf16_f32 v33, v34, v35
	v_cvt_pk_bf16_f32 v16, v16, v17
	v_cvt_pk_bf16_f32 v17, v18, v19
	v_cvt_pk_bf16_f32 v0, v0, v1
	v_cvt_pk_bf16_f32 v1, v2, v3
	global_store_dwordx2 v129, v[112:113], s[30:31] offset:32
	v_pk_mul_f32 v[112:113], v[128:129], v[124:125] op_sel_hi:[0,1]
	v_pk_mul_f32 v[114:115], v[128:129], v[126:127] op_sel_hi:[0,1]
	global_store_dwordx2 v129, v[96:97], s[30:31] offset:96
	v_pk_mul_f32 v[96:97], v[128:129], v[108:109] op_sel_hi:[0,1]
	v_pk_mul_f32 v[98:99], v[128:129], v[110:111] op_sel_hi:[0,1]
	global_store_dwordx2 v129, v[80:81], s[30:31] offset:160
	v_pk_mul_f32 v[80:81], v[128:129], v[92:93] op_sel_hi:[0,1]
	v_pk_mul_f32 v[82:83], v[128:129], v[94:95] op_sel_hi:[0,1]
	global_store_dwordx2 v129, v[64:65], s[30:31] offset:224
	v_pk_mul_f32 v[64:65], v[128:129], v[76:77] op_sel_hi:[0,1]
	v_pk_mul_f32 v[66:67], v[128:129], v[78:79] op_sel_hi:[0,1]
	global_store_dwordx2 v129, v[48:49], s[30:31] offset:288
	v_pk_mul_f32 v[48:49], v[128:129], v[60:61] op_sel_hi:[0,1]
	v_pk_mul_f32 v[50:51], v[128:129], v[62:63] op_sel_hi:[0,1]
	global_store_dwordx2 v129, v[32:33], s[30:31] offset:352
	v_pk_mul_f32 v[32:33], v[128:129], v[44:45] op_sel_hi:[0,1]
	v_pk_mul_f32 v[34:35], v[128:129], v[46:47] op_sel_hi:[0,1]
	global_store_dwordx2 v129, v[16:17], s[30:31] offset:416
	v_pk_mul_f32 v[16:17], v[128:129], v[28:29] op_sel_hi:[0,1]
	v_pk_mul_f32 v[18:19], v[128:129], v[30:31] op_sel_hi:[0,1]
	global_store_dwordx2 v129, v[0:1], s[30:31] offset:480
	v_pk_mul_f32 v[0:1], v[128:129], v[12:13] op_sel_hi:[0,1]
	v_pk_mul_f32 v[2:3], v[128:129], v[14:15] op_sel_hi:[0,1]
	s_add_i32 s0, s0, s68
	s_add_i32 s33, s33, s28
	v_cvt_pk_bf16_f32 v112, v112, v113
	v_cvt_pk_bf16_f32 v113, v114, v115
	v_cvt_pk_bf16_f32 v96, v96, v97
	v_cvt_pk_bf16_f32 v97, v98, v99
	v_cvt_pk_bf16_f32 v80, v80, v81
	v_cvt_pk_bf16_f32 v81, v82, v83
	v_cvt_pk_bf16_f32 v64, v64, v65
	v_cvt_pk_bf16_f32 v65, v66, v67
	v_cvt_pk_bf16_f32 v48, v48, v49
	v_cvt_pk_bf16_f32 v49, v50, v51
	v_cvt_pk_bf16_f32 v32, v32, v33
	v_cvt_pk_bf16_f32 v33, v34, v35
	v_cvt_pk_bf16_f32 v16, v16, v17
	v_cvt_pk_bf16_f32 v17, v18, v19
	v_cvt_pk_bf16_f32 v0, v0, v1
	v_cvt_pk_bf16_f32 v1, v2, v3
	s_cmpk_lt_i32 s33, 0x200
	global_store_dwordx2 v129, v[112:113], s[30:31] offset:48
	global_store_dwordx2 v129, v[96:97], s[30:31] offset:112
	global_store_dwordx2 v129, v[80:81], s[30:31] offset:176
	global_store_dwordx2 v129, v[64:65], s[30:31] offset:240
	global_store_dwordx2 v129, v[48:49], s[30:31] offset:304
	global_store_dwordx2 v129, v[32:33], s[30:31] offset:368
	global_store_dwordx2 v129, v[16:17], s[30:31] offset:432
	global_store_dwordx2 v129, v[0:1], s[30:31] offset:496
	v_readlane_b32 s1, v254, 7
	s_cbranch_scc0 .LBB0_634
